# K-loop load segments: LDS-DMA tile loads issued before the ds_read fragment reads (longer lead before vmcnt(8)); on top of early buffer_inv + pipelined ret_scan
# baseline (speedup 1.0000x reference)
; #define PG8_STAGE(bufoff, gbase, voff) do { _Pragma("unroll") for (int _i = 0; _i < 2; ++_i) \
;         __builtin_amdgcn_global_load_lds((const GAS unsigned*)((const GAS char*)(gbase) + (voff)[_i]), (LAS unsigned*)(lds + (bufoff) + ldsw + _i * 8192), 16, 0, 0); } while (0)
; #define PG8_LDA(dst, b, h) do { _Pragma("unroll") for (int m = 0; m < 4; ++m) _Pragma("unroll") for (int k = 0; k < 2; ++k) dst[m][k] = *(const LAS bf16x8*)(lds + PG8_SA(b, h) + aoff + m * 2048 + k * 1024); } while (0)
; #define PG8_LDB(dst, b, h) do { _Pragma("unroll") for (int n = 0; n < 2; ++n) _Pragma("unroll") for (int k = 0; k < 2; ++k) dst[n][k] = *(const LAS bf16x8*)(lds + PG8_SB(b, h) + boff + n * 2048 + k * 1024); } while (0)
; #define PG8_MMA(ai, bj, At, Bt) do { __builtin_amdgcn_s_setprio(1); _Pragma("unroll") for (int m = 0; m < 4; ++m) _Pragma("unroll") for (int n = 0; n < 2; ++n) _Pragma("unroll") for (int k = 0; k < 2; ++k) \
;         acc[ai][bj][m][n] = __builtin_amdgcn_mfma_f32_16x16x32_bf16(Bt[n][k], At[m][k], acc[ai][bj][m][n], 0, 0, 0); __builtin_amdgcn_s_setprio(0); } while (0)
; #define PG8_WAIT_V(n) asm volatile("s_waitcnt vmcnt(" #n ")" ::: "memory")
; #define PG8_WAIT_L(n) asm volatile("s_waitcnt lgkmcnt(" #n ")" ::: "memory")
; #define PG8_BAR __builtin_amdgcn_s_barrier()
; #define PG8_SCHED __builtin_amdgcn_sched_barrier(0)
; template <class Epi, class Sched, bool ALIGN_EPI>
; __device__ __forceinline__ void gemm_phase(LAS unsigned char* lds, const Gemm g, const Sched& S, const Epi& E, int wave_id) {
;     ...
;             PG8_LDB(B0, 0, 0); PG8_LDB(B1, 0, 1); PG8_SCHED; PG8_LDA(At, 0, 0); PG8_STAGE(PG8_SA(1, 1), a1 + hsA, voffA);
;             PG8_WAIT_V(8); PG8_WAIT_L(0); PG8_BAR; PG8_MMA(0, 0, At, B0); PG8_MMA(0, 1, At, B1); PG8_BAR; PG8_SCHED;
;             PG8_LDA(At, 0, 1); PG8_STAGE(PG8_SB(0, 0), b2, voffB); PG8_STAGE(PG8_SB(0, 1), b2 + hsB, voffB); PG8_STAGE(PG8_SA(0, 0), a2, voffA);
;             PG8_WAIT_V(8); PG8_WAIT_L(0); PG8_BAR; PG8_MMA(1, 0, At, B0); PG8_MMA(1, 1, At, B1); PG8_BAR; PG8_SCHED;
.LBB0_1117:
	s_add_u32 s58, s0, 0xfff80080
	s_addc_u32 s59, s1, -1
	s_cmp_eq_u32 s76, 28
	s_cselect_b32 s61, s33, s59
	s_cselect_b32 s60, s47, s58
	s_cselect_b32 s59, s49, s74
	s_cselect_b32 s58, s57, s71
	s_mov_b32 m0, s87
	v_lshl_add_u64 v[206:207], s[0:1], 0, v[204:205]
	global_load_lds_dwordx4 v[206:207], off
	v_lshl_add_u64 v[206:207], s[0:1], 0, v[202:203]
	s_mov_b32 m0, s88
	s_nop 0
	global_load_lds_dwordx4 v[206:207], off
	v_add_u32_e32 v0, 0x10400, v250
	ds_read_b128 v[130:133], v0
	ds_read_b128 v[134:137], v0 offset:1024
	ds_read_b128 v[138:141], v0 offset:2048
	ds_read_b128 v[142:145], v0 offset:3072
	v_add_u32_e32 v0, 0x14400, v250
	ds_read_b128 v[146:149], v0
	ds_read_b128 v[150:153], v0 offset:1024
	ds_read_b128 v[154:157], v0 offset:2048
	ds_read_b128 v[158:161], v0 offset:3072
	ds_read_b128 v[162:165], v253 offset:1024
	ds_read_b128 v[166:169], v253 offset:2048
	ds_read_b128 v[170:173], v253 offset:3072
	ds_read_b128 v[174:177], v253 offset:4096
	ds_read_b128 v[178:181], v253 offset:5120
	ds_read_b128 v[182:185], v253 offset:6144
	ds_read_b128 v[186:189], v253 offset:7168
	ds_read_b128 v[190:193], v253 offset:8192
	s_waitcnt vmcnt(8)
	s_waitcnt lgkmcnt(0)
	s_barrier
	s_setprio 1
	s_waitcnt lgkmcnt(0)
	v_mfma_f32_16x16x32_bf16 v[126:129], v[130:133], v[162:165], v[126:129]
	v_mfma_f32_16x16x32_bf16 v[122:125], v[138:141], v[162:165], v[122:125]
	v_mfma_f32_16x16x32_bf16 v[110:113], v[130:133], v[170:173], v[110:113]
	v_mfma_f32_16x16x32_bf16 v[106:109], v[138:141], v[170:173], v[106:109]
	v_mfma_f32_16x16x32_bf16 v[94:97], v[130:133], v[178:181], v[94:97]
	v_mfma_f32_16x16x32_bf16 v[90:93], v[138:141], v[178:181], v[90:93]
	v_mfma_f32_16x16x32_bf16 v[78:81], v[130:133], v[186:189], v[78:81]
	v_mfma_f32_16x16x32_bf16 v[74:77], v[138:141], v[186:189], v[74:77]
	v_mfma_f32_16x16x32_bf16 v[126:129], v[134:137], v[166:169], v[126:129]
	v_mfma_f32_16x16x32_bf16 v[122:125], v[142:145], v[166:169], v[122:125]
	v_mfma_f32_16x16x32_bf16 v[110:113], v[134:137], v[174:177], v[110:113]
	v_mfma_f32_16x16x32_bf16 v[106:109], v[142:145], v[174:177], v[106:109]
	v_mfma_f32_16x16x32_bf16 v[94:97], v[134:137], v[182:185], v[94:97]
	v_mfma_f32_16x16x32_bf16 v[90:93], v[142:145], v[182:185], v[90:93]
	v_mfma_f32_16x16x32_bf16 v[78:81], v[134:137], v[190:193], v[78:81]
	v_mfma_f32_16x16x32_bf16 v[74:77], v[142:145], v[190:193], v[74:77]
	s_setprio 0
	s_setprio 1
	v_mfma_f32_16x16x32_bf16 v[118:121], v[146:149], v[162:165], v[118:121]
	v_mfma_f32_16x16x32_bf16 v[114:117], v[154:157], v[162:165], v[114:117]
	v_mfma_f32_16x16x32_bf16 v[102:105], v[146:149], v[170:173], v[102:105]
	v_mfma_f32_16x16x32_bf16 v[98:101], v[154:157], v[170:173], v[98:101]
	v_mfma_f32_16x16x32_bf16 v[86:89], v[146:149], v[178:181], v[86:89]
	v_mfma_f32_16x16x32_bf16 v[82:85], v[154:157], v[178:181], v[82:85]
	v_mfma_f32_16x16x32_bf16 v[70:73], v[146:149], v[186:189], v[70:73]
	v_mfma_f32_16x16x32_bf16 v[66:69], v[154:157], v[186:189], v[66:69]
	v_mfma_f32_16x16x32_bf16 v[118:121], v[150:153], v[166:169], v[118:121]
	v_mfma_f32_16x16x32_bf16 v[114:117], v[158:161], v[166:169], v[114:117]
	v_mfma_f32_16x16x32_bf16 v[102:105], v[150:153], v[174:177], v[102:105]
	v_mfma_f32_16x16x32_bf16 v[98:101], v[158:161], v[174:177], v[98:101]
	v_mfma_f32_16x16x32_bf16 v[86:89], v[150:153], v[182:185], v[86:89]
	v_mfma_f32_16x16x32_bf16 v[82:85], v[158:161], v[182:185], v[82:85]
	v_mfma_f32_16x16x32_bf16 v[70:73], v[150:153], v[190:193], v[70:73]
	v_mfma_f32_16x16x32_bf16 v[66:69], v[158:161], v[190:193], v[66:69]
	s_setprio 0
	s_barrier
	s_mov_b32 m0, s15
	v_lshl_add_u64 v[206:207], s[58:59], 0, v[196:197]
	s_add_u32 vcc_lo, s58, 0x80000
	global_load_lds_dwordx4 v[206:207], off
	v_lshl_add_u64 v[208:209], s[58:59], 0, v[200:201]
	s_mov_b32 m0, s73
	s_addc_u32 vcc_hi, s59, 0
	global_load_lds_dwordx4 v[208:209], off
	v_lshl_add_u64 v[210:211], vcc, 0, v[196:197]
	s_mov_b32 m0, s75
	v_lshl_add_u64 v[212:213], s[60:61], 0, v[198:199]
	global_load_lds_dwordx4 v[210:211], off
	v_lshl_add_u64 v[210:211], vcc, 0, v[200:201]
	s_mov_b32 m0, s80
	s_nop 0
	global_load_lds_dwordx4 v[210:211], off
	v_lshl_add_u64 v[210:211], s[60:61], 0, v[194:195]
	s_mov_b32 m0, s81
	s_nop 0
	global_load_lds_dwordx4 v[210:211], off
	s_mov_b32 m0, s82
	s_nop 0
	global_load_lds_dwordx4 v[212:213], off
	ds_read_b128 v[162:165], v253 offset:17408
	ds_read_b128 v[166:169], v253 offset:18432
	ds_read_b128 v[170:173], v253 offset:19456
	ds_read_b128 v[174:177], v253 offset:20480
	ds_read_b128 v[178:181], v253 offset:21504
	ds_read_b128 v[182:185], v253 offset:22528
	ds_read_b128 v[186:189], v253 offset:23552
	ds_read_b128 v[190:193], v253 offset:24576
	s_waitcnt vmcnt(8)
	s_waitcnt lgkmcnt(0)
	s_barrier
; #define PG8_STAGE(bufoff, gbase, voff) do { _Pragma("unroll") for (int _i = 0; _i < 2; ++_i) \
;         __builtin_amdgcn_global_load_lds((const GAS unsigned*)((const GAS char*)(gbase) + (voff)[_i]), (LAS unsigned*)(lds + (bufoff) + ldsw + _i * 8192), 16, 0, 0); } while (0)
; #define PG8_LDA(dst, b, h) do { _Pragma("unroll") for (int m = 0; m < 4; ++m) _Pragma("unroll") for (int k = 0; k < 2; ++k) dst[m][k] = *(const LAS bf16x8*)(lds + PG8_SA(b, h) + aoff + m * 2048 + k * 1024); } while (0)
; #define PG8_LDB(dst, b, h) do { _Pragma("unroll") for (int n = 0; n < 2; ++n) _Pragma("unroll") for (int k = 0; k < 2; ++k) dst[n][k] = *(const LAS bf16x8*)(lds + PG8_SB(b, h) + boff + n * 2048 + k * 1024); } while (0)
; #define PG8_MMA(ai, bj, At, Bt) do { __builtin_amdgcn_s_setprio(1); _Pragma("unroll") for (int m = 0; m < 4; ++m) _Pragma("unroll") for (int n = 0; n < 2; ++n) _Pragma("unroll") for (int k = 0; k < 2; ++k) \
;         acc[ai][bj][m][n] = __builtin_amdgcn_mfma_f32_16x16x32_bf16(Bt[n][k], At[m][k], acc[ai][bj][m][n], 0, 0, 0); __builtin_amdgcn_s_setprio(0); } while (0)
; #define PG8_WAIT_V(n) asm volatile("s_waitcnt vmcnt(" #n ")" ::: "memory")
; #define PG8_WAIT_L(n) asm volatile("s_waitcnt lgkmcnt(" #n ")" ::: "memory")
; #define PG8_BAR __builtin_amdgcn_s_barrier()
; #define PG8_SCHED __builtin_amdgcn_sched_barrier(0)
; template <class Epi, class Sched, bool ALIGN_EPI>
; __device__ __forceinline__ void gemm_phase(LAS unsigned char* lds, const Gemm g, const Sched& S, const Epi& E, int wave_id) {
;     ...
;             PG8_WAIT_V(8); PG8_WAIT_L(0); PG8_BAR; PG8_MMA(1, 0, At, B0); PG8_MMA(1, 1, At, B1); PG8_BAR; PG8_SCHED;
;             PG8_LDB(B0, 1, 0); PG8_LDB(B1, 1, 1); PG8_SCHED; PG8_LDA(At, 1, 0); PG8_STAGE(PG8_SA(0, 1), a2 + hsA, voffA);
;             PG8_WAIT_V(8); PG8_WAIT_L(0); PG8_BAR; PG8_MMA(0, 0, At, B0); PG8_MMA(0, 1, At, B1); PG8_BAR; PG8_SCHED;
	s_setprio 1
	s_waitcnt lgkmcnt(0)
	v_mfma_f32_16x16x32_bf16 v[62:65], v[130:133], v[162:165], v[62:65]
	v_mfma_f32_16x16x32_bf16 v[58:61], v[138:141], v[162:165], v[58:61]
	v_mfma_f32_16x16x32_bf16 v[46:49], v[130:133], v[170:173], v[46:49]
	v_mfma_f32_16x16x32_bf16 v[42:45], v[138:141], v[170:173], v[42:45]
	v_mfma_f32_16x16x32_bf16 v[30:33], v[130:133], v[178:181], v[30:33]
	v_mfma_f32_16x16x32_bf16 v[26:29], v[138:141], v[178:181], v[26:29]
	v_mfma_f32_16x16x32_bf16 v[14:17], v[130:133], v[186:189], v[14:17]
	v_mfma_f32_16x16x32_bf16 v[10:13], v[138:141], v[186:189], v[10:13]
	v_mfma_f32_16x16x32_bf16 v[62:65], v[134:137], v[166:169], v[62:65]
	v_mfma_f32_16x16x32_bf16 v[58:61], v[142:145], v[166:169], v[58:61]
	v_mfma_f32_16x16x32_bf16 v[46:49], v[134:137], v[174:177], v[46:49]
	v_mfma_f32_16x16x32_bf16 v[42:45], v[142:145], v[174:177], v[42:45]
	v_mfma_f32_16x16x32_bf16 v[30:33], v[134:137], v[182:185], v[30:33]
	v_mfma_f32_16x16x32_bf16 v[26:29], v[142:145], v[182:185], v[26:29]
	v_mfma_f32_16x16x32_bf16 v[14:17], v[134:137], v[190:193], v[14:17]
	v_mfma_f32_16x16x32_bf16 v[10:13], v[142:145], v[190:193], v[10:13]
	s_setprio 0
	s_setprio 1
	v_mfma_f32_16x16x32_bf16 v[54:57], v[146:149], v[162:165], v[54:57]
	v_mfma_f32_16x16x32_bf16 v[50:53], v[154:157], v[162:165], v[50:53]
	v_mfma_f32_16x16x32_bf16 v[38:41], v[146:149], v[170:173], v[38:41]
	v_mfma_f32_16x16x32_bf16 v[34:37], v[154:157], v[170:173], v[34:37]
	v_mfma_f32_16x16x32_bf16 v[22:25], v[146:149], v[178:181], v[22:25]
	v_mfma_f32_16x16x32_bf16 v[18:21], v[154:157], v[178:181], v[18:21]
	v_mfma_f32_16x16x32_bf16 v[6:9], v[146:149], v[186:189], v[6:9]
	v_mfma_f32_16x16x32_bf16 v[2:5], v[154:157], v[186:189], v[2:5]
	v_mfma_f32_16x16x32_bf16 v[54:57], v[150:153], v[166:169], v[54:57]
	v_mfma_f32_16x16x32_bf16 v[50:53], v[158:161], v[166:169], v[50:53]
	v_mfma_f32_16x16x32_bf16 v[38:41], v[150:153], v[174:177], v[38:41]
	v_mfma_f32_16x16x32_bf16 v[34:37], v[158:161], v[174:177], v[34:37]
	v_mfma_f32_16x16x32_bf16 v[22:25], v[150:153], v[182:185], v[22:25]
	v_mfma_f32_16x16x32_bf16 v[18:21], v[158:161], v[182:185], v[18:21]
	v_mfma_f32_16x16x32_bf16 v[6:9], v[150:153], v[190:193], v[6:9]
	v_mfma_f32_16x16x32_bf16 v[2:5], v[158:161], v[190:193], v[2:5]
	s_setprio 0
	s_barrier
	s_add_u32 s60, s60, 0x80000
	s_addc_u32 s61, s61, 0
	s_mov_b32 m0, s83
	v_lshl_add_u64 v[214:215], s[60:61], 0, v[194:195]
	global_load_lds_dwordx4 v[214:215], off
	v_lshl_add_u64 v[214:215], s[60:61], 0, v[198:199]
	s_mov_b32 m0, s84
	s_nop 0
	global_load_lds_dwordx4 v[214:215], off
	v_add_u32_e32 v0, 0x18400, v250
	ds_read_b128 v[130:133], v0
	ds_read_b128 v[134:137], v0 offset:1024
	ds_read_b128 v[138:141], v0 offset:2048
	ds_read_b128 v[142:145], v0 offset:3072
	v_add_u32_e32 v0, 0x1c400, v250
	ds_read_b128 v[146:149], v0
	ds_read_b128 v[150:153], v0 offset:1024
	ds_read_b128 v[154:157], v0 offset:2048
	ds_read_b128 v[158:161], v0 offset:3072
	ds_read_b128 v[162:165], v253 offset:33792
	ds_read_b128 v[166:169], v253 offset:34816
	ds_read_b128 v[170:173], v253 offset:35840
	ds_read_b128 v[174:177], v253 offset:36864
	ds_read_b128 v[178:181], v253 offset:37888
	ds_read_b128 v[182:185], v253 offset:38912
	ds_read_b128 v[186:189], v253 offset:39936
	ds_read_b128 v[190:193], v253 offset:40960
	s_waitcnt vmcnt(8)
	s_waitcnt lgkmcnt(0)
	s_barrier
	s_setprio 1
	s_waitcnt lgkmcnt(0)
	v_mfma_f32_16x16x32_bf16 v[126:129], v[130:133], v[162:165], v[126:129]
	v_mfma_f32_16x16x32_bf16 v[122:125], v[138:141], v[162:165], v[122:125]
	v_mfma_f32_16x16x32_bf16 v[110:113], v[130:133], v[170:173], v[110:113]
	v_mfma_f32_16x16x32_bf16 v[106:109], v[138:141], v[170:173], v[106:109]
	v_mfma_f32_16x16x32_bf16 v[94:97], v[130:133], v[178:181], v[94:97]
	v_mfma_f32_16x16x32_bf16 v[90:93], v[138:141], v[178:181], v[90:93]
	v_mfma_f32_16x16x32_bf16 v[78:81], v[130:133], v[186:189], v[78:81]
	v_mfma_f32_16x16x32_bf16 v[74:77], v[138:141], v[186:189], v[74:77]
	v_mfma_f32_16x16x32_bf16 v[126:129], v[134:137], v[166:169], v[126:129]
	v_mfma_f32_16x16x32_bf16 v[122:125], v[142:145], v[166:169], v[122:125]
	v_mfma_f32_16x16x32_bf16 v[110:113], v[134:137], v[174:177], v[110:113]
	v_mfma_f32_16x16x32_bf16 v[106:109], v[142:145], v[174:177], v[106:109]
	v_mfma_f32_16x16x32_bf16 v[94:97], v[134:137], v[182:185], v[94:97]
	v_mfma_f32_16x16x32_bf16 v[90:93], v[142:145], v[182:185], v[90:93]
	v_mfma_f32_16x16x32_bf16 v[78:81], v[134:137], v[190:193], v[78:81]
	v_mfma_f32_16x16x32_bf16 v[74:77], v[142:145], v[190:193], v[74:77]
	s_setprio 0
	s_setprio 1
	v_mfma_f32_16x16x32_bf16 v[118:121], v[146:149], v[162:165], v[118:121]
	v_mfma_f32_16x16x32_bf16 v[114:117], v[154:157], v[162:165], v[114:117]
	v_mfma_f32_16x16x32_bf16 v[102:105], v[146:149], v[170:173], v[102:105]
	v_mfma_f32_16x16x32_bf16 v[98:101], v[154:157], v[170:173], v[98:101]
	v_mfma_f32_16x16x32_bf16 v[86:89], v[146:149], v[178:181], v[86:89]
	v_mfma_f32_16x16x32_bf16 v[82:85], v[154:157], v[178:181], v[82:85]
	v_mfma_f32_16x16x32_bf16 v[70:73], v[146:149], v[186:189], v[70:73]
	v_mfma_f32_16x16x32_bf16 v[66:69], v[154:157], v[186:189], v[66:69]
	v_mfma_f32_16x16x32_bf16 v[118:121], v[150:153], v[166:169], v[118:121]
	v_mfma_f32_16x16x32_bf16 v[114:117], v[158:161], v[166:169], v[114:117]
	v_mfma_f32_16x16x32_bf16 v[102:105], v[150:153], v[174:177], v[102:105]
	v_mfma_f32_16x16x32_bf16 v[98:101], v[158:161], v[174:177], v[98:101]
	v_mfma_f32_16x16x32_bf16 v[86:89], v[150:153], v[182:185], v[86:89]
	v_mfma_f32_16x16x32_bf16 v[82:85], v[158:161], v[182:185], v[82:85]
	v_mfma_f32_16x16x32_bf16 v[70:73], v[150:153], v[190:193], v[70:73]
	v_mfma_f32_16x16x32_bf16 v[66:69], v[158:161], v[190:193], v[66:69]
	s_setprio 0
	s_barrier
; #define PG8_STAGE(bufoff, gbase, voff) do { _Pragma("unroll") for (int _i = 0; _i < 2; ++_i) \
;         __builtin_amdgcn_global_load_lds((const GAS unsigned*)((const GAS char*)(gbase) + (voff)[_i]), (LAS unsigned*)(lds + (bufoff) + ldsw + _i * 8192), 16, 0, 0); } while (0)
; #define PG8_LDA(dst, b, h) do { _Pragma("unroll") for (int m = 0; m < 4; ++m) _Pragma("unroll") for (int k = 0; k < 2; ++k) dst[m][k] = *(const LAS bf16x8*)(lds + PG8_SA(b, h) + aoff + m * 2048 + k * 1024); } while (0)
; #define PG8_MMA(ai, bj, At, Bt) do { __builtin_amdgcn_s_setprio(1); _Pragma("unroll") for (int m = 0; m < 4; ++m) _Pragma("unroll") for (int n = 0; n < 2; ++n) _Pragma("unroll") for (int k = 0; k < 2; ++k) \
;         acc[ai][bj][m][n] = __builtin_amdgcn_mfma_f32_16x16x32_bf16(Bt[n][k], At[m][k], acc[ai][bj][m][n], 0, 0, 0); __builtin_amdgcn_s_setprio(0); } while (0)
; #define PG8_WAIT_V(n) asm volatile("s_waitcnt vmcnt(" #n ")" ::: "memory")
; #define PG8_WAIT_L(n) asm volatile("s_waitcnt lgkmcnt(" #n ")" ::: "memory")
; #define PG8_BAR __builtin_amdgcn_s_barrier()
; #define PG8_SCHED __builtin_amdgcn_sched_barrier(0)
; template <class Epi, class Sched, bool ALIGN_EPI>
; __device__ __forceinline__ void gemm_phase(LAS unsigned char* lds, const Gemm g, const Sched& S, const Epi& E, int wave_id) {
;     ...
;             PG8_LDA(At, 1, 1); PG8_STAGE(PG8_SB(1, 0), b3, voffB); PG8_STAGE(PG8_SB(1, 1), b3 + hsB, voffB); PG8_STAGE(PG8_SA(1, 0), a3, voffA);
;             PG8_WAIT_V(8); PG8_WAIT_L(0); PG8_BAR; PG8_MMA(1, 0, At, B0); PG8_MMA(1, 1, At, B1); PG8_BAR; PG8_SCHED;
;         }
	s_mov_b32 m0, s95
	v_lshl_add_u64 v[206:207], v[206:207], 0, s[92:93]
	s_add_u32 s58, s58, 0x80080
	global_load_lds_dwordx4 v[206:207], off
	v_lshl_add_u64 v[206:207], v[208:209], 0, s[92:93]
	s_mov_b32 m0, s96
	s_addc_u32 s59, s59, 0
	global_load_lds_dwordx4 v[206:207], off
	v_lshl_add_u64 v[206:207], s[58:59], 0, v[196:197]
	s_mov_b32 m0, s17
	s_nop 0
	global_load_lds_dwordx4 v[206:207], off
	v_lshl_add_u64 v[206:207], s[58:59], 0, v[200:201]
	s_mov_b32 m0, s18
	s_nop 0
	global_load_lds_dwordx4 v[206:207], off
	v_lshl_add_u64 v[206:207], v[210:211], 0, s[92:93]
	s_mov_b32 m0, s97
	s_nop 0
	global_load_lds_dwordx4 v[206:207], off
	v_lshl_add_u64 v[206:207], v[212:213], 0, s[92:93]
	s_mov_b32 m0, s16
	s_nop 0
	global_load_lds_dwordx4 v[206:207], off
	ds_read_b128 v[162:165], v253 offset:50176
	ds_read_b128 v[166:169], v253 offset:51200
	ds_read_b128 v[170:173], v253 offset:52224
	ds_read_b128 v[174:177], v253 offset:53248
	ds_read_b128 v[178:181], v253 offset:54272
	ds_read_b128 v[182:185], v253 offset:55296
	ds_read_b128 v[186:189], v253 offset:56320
	ds_read_b128 v[190:193], v253 offset:57344
	s_waitcnt vmcnt(8)
	s_waitcnt lgkmcnt(0)
	s_barrier
	s_setprio 1
	s_waitcnt lgkmcnt(0)
	v_mfma_f32_16x16x32_bf16 v[62:65], v[130:133], v[162:165], v[62:65]
	v_mfma_f32_16x16x32_bf16 v[58:61], v[138:141], v[162:165], v[58:61]
	v_mfma_f32_16x16x32_bf16 v[46:49], v[130:133], v[170:173], v[46:49]
	v_mfma_f32_16x16x32_bf16 v[42:45], v[138:141], v[170:173], v[42:45]
	v_mfma_f32_16x16x32_bf16 v[30:33], v[130:133], v[178:181], v[30:33]
	v_mfma_f32_16x16x32_bf16 v[26:29], v[138:141], v[178:181], v[26:29]
	v_mfma_f32_16x16x32_bf16 v[14:17], v[130:133], v[186:189], v[14:17]
	v_mfma_f32_16x16x32_bf16 v[10:13], v[138:141], v[186:189], v[10:13]
	v_mfma_f32_16x16x32_bf16 v[62:65], v[134:137], v[166:169], v[62:65]
	v_mfma_f32_16x16x32_bf16 v[58:61], v[142:145], v[166:169], v[58:61]
	v_mfma_f32_16x16x32_bf16 v[46:49], v[134:137], v[174:177], v[46:49]
	v_mfma_f32_16x16x32_bf16 v[42:45], v[142:145], v[174:177], v[42:45]
	v_mfma_f32_16x16x32_bf16 v[30:33], v[134:137], v[182:185], v[30:33]
	v_mfma_f32_16x16x32_bf16 v[26:29], v[142:145], v[182:185], v[26:29]
	v_mfma_f32_16x16x32_bf16 v[14:17], v[134:137], v[190:193], v[14:17]
	v_mfma_f32_16x16x32_bf16 v[10:13], v[142:145], v[190:193], v[10:13]
	s_setprio 0
	s_setprio 1
	v_mfma_f32_16x16x32_bf16 v[54:57], v[146:149], v[162:165], v[54:57]
	v_mfma_f32_16x16x32_bf16 v[50:53], v[154:157], v[162:165], v[50:53]
	v_mfma_f32_16x16x32_bf16 v[38:41], v[146:149], v[170:173], v[38:41]
	v_mfma_f32_16x16x32_bf16 v[34:37], v[154:157], v[170:173], v[34:37]
	v_mfma_f32_16x16x32_bf16 v[22:25], v[146:149], v[178:181], v[22:25]
	v_mfma_f32_16x16x32_bf16 v[18:21], v[154:157], v[178:181], v[18:21]
	v_mfma_f32_16x16x32_bf16 v[6:9], v[146:149], v[186:189], v[6:9]
	v_mfma_f32_16x16x32_bf16 v[2:5], v[154:157], v[186:189], v[2:5]
	v_mfma_f32_16x16x32_bf16 v[54:57], v[150:153], v[166:169], v[54:57]
	v_mfma_f32_16x16x32_bf16 v[50:53], v[158:161], v[166:169], v[50:53]
	v_mfma_f32_16x16x32_bf16 v[38:41], v[150:153], v[174:177], v[38:41]
	v_mfma_f32_16x16x32_bf16 v[34:37], v[158:161], v[174:177], v[34:37]
	v_mfma_f32_16x16x32_bf16 v[22:25], v[150:153], v[182:185], v[22:25]
	v_mfma_f32_16x16x32_bf16 v[18:21], v[158:161], v[182:185], v[18:21]
	v_mfma_f32_16x16x32_bf16 v[6:9], v[150:153], v[190:193], v[6:9]
	v_mfma_f32_16x16x32_bf16 v[2:5], v[158:161], v[190:193], v[2:5]
	s_setprio 0
	s_barrier
	s_add_i32 s76, s76, 2
	s_add_u32 s71, s71, 0x100
	s_addc_u32 s74, s74, 0
	s_add_u32 s0, s0, 0x100
	s_addc_u32 s1, s1, 0
	s_cmp_gt_u32 s76, 29
	s_cbranch_scc0 .LBB0_1117
	s_and_b64 vcc, exec, s[44:45]
	s_cbranch_vccz .LBB0_1120
	s_barrier

; #define PG8_STAGE(bufoff, gbase, voff) do { _Pragma("unroll") for (int _i = 0; _i < 2; ++_i) \
;         __builtin_amdgcn_global_load_lds((const GAS unsigned*)((const GAS char*)(gbase) + (voff)[_i]), (LAS unsigned*)(lds + (bufoff) + ldsw + _i * 8192), 16, 0, 0); } while (0)
; #define PG8_LDA(dst, b, h) do { _Pragma("unroll") for (int m = 0; m < 4; ++m) _Pragma("unroll") for (int k = 0; k < 2; ++k) dst[m][k] = *(const LAS bf16x8*)(lds + PG8_SA(b, h) + aoff + m * 2048 + k * 1024); } while (0)
; #define PG8_LDB(dst, b, h) do { _Pragma("unroll") for (int n = 0; n < 2; ++n) _Pragma("unroll") for (int k = 0; k < 2; ++k) dst[n][k] = *(const LAS bf16x8*)(lds + PG8_SB(b, h) + boff + n * 2048 + k * 1024); } while (0)
; #define PG8_MMA(ai, bj, At, Bt) do { __builtin_amdgcn_s_setprio(1); _Pragma("unroll") for (int m = 0; m < 4; ++m) _Pragma("unroll") for (int n = 0; n < 2; ++n) _Pragma("unroll") for (int k = 0; k < 2; ++k) \
;         acc[ai][bj][m][n] = __builtin_amdgcn_mfma_f32_16x16x32_bf16(Bt[n][k], At[m][k], acc[ai][bj][m][n], 0, 0, 0); __builtin_amdgcn_s_setprio(0); } while (0)
; #define PG8_WAIT_V(n) asm volatile("s_waitcnt vmcnt(" #n ")" ::: "memory")
; #define PG8_WAIT_L(n) asm volatile("s_waitcnt lgkmcnt(" #n ")" ::: "memory")
; #define PG8_BAR __builtin_amdgcn_s_barrier()
; #define PG8_SCHED __builtin_amdgcn_sched_barrier(0)
; template <class Epi, class Sched, bool ALIGN_EPI>
; __device__ __forceinline__ void gemm_phase(LAS unsigned char* lds, const Gemm g, const Sched& S, const Epi& E, int wave_id) {
;     ...
;             PG8_LDB(B0, 0, 0); PG8_LDB(B1, 0, 1); PG8_SCHED; PG8_LDA(At, 0, 0); PG8_STAGE(PG8_SA(1, 1), a1 + hsA, voffA);
;             PG8_WAIT_V(8); PG8_WAIT_L(0); PG8_BAR; PG8_MMA(0, 0, At, B0); PG8_MMA(0, 1, At, B1); PG8_BAR; PG8_SCHED;
;             PG8_LDA(At, 0, 1); PG8_STAGE(PG8_SB(0, 0), b2, voffB); PG8_STAGE(PG8_SB(0, 1), b2 + hsB, voffB); PG8_STAGE(PG8_SA(0, 0), a2, voffA);
;             PG8_WAIT_V(8); PG8_WAIT_L(0); PG8_BAR; PG8_MMA(1, 0, At, B0); PG8_MMA(1, 1, At, B1); PG8_BAR; PG8_SCHED;
.LBB0_1335:
	s_add_u32 s34, s12, s26
	s_addc_u32 s35, s13, s27
	s_add_u32 s30, s34, 0x100
	s_addc_u32 s31, s35, 0
	s_and_b64 s[28:29], s[24:25], exec
	s_cselect_b32 s29, s17, s31
	s_cselect_b32 s28, s16, s30
	s_add_u32 s26, s10, s26
	s_addc_u32 s27, s11, s27
	s_add_u32 s26, s26, 0x100
	s_addc_u32 s27, s27, 0
	s_and_b64 s[24:25], s[24:25], exec
	s_cselect_b32 s31, s60, s27
	s_cselect_b32 s30, s61, s26
	s_add_u32 s36, s34, 0x18080
	s_addc_u32 s37, s35, 0
	s_add_i32 m0, s40, 0xc400
	s_add_i32 s62, s40, 0xe400
	s_add_u32 s34, s30, 0x10000
	s_addc_u32 s35, s31, 0
	s_add_u32 s26, s28, 0x18000
	s_addc_u32 s27, s29, 0
	s_add_u32 s24, s30, 0x10080
	s_addc_u32 s25, s31, 0
	v_lshl_add_u64 v[122:123], s[36:37], 0, v[70:71]
	global_load_lds_dwordx4 v[122:123], off
	v_lshl_add_u64 v[122:123], s[36:37], 0, v[68:69]
	s_mov_b32 m0, s62
	s_nop 0
	global_load_lds_dwordx4 v[122:123], off
	v_add_u32_e32 v86, 0x10400, v73
	ds_read_b128 v[74:77], v86
	ds_read_b128 v[78:81], v86 offset:1024
	ds_read_b128 v[82:85], v86 offset:2048
	ds_read_b128 v[86:89], v86 offset:3072
	ds_read_b128 v[90:93], v72 offset:1024
	ds_read_b128 v[94:97], v72 offset:2048
	ds_read_b128 v[98:101], v72 offset:3072
	ds_read_b128 v[102:105], v72 offset:4096
	ds_read_b128 v[106:109], v72 offset:5120
	ds_read_b128 v[110:113], v72 offset:6144
	ds_read_b128 v[114:117], v72 offset:7168
	ds_read_b128 v[118:121], v72 offset:8192
	s_waitcnt vmcnt(8)
	s_waitcnt lgkmcnt(0)
	s_barrier
	s_setprio 1
	s_waitcnt lgkmcnt(0)
	v_mfma_f32_16x16x32_bf16 v[62:65], v[74:77], v[90:93], v[62:65]
	v_mfma_f32_16x16x32_bf16 v[58:61], v[82:85], v[90:93], v[58:61]
	v_mfma_f32_16x16x32_bf16 v[54:57], v[74:77], v[98:101], v[54:57]
	v_mfma_f32_16x16x32_bf16 v[50:53], v[82:85], v[98:101], v[50:53]
	v_mfma_f32_16x16x32_bf16 v[46:49], v[74:77], v[106:109], v[46:49]
	v_mfma_f32_16x16x32_bf16 v[42:45], v[82:85], v[106:109], v[42:45]
	v_mfma_f32_16x16x32_bf16 v[38:41], v[74:77], v[114:117], v[38:41]
	v_mfma_f32_16x16x32_bf16 v[34:37], v[82:85], v[114:117], v[34:37]
	v_mfma_f32_16x16x32_bf16 v[62:65], v[78:81], v[94:97], v[62:65]
	v_mfma_f32_16x16x32_bf16 v[58:61], v[86:89], v[94:97], v[58:61]
	v_mfma_f32_16x16x32_bf16 v[54:57], v[78:81], v[102:105], v[54:57]
	v_mfma_f32_16x16x32_bf16 v[50:53], v[86:89], v[102:105], v[50:53]
	v_mfma_f32_16x16x32_bf16 v[46:49], v[78:81], v[110:113], v[46:49]
	v_mfma_f32_16x16x32_bf16 v[42:45], v[86:89], v[110:113], v[42:45]
	v_mfma_f32_16x16x32_bf16 v[38:41], v[78:81], v[118:121], v[38:41]
	v_mfma_f32_16x16x32_bf16 v[34:37], v[86:89], v[118:121], v[34:37]
	s_setprio 0
	s_setprio 1
	s_setprio 0
	s_barrier
	s_mov_b32 m0, s41
	v_lshl_add_u64 v[122:123], s[30:31], 0, v[0:1]
	global_load_lds_dwordx4 v[122:123], off
	v_lshl_add_u64 v[124:125], s[30:31], 0, v[66:67]
	s_mov_b32 m0, s42
	v_lshl_add_u64 v[126:127], s[34:35], 0, v[0:1]
	global_load_lds_dwordx4 v[124:125], off
	s_mov_b32 m0, s43
	v_lshl_add_u64 v[128:129], s[28:29], 0, v[68:69]
	global_load_lds_dwordx4 v[126:127], off
	v_lshl_add_u64 v[126:127], s[34:35], 0, v[66:67]
	s_mov_b32 m0, s44
	s_nop 0
	global_load_lds_dwordx4 v[126:127], off
	v_lshl_add_u64 v[126:127], s[28:29], 0, v[70:71]
	s_mov_b32 m0, s45
	s_nop 0
	global_load_lds_dwordx4 v[126:127], off
	s_mov_b32 m0, s46
	s_nop 0
	global_load_lds_dwordx4 v[128:129], off
	ds_read_b128 v[90:93], v72 offset:17408
	ds_read_b128 v[94:97], v72 offset:18432
	ds_read_b128 v[98:101], v72 offset:19456
	ds_read_b128 v[102:105], v72 offset:20480
	ds_read_b128 v[106:109], v72 offset:21504
	ds_read_b128 v[110:113], v72 offset:22528
	ds_read_b128 v[114:117], v72 offset:23552
	ds_read_b128 v[118:121], v72 offset:24576
	s_waitcnt vmcnt(8)
	s_waitcnt lgkmcnt(0)
	s_barrier
	s_setprio 1
	s_waitcnt lgkmcnt(0)
	v_mfma_f32_16x16x32_bf16 v[30:33], v[74:77], v[90:93], v[30:33]
	v_mfma_f32_16x16x32_bf16 v[26:29], v[82:85], v[90:93], v[26:29]
	v_mfma_f32_16x16x32_bf16 v[22:25], v[74:77], v[98:101], v[22:25]
	v_mfma_f32_16x16x32_bf16 v[18:21], v[82:85], v[98:101], v[18:21]
	v_mfma_f32_16x16x32_bf16 v[14:17], v[74:77], v[106:109], v[14:17]
	v_mfma_f32_16x16x32_bf16 v[10:13], v[82:85], v[106:109], v[10:13]
	v_mfma_f32_16x16x32_bf16 v[6:9], v[74:77], v[114:117], v[6:9]
	v_mfma_f32_16x16x32_bf16 v[2:5], v[82:85], v[114:117], v[2:5]
	v_mfma_f32_16x16x32_bf16 v[30:33], v[78:81], v[94:97], v[30:33]
	v_mfma_f32_16x16x32_bf16 v[26:29], v[86:89], v[94:97], v[26:29]
	v_mfma_f32_16x16x32_bf16 v[22:25], v[78:81], v[102:105], v[22:25]
	v_mfma_f32_16x16x32_bf16 v[18:21], v[86:89], v[102:105], v[18:21]
	v_mfma_f32_16x16x32_bf16 v[14:17], v[78:81], v[110:113], v[14:17]
	v_mfma_f32_16x16x32_bf16 v[10:13], v[86:89], v[110:113], v[10:13]
	v_mfma_f32_16x16x32_bf16 v[6:9], v[78:81], v[118:121], v[6:9]
	v_mfma_f32_16x16x32_bf16 v[2:5], v[86:89], v[118:121], v[2:5]
	s_setprio 0
	s_setprio 1
	s_setprio 0
	s_barrier
; #define PG8_STAGE(bufoff, gbase, voff) do { _Pragma("unroll") for (int _i = 0; _i < 2; ++_i) \
;         __builtin_amdgcn_global_load_lds((const GAS unsigned*)((const GAS char*)(gbase) + (voff)[_i]), (LAS unsigned*)(lds + (bufoff) + ldsw + _i * 8192), 16, 0, 0); } while (0)
; #define PG8_LDA(dst, b, h) do { _Pragma("unroll") for (int m = 0; m < 4; ++m) _Pragma("unroll") for (int k = 0; k < 2; ++k) dst[m][k] = *(const LAS bf16x8*)(lds + PG8_SA(b, h) + aoff + m * 2048 + k * 1024); } while (0)
; #define PG8_LDB(dst, b, h) do { _Pragma("unroll") for (int n = 0; n < 2; ++n) _Pragma("unroll") for (int k = 0; k < 2; ++k) dst[n][k] = *(const LAS bf16x8*)(lds + PG8_SB(b, h) + boff + n * 2048 + k * 1024); } while (0)
; #define PG8_MMA(ai, bj, At, Bt) do { __builtin_amdgcn_s_setprio(1); _Pragma("unroll") for (int m = 0; m < 4; ++m) _Pragma("unroll") for (int n = 0; n < 2; ++n) _Pragma("unroll") for (int k = 0; k < 2; ++k) \
;         acc[ai][bj][m][n] = __builtin_amdgcn_mfma_f32_16x16x32_bf16(Bt[n][k], At[m][k], acc[ai][bj][m][n], 0, 0, 0); __builtin_amdgcn_s_setprio(0); } while (0)
; #define PG8_WAIT_V(n) asm volatile("s_waitcnt vmcnt(" #n ")" ::: "memory")
; #define PG8_WAIT_L(n) asm volatile("s_waitcnt lgkmcnt(" #n ")" ::: "memory")
; #define PG8_BAR __builtin_amdgcn_s_barrier()
; #define PG8_SCHED __builtin_amdgcn_sched_barrier(0)
; template <class Epi, class Sched, bool ALIGN_EPI>
; __device__ __forceinline__ void gemm_phase(LAS unsigned char* lds, const Gemm g, const Sched& S, const Epi& E, int wave_id) {
;     ...
;             PG8_LDB(B0, 1, 0); PG8_LDB(B1, 1, 1); PG8_SCHED; PG8_LDA(At, 1, 0); PG8_STAGE(PG8_SA(0, 1), a2 + hsA, voffA);
;             PG8_WAIT_V(8); PG8_WAIT_L(0); PG8_BAR; PG8_MMA(0, 0, At, B0); PG8_MMA(0, 1, At, B1); PG8_BAR; PG8_SCHED;
;             PG8_LDA(At, 1, 1); PG8_STAGE(PG8_SB(1, 0), b3, voffB); PG8_STAGE(PG8_SB(1, 1), b3 + hsB, voffB); PG8_STAGE(PG8_SA(1, 0), a3, voffA);
;             PG8_WAIT_V(8); PG8_WAIT_L(0); PG8_BAR; PG8_MMA(1, 0, At, B0); PG8_MMA(1, 1, At, B1); PG8_BAR; PG8_SCHED;
;         }
	s_mov_b32 m0, s47
	v_lshl_add_u64 v[130:131], s[26:27], 0, v[70:71]
	global_load_lds_dwordx4 v[130:131], off
	v_lshl_add_u64 v[130:131], s[26:27], 0, v[68:69]
	s_mov_b32 m0, s48
	s_nop 0
	global_load_lds_dwordx4 v[130:131], off
	v_add_u32_e32 v86, 0x18400, v73
	ds_read_b128 v[74:77], v86
	ds_read_b128 v[78:81], v86 offset:1024
	ds_read_b128 v[82:85], v86 offset:2048
	ds_read_b128 v[86:89], v86 offset:3072
	ds_read_b128 v[90:93], v72 offset:33792
	ds_read_b128 v[94:97], v72 offset:34816
	ds_read_b128 v[98:101], v72 offset:35840
	ds_read_b128 v[102:105], v72 offset:36864
	ds_read_b128 v[106:109], v72 offset:37888
	ds_read_b128 v[110:113], v72 offset:38912
	ds_read_b128 v[114:117], v72 offset:39936
	ds_read_b128 v[118:121], v72 offset:40960
	s_waitcnt vmcnt(8)
	s_waitcnt lgkmcnt(0)
	s_barrier
	s_setprio 1
	s_waitcnt lgkmcnt(0)
	v_mfma_f32_16x16x32_bf16 v[62:65], v[74:77], v[90:93], v[62:65]
	v_mfma_f32_16x16x32_bf16 v[58:61], v[82:85], v[90:93], v[58:61]
	v_mfma_f32_16x16x32_bf16 v[54:57], v[74:77], v[98:101], v[54:57]
	v_mfma_f32_16x16x32_bf16 v[50:53], v[82:85], v[98:101], v[50:53]
	v_mfma_f32_16x16x32_bf16 v[46:49], v[74:77], v[106:109], v[46:49]
	v_mfma_f32_16x16x32_bf16 v[42:45], v[82:85], v[106:109], v[42:45]
	v_mfma_f32_16x16x32_bf16 v[38:41], v[74:77], v[114:117], v[38:41]
	v_mfma_f32_16x16x32_bf16 v[34:37], v[82:85], v[114:117], v[34:37]
	v_mfma_f32_16x16x32_bf16 v[62:65], v[78:81], v[94:97], v[62:65]
	v_mfma_f32_16x16x32_bf16 v[58:61], v[86:89], v[94:97], v[58:61]
	v_mfma_f32_16x16x32_bf16 v[54:57], v[78:81], v[102:105], v[54:57]
	v_mfma_f32_16x16x32_bf16 v[50:53], v[86:89], v[102:105], v[50:53]
	v_mfma_f32_16x16x32_bf16 v[46:49], v[78:81], v[110:113], v[46:49]
	v_mfma_f32_16x16x32_bf16 v[42:45], v[86:89], v[110:113], v[42:45]
	v_mfma_f32_16x16x32_bf16 v[38:41], v[78:81], v[118:121], v[38:41]
	v_mfma_f32_16x16x32_bf16 v[34:37], v[86:89], v[118:121], v[34:37]
	s_setprio 0
	s_setprio 1
	s_setprio 0
	s_barrier
	s_mov_b32 m0, s51
	v_lshl_add_u64 v[122:123], v[122:123], 0, s[92:93]
	global_load_lds_dwordx4 v[122:123], off
	v_lshl_add_u64 v[122:123], v[124:125], 0, s[92:93]
	s_mov_b32 m0, s52
	s_nop 0
	global_load_lds_dwordx4 v[122:123], off
	v_lshl_add_u64 v[122:123], s[24:25], 0, v[0:1]
	s_mov_b32 m0, s55
	s_nop 0
	global_load_lds_dwordx4 v[122:123], off
	v_lshl_add_u64 v[122:123], s[24:25], 0, v[66:67]
	s_mov_b32 m0, s56
	s_nop 0
	global_load_lds_dwordx4 v[122:123], off
	v_lshl_add_u64 v[122:123], v[126:127], 0, s[92:93]
	s_mov_b32 m0, s53
	s_nop 0
	global_load_lds_dwordx4 v[122:123], off
	v_lshl_add_u64 v[122:123], v[128:129], 0, s[92:93]
	s_mov_b32 m0, s54
	s_nop 0
	global_load_lds_dwordx4 v[122:123], off
	ds_read_b128 v[90:93], v72 offset:50176
	ds_read_b128 v[94:97], v72 offset:51200
	ds_read_b128 v[98:101], v72 offset:52224
	ds_read_b128 v[102:105], v72 offset:53248
	ds_read_b128 v[106:109], v72 offset:54272
	ds_read_b128 v[110:113], v72 offset:55296
	ds_read_b128 v[114:117], v72 offset:56320
	ds_read_b128 v[118:121], v72 offset:57344
	s_waitcnt vmcnt(8)
	s_waitcnt lgkmcnt(0)
	s_barrier
	s_setprio 1
	s_waitcnt lgkmcnt(0)
	v_mfma_f32_16x16x32_bf16 v[30:33], v[74:77], v[90:93], v[30:33]
	v_mfma_f32_16x16x32_bf16 v[26:29], v[82:85], v[90:93], v[26:29]
	v_mfma_f32_16x16x32_bf16 v[22:25], v[74:77], v[98:101], v[22:25]
	v_mfma_f32_16x16x32_bf16 v[18:21], v[82:85], v[98:101], v[18:21]
	v_mfma_f32_16x16x32_bf16 v[14:17], v[74:77], v[106:109], v[14:17]
	v_mfma_f32_16x16x32_bf16 v[10:13], v[82:85], v[106:109], v[10:13]
	v_mfma_f32_16x16x32_bf16 v[6:9], v[74:77], v[114:117], v[6:9]
	v_mfma_f32_16x16x32_bf16 v[2:5], v[82:85], v[114:117], v[2:5]
	v_mfma_f32_16x16x32_bf16 v[30:33], v[78:81], v[94:97], v[30:33]
	v_mfma_f32_16x16x32_bf16 v[26:29], v[86:89], v[94:97], v[26:29]
	v_mfma_f32_16x16x32_bf16 v[22:25], v[78:81], v[102:105], v[22:25]
	v_mfma_f32_16x16x32_bf16 v[18:21], v[86:89], v[102:105], v[18:21]
	v_mfma_f32_16x16x32_bf16 v[14:17], v[78:81], v[110:113], v[14:17]
	v_mfma_f32_16x16x32_bf16 v[10:13], v[86:89], v[110:113], v[10:13]
	v_mfma_f32_16x16x32_bf16 v[6:9], v[78:81], v[118:121], v[6:9]
	v_mfma_f32_16x16x32_bf16 v[2:5], v[86:89], v[118:121], v[2:5]
	s_setprio 0
	s_setprio 1
	s_setprio 0
	s_barrier
	s_andn2_b64 vcc, exec, s[22:23]
	s_mov_b64 s[24:25], -1
	s_mov_b64 s[22:23], 0
	s_mov_b64 s[26:27], 0x100
	s_cbranch_vccz .LBB0_1335
	s_and_b64 vcc, exec, s[14:15]
	s_cbranch_vccz .LBB0_1338
	s_barrier

; #define PG8_STAGE(bufoff, gbase, voff) do { _Pragma("unroll") for (int _i = 0; _i < 2; ++_i) \
;         __builtin_amdgcn_global_load_lds((const GAS unsigned*)((const GAS char*)(gbase) + (voff)[_i]), (LAS unsigned*)(lds + (bufoff) + ldsw + _i * 8192), 16, 0, 0); } while (0)
; #define PG8_LDA(dst, b, h) do { _Pragma("unroll") for (int m = 0; m < 4; ++m) _Pragma("unroll") for (int k = 0; k < 2; ++k) dst[m][k] = *(const LAS bf16x8*)(lds + PG8_SA(b, h) + aoff + m * 2048 + k * 1024); } while (0)
; #define PG8_LDB(dst, b, h) do { _Pragma("unroll") for (int n = 0; n < 2; ++n) _Pragma("unroll") for (int k = 0; k < 2; ++k) dst[n][k] = *(const LAS bf16x8*)(lds + PG8_SB(b, h) + boff + n * 2048 + k * 1024); } while (0)
; #define PG8_MMA(ai, bj, At, Bt) do { __builtin_amdgcn_s_setprio(1); _Pragma("unroll") for (int m = 0; m < 4; ++m) _Pragma("unroll") for (int n = 0; n < 2; ++n) _Pragma("unroll") for (int k = 0; k < 2; ++k) \
;         acc[ai][bj][m][n] = __builtin_amdgcn_mfma_f32_16x16x32_bf16(Bt[n][k], At[m][k], acc[ai][bj][m][n], 0, 0, 0); __builtin_amdgcn_s_setprio(0); } while (0)
; #define PG8_WAIT_V(n) asm volatile("s_waitcnt vmcnt(" #n ")" ::: "memory")
; #define PG8_WAIT_L(n) asm volatile("s_waitcnt lgkmcnt(" #n ")" ::: "memory")
; #define PG8_BAR __builtin_amdgcn_s_barrier()
; #define PG8_SCHED __builtin_amdgcn_sched_barrier(0)
; template <class Epi, class Sched, bool ALIGN_EPI>
; __device__ __forceinline__ void gemm_phase(LAS unsigned char* lds, const Gemm g, const Sched& S, const Epi& E, int wave_id) {
;     ...
;             PG8_LDB(B0, 0, 0); PG8_LDB(B1, 0, 1); PG8_SCHED; PG8_LDA(At, 0, 0); PG8_STAGE(PG8_SA(1, 1), a1 + hsA, voffA);
;             PG8_WAIT_V(8); PG8_WAIT_L(0); PG8_BAR; PG8_MMA(0, 0, At, B0); PG8_MMA(0, 1, At, B1); PG8_BAR; PG8_SCHED;
;             PG8_LDA(At, 0, 1); PG8_STAGE(PG8_SB(0, 0), b2, voffB); PG8_STAGE(PG8_SB(0, 1), b2 + hsB, voffB); PG8_STAGE(PG8_SA(0, 0), a2, voffA);
;             PG8_WAIT_V(8); PG8_WAIT_L(0); PG8_BAR; PG8_MMA(1, 0, At, B0); PG8_MMA(1, 1, At, B1); PG8_BAR; PG8_SCHED;
.LBB0_1458:
	s_add_u32 s21, s26, s34
	s_addc_u32 s33, s27, s35
	s_add_u32 s38, s21, 0x100
	s_addc_u32 s39, s33, 0
	s_and_b64 s[36:37], s[30:31], exec
	s_cselect_b32 s37, s3, s39
	s_cselect_b32 s36, s5, s38
	s_add_u32 s34, s6, s34
	s_addc_u32 s35, s7, s35
	s_add_u32 s34, s34, 0x100
	s_addc_u32 s35, s35, 0
	s_and_b64 s[30:31], s[30:31], exec
	s_cselect_b32 s39, s9, s35
	s_cselect_b32 s38, s19, s34
	s_add_u32 s42, s21, 0x10080
	s_addc_u32 s43, s33, 0
	s_add_i32 m0, s49, 0xc400
	s_add_i32 s21, s49, 0xe400
	s_add_u32 s40, s38, 0x10000
	s_addc_u32 s41, s39, 0
	s_add_u32 s34, s36, 0x10000
	s_addc_u32 s35, s37, 0
	s_add_u32 s30, s38, 0x10080
	s_addc_u32 s31, s39, 0
	v_lshl_add_u64 v[2:3], s[42:43], 0, v[140:141]
	global_load_lds_dwordx4 v[2:3], off
	v_lshl_add_u64 v[2:3], s[42:43], 0, v[144:145]
	s_mov_b32 m0, s21
	s_nop 0
	global_load_lds_dwordx4 v[2:3], off
	v_add_u32_e32 v0, 0x10400, v159
	ds_read_b128 v[100:103], v0
	ds_read_b128 v[108:111], v0 offset:1024
	ds_read_b128 v[148:151], v0 offset:2048
	ds_read_b128 v[152:155], v0 offset:3072
	v_add_u32_e32 v0, 0x14400, v159
	ds_read_b128 v[160:163], v0
	ds_read_b128 v[164:167], v0 offset:1024
	ds_read_b128 v[168:171], v0 offset:2048
	ds_read_b128 v[172:175], v0 offset:3072
	ds_read_b128 v[176:179], v158 offset:1024
	ds_read_b128 v[180:183], v158 offset:2048
	ds_read_b128 v[184:187], v158 offset:3072
	ds_read_b128 v[188:191], v158 offset:4096
	ds_read_b128 v[192:195], v158 offset:5120
	ds_read_b128 v[196:199], v158 offset:6144
	ds_read_b128 v[200:203], v158 offset:7168
	ds_read_b128 v[204:207], v158 offset:8192
	s_waitcnt vmcnt(8)
	s_waitcnt lgkmcnt(0)
	s_barrier
	s_setprio 1
	s_waitcnt lgkmcnt(0)
	v_mfma_f32_16x16x32_bf16 v[136:139], v[100:103], v[176:179], v[136:139]
	v_mfma_f32_16x16x32_bf16 v[132:135], v[148:151], v[176:179], v[132:135]
	v_mfma_f32_16x16x32_bf16 v[128:131], v[100:103], v[184:187], v[128:131]
	v_mfma_f32_16x16x32_bf16 v[124:127], v[148:151], v[184:187], v[124:127]
	v_mfma_f32_16x16x32_bf16 v[120:123], v[100:103], v[192:195], v[120:123]
	v_mfma_f32_16x16x32_bf16 v[116:119], v[148:151], v[192:195], v[116:119]
	v_mfma_f32_16x16x32_bf16 v[112:115], v[100:103], v[200:203], v[112:115]
	v_mfma_f32_16x16x32_bf16 v[104:107], v[148:151], v[200:203], v[104:107]
	v_mfma_f32_16x16x32_bf16 v[136:139], v[108:111], v[180:183], v[136:139]
	v_mfma_f32_16x16x32_bf16 v[132:135], v[152:155], v[180:183], v[132:135]
	v_mfma_f32_16x16x32_bf16 v[128:131], v[108:111], v[188:191], v[128:131]
	v_mfma_f32_16x16x32_bf16 v[124:127], v[152:155], v[188:191], v[124:127]
	v_mfma_f32_16x16x32_bf16 v[120:123], v[108:111], v[196:199], v[120:123]
	v_mfma_f32_16x16x32_bf16 v[116:119], v[152:155], v[196:199], v[116:119]
	v_mfma_f32_16x16x32_bf16 v[112:115], v[108:111], v[204:207], v[112:115]
	v_mfma_f32_16x16x32_bf16 v[104:107], v[152:155], v[204:207], v[104:107]
	s_setprio 0
	s_setprio 1
	v_mfma_f32_16x16x32_bf16 v[64:67], v[160:163], v[176:179], v[64:67]
	v_mfma_f32_16x16x32_bf16 v[60:63], v[168:171], v[176:179], v[60:63]
	v_mfma_f32_16x16x32_bf16 v[56:59], v[160:163], v[184:187], v[56:59]
	v_mfma_f32_16x16x32_bf16 v[52:55], v[168:171], v[184:187], v[52:55]
	v_mfma_f32_16x16x32_bf16 v[48:51], v[160:163], v[192:195], v[48:51]
	v_mfma_f32_16x16x32_bf16 v[44:47], v[168:171], v[192:195], v[44:47]
	v_mfma_f32_16x16x32_bf16 v[40:43], v[160:163], v[200:203], v[40:43]
	v_mfma_f32_16x16x32_bf16 v[36:39], v[168:171], v[200:203], v[36:39]
	v_mfma_f32_16x16x32_bf16 v[64:67], v[164:167], v[180:183], v[64:67]
	v_mfma_f32_16x16x32_bf16 v[60:63], v[172:175], v[180:183], v[60:63]
	v_mfma_f32_16x16x32_bf16 v[56:59], v[164:167], v[188:191], v[56:59]
	v_mfma_f32_16x16x32_bf16 v[52:55], v[172:175], v[188:191], v[52:55]
	v_mfma_f32_16x16x32_bf16 v[48:51], v[164:167], v[196:199], v[48:51]
	v_mfma_f32_16x16x32_bf16 v[44:47], v[172:175], v[196:199], v[44:47]
	v_mfma_f32_16x16x32_bf16 v[40:43], v[164:167], v[204:207], v[40:43]
	v_mfma_f32_16x16x32_bf16 v[36:39], v[172:175], v[204:207], v[36:39]
	s_setprio 0
	s_barrier
	s_mov_b32 m0, s50
	v_lshl_add_u64 v[156:157], s[38:39], 0, v[142:143]
	global_load_lds_dwordx4 v[156:157], off
	v_lshl_add_u64 v[208:209], s[38:39], 0, v[146:147]
	s_mov_b32 m0, s51
	v_lshl_add_u64 v[2:3], s[40:41], 0, v[142:143]
	global_load_lds_dwordx4 v[208:209], off
	s_mov_b32 m0, s52
	v_lshl_add_u64 v[210:211], s[36:37], 0, v[140:141]
	global_load_lds_dwordx4 v[2:3], off
	v_lshl_add_u64 v[2:3], s[40:41], 0, v[146:147]
	s_mov_b32 m0, s53
	v_lshl_add_u64 v[212:213], s[36:37], 0, v[144:145]
	global_load_lds_dwordx4 v[2:3], off
	s_mov_b32 m0, s54
	s_nop 0
	global_load_lds_dwordx4 v[210:211], off
	s_mov_b32 m0, s55
	s_nop 0
	global_load_lds_dwordx4 v[212:213], off
	ds_read_b128 v[176:179], v158 offset:17408
	ds_read_b128 v[180:183], v158 offset:18432
	ds_read_b128 v[184:187], v158 offset:19456
	ds_read_b128 v[188:191], v158 offset:20480
	ds_read_b128 v[192:195], v158 offset:21504
	ds_read_b128 v[196:199], v158 offset:22528
	ds_read_b128 v[200:203], v158 offset:23552
	ds_read_b128 v[204:207], v158 offset:24576
	s_waitcnt vmcnt(8)
	s_waitcnt lgkmcnt(0)
	s_barrier
; #define PG8_STAGE(bufoff, gbase, voff) do { _Pragma("unroll") for (int _i = 0; _i < 2; ++_i) \
;         __builtin_amdgcn_global_load_lds((const GAS unsigned*)((const GAS char*)(gbase) + (voff)[_i]), (LAS unsigned*)(lds + (bufoff) + ldsw + _i * 8192), 16, 0, 0); } while (0)
; #define PG8_LDA(dst, b, h) do { _Pragma("unroll") for (int m = 0; m < 4; ++m) _Pragma("unroll") for (int k = 0; k < 2; ++k) dst[m][k] = *(const LAS bf16x8*)(lds + PG8_SA(b, h) + aoff + m * 2048 + k * 1024); } while (0)
; #define PG8_LDB(dst, b, h) do { _Pragma("unroll") for (int n = 0; n < 2; ++n) _Pragma("unroll") for (int k = 0; k < 2; ++k) dst[n][k] = *(const LAS bf16x8*)(lds + PG8_SB(b, h) + boff + n * 2048 + k * 1024); } while (0)
; #define PG8_MMA(ai, bj, At, Bt) do { __builtin_amdgcn_s_setprio(1); _Pragma("unroll") for (int m = 0; m < 4; ++m) _Pragma("unroll") for (int n = 0; n < 2; ++n) _Pragma("unroll") for (int k = 0; k < 2; ++k) \
;         acc[ai][bj][m][n] = __builtin_amdgcn_mfma_f32_16x16x32_bf16(Bt[n][k], At[m][k], acc[ai][bj][m][n], 0, 0, 0); __builtin_amdgcn_s_setprio(0); } while (0)
; #define PG8_WAIT_V(n) asm volatile("s_waitcnt vmcnt(" #n ")" ::: "memory")
; #define PG8_WAIT_L(n) asm volatile("s_waitcnt lgkmcnt(" #n ")" ::: "memory")
; #define PG8_BAR __builtin_amdgcn_s_barrier()
; #define PG8_SCHED __builtin_amdgcn_sched_barrier(0)
; template <class Epi, class Sched, bool ALIGN_EPI>
; __device__ __forceinline__ void gemm_phase(LAS unsigned char* lds, const Gemm g, const Sched& S, const Epi& E, int wave_id) {
;     ...
;             PG8_WAIT_V(8); PG8_WAIT_L(0); PG8_BAR; PG8_MMA(1, 0, At, B0); PG8_MMA(1, 1, At, B1); PG8_BAR; PG8_SCHED;
;             PG8_LDB(B0, 1, 0); PG8_LDB(B1, 1, 1); PG8_SCHED; PG8_LDA(At, 1, 0); PG8_STAGE(PG8_SA(0, 1), a2 + hsA, voffA);
;             PG8_WAIT_V(8); PG8_WAIT_L(0); PG8_BAR; PG8_MMA(0, 0, At, B0); PG8_MMA(0, 1, At, B1); PG8_BAR; PG8_SCHED;
	s_setprio 1
	s_waitcnt lgkmcnt(0)
	v_mfma_f32_16x16x32_bf16 v[96:99], v[100:103], v[176:179], v[96:99]
	v_mfma_f32_16x16x32_bf16 v[92:95], v[148:151], v[176:179], v[92:95]
	v_mfma_f32_16x16x32_bf16 v[88:91], v[100:103], v[184:187], v[88:91]
	v_mfma_f32_16x16x32_bf16 v[84:87], v[148:151], v[184:187], v[84:87]
	v_mfma_f32_16x16x32_bf16 v[80:83], v[100:103], v[192:195], v[80:83]
	v_mfma_f32_16x16x32_bf16 v[76:79], v[148:151], v[192:195], v[76:79]
	v_mfma_f32_16x16x32_bf16 v[72:75], v[100:103], v[200:203], v[72:75]
	v_mfma_f32_16x16x32_bf16 v[68:71], v[148:151], v[200:203], v[68:71]
	v_mfma_f32_16x16x32_bf16 v[96:99], v[108:111], v[180:183], v[96:99]
	v_mfma_f32_16x16x32_bf16 v[92:95], v[152:155], v[180:183], v[92:95]
	v_mfma_f32_16x16x32_bf16 v[88:91], v[108:111], v[188:191], v[88:91]
	v_mfma_f32_16x16x32_bf16 v[84:87], v[152:155], v[188:191], v[84:87]
	v_mfma_f32_16x16x32_bf16 v[80:83], v[108:111], v[196:199], v[80:83]
	v_mfma_f32_16x16x32_bf16 v[76:79], v[152:155], v[196:199], v[76:79]
	v_mfma_f32_16x16x32_bf16 v[72:75], v[108:111], v[204:207], v[72:75]
	v_mfma_f32_16x16x32_bf16 v[68:71], v[152:155], v[204:207], v[68:71]
	s_setprio 0
	s_setprio 1
	v_mfma_f32_16x16x32_bf16 v[32:35], v[160:163], v[176:179], v[32:35]
	v_mfma_f32_16x16x32_bf16 v[28:31], v[168:171], v[176:179], v[28:31]
	v_mfma_f32_16x16x32_bf16 v[24:27], v[160:163], v[184:187], v[24:27]
	v_mfma_f32_16x16x32_bf16 v[20:23], v[168:171], v[184:187], v[20:23]
	v_mfma_f32_16x16x32_bf16 v[16:19], v[160:163], v[192:195], v[16:19]
	v_mfma_f32_16x16x32_bf16 v[12:15], v[168:171], v[192:195], v[12:15]
	v_mfma_f32_16x16x32_bf16 v[8:11], v[160:163], v[200:203], v[8:11]
	v_mfma_f32_16x16x32_bf16 v[2:5], v[168:171], v[200:203], v[4:7]
	v_mfma_f32_16x16x32_bf16 v[32:35], v[164:167], v[180:183], v[32:35]
	v_mfma_f32_16x16x32_bf16 v[28:31], v[172:175], v[180:183], v[28:31]
	v_mfma_f32_16x16x32_bf16 v[24:27], v[164:167], v[188:191], v[24:27]
	v_mfma_f32_16x16x32_bf16 v[20:23], v[172:175], v[188:191], v[20:23]
	v_mfma_f32_16x16x32_bf16 v[16:19], v[164:167], v[196:199], v[16:19]
	v_mfma_f32_16x16x32_bf16 v[12:15], v[172:175], v[196:199], v[12:15]
	v_mfma_f32_16x16x32_bf16 v[8:11], v[164:167], v[204:207], v[8:11]
	v_mfma_f32_16x16x32_bf16 v[2:5], v[172:175], v[204:207], v[2:5]
	s_setprio 0
	s_barrier
	s_mov_b32 m0, s56
	v_lshl_add_u64 v[6:7], s[34:35], 0, v[140:141]
	global_load_lds_dwordx4 v[6:7], off
	v_lshl_add_u64 v[6:7], s[34:35], 0, v[144:145]
	s_mov_b32 m0, s57
	s_nop 0
	global_load_lds_dwordx4 v[6:7], off
	v_add_u32_e32 v0, 0x18400, v159
	ds_read_b128 v[100:103], v0
	ds_read_b128 v[108:111], v0 offset:1024
	ds_read_b128 v[148:151], v0 offset:2048
	ds_read_b128 v[152:155], v0 offset:3072
	v_add_u32_e32 v0, 0x1c400, v159
	ds_read_b128 v[160:163], v0
	ds_read_b128 v[164:167], v0 offset:1024
	ds_read_b128 v[168:171], v0 offset:2048
	ds_read_b128 v[172:175], v0 offset:3072
	ds_read_b128 v[176:179], v158 offset:33792
	ds_read_b128 v[180:183], v158 offset:34816
	ds_read_b128 v[184:187], v158 offset:35840
	ds_read_b128 v[188:191], v158 offset:36864
	ds_read_b128 v[192:195], v158 offset:37888
	ds_read_b128 v[196:199], v158 offset:38912
	ds_read_b128 v[200:203], v158 offset:39936
	ds_read_b128 v[204:207], v158 offset:40960
	s_waitcnt vmcnt(8)
	s_waitcnt lgkmcnt(0)
	s_barrier
	s_setprio 1
	s_waitcnt lgkmcnt(0)
	v_mfma_f32_16x16x32_bf16 v[136:139], v[100:103], v[176:179], v[136:139]
	v_mfma_f32_16x16x32_bf16 v[132:135], v[148:151], v[176:179], v[132:135]
	v_mfma_f32_16x16x32_bf16 v[128:131], v[100:103], v[184:187], v[128:131]
	v_mfma_f32_16x16x32_bf16 v[124:127], v[148:151], v[184:187], v[124:127]
	v_mfma_f32_16x16x32_bf16 v[120:123], v[100:103], v[192:195], v[120:123]
	v_mfma_f32_16x16x32_bf16 v[116:119], v[148:151], v[192:195], v[116:119]
	v_mfma_f32_16x16x32_bf16 v[112:115], v[100:103], v[200:203], v[112:115]
	v_mfma_f32_16x16x32_bf16 v[104:107], v[148:151], v[200:203], v[104:107]
	v_mfma_f32_16x16x32_bf16 v[136:139], v[108:111], v[180:183], v[136:139]
	v_mfma_f32_16x16x32_bf16 v[132:135], v[152:155], v[180:183], v[132:135]
	v_mfma_f32_16x16x32_bf16 v[128:131], v[108:111], v[188:191], v[128:131]
	v_mfma_f32_16x16x32_bf16 v[124:127], v[152:155], v[188:191], v[124:127]
	v_mfma_f32_16x16x32_bf16 v[120:123], v[108:111], v[196:199], v[120:123]
	v_mfma_f32_16x16x32_bf16 v[116:119], v[152:155], v[196:199], v[116:119]
	v_mfma_f32_16x16x32_bf16 v[112:115], v[108:111], v[204:207], v[112:115]
	v_mfma_f32_16x16x32_bf16 v[104:107], v[152:155], v[204:207], v[104:107]
	s_setprio 0
	s_setprio 1
	v_mfma_f32_16x16x32_bf16 v[64:67], v[160:163], v[176:179], v[64:67]
	v_mfma_f32_16x16x32_bf16 v[60:63], v[168:171], v[176:179], v[60:63]
	v_mfma_f32_16x16x32_bf16 v[56:59], v[160:163], v[184:187], v[56:59]
	v_mfma_f32_16x16x32_bf16 v[52:55], v[168:171], v[184:187], v[52:55]
	v_mfma_f32_16x16x32_bf16 v[48:51], v[160:163], v[192:195], v[48:51]
	v_mfma_f32_16x16x32_bf16 v[44:47], v[168:171], v[192:195], v[44:47]
	v_mfma_f32_16x16x32_bf16 v[40:43], v[160:163], v[200:203], v[40:43]
	v_mfma_f32_16x16x32_bf16 v[36:39], v[168:171], v[200:203], v[36:39]
	v_mfma_f32_16x16x32_bf16 v[64:67], v[164:167], v[180:183], v[64:67]
	v_mfma_f32_16x16x32_bf16 v[60:63], v[172:175], v[180:183], v[60:63]
	v_mfma_f32_16x16x32_bf16 v[56:59], v[164:167], v[188:191], v[56:59]
	v_mfma_f32_16x16x32_bf16 v[52:55], v[172:175], v[188:191], v[52:55]
	v_mfma_f32_16x16x32_bf16 v[48:51], v[164:167], v[196:199], v[48:51]
	v_mfma_f32_16x16x32_bf16 v[44:47], v[172:175], v[196:199], v[44:47]
	v_mfma_f32_16x16x32_bf16 v[40:43], v[164:167], v[204:207], v[40:43]
	v_mfma_f32_16x16x32_bf16 v[36:39], v[172:175], v[204:207], v[36:39]
	s_setprio 0
	s_barrier
; #define PG8_STAGE(bufoff, gbase, voff) do { _Pragma("unroll") for (int _i = 0; _i < 2; ++_i) \
;         __builtin_amdgcn_global_load_lds((const GAS unsigned*)((const GAS char*)(gbase) + (voff)[_i]), (LAS unsigned*)(lds + (bufoff) + ldsw + _i * 8192), 16, 0, 0); } while (0)
; #define PG8_LDA(dst, b, h) do { _Pragma("unroll") for (int m = 0; m < 4; ++m) _Pragma("unroll") for (int k = 0; k < 2; ++k) dst[m][k] = *(const LAS bf16x8*)(lds + PG8_SA(b, h) + aoff + m * 2048 + k * 1024); } while (0)
; #define PG8_MMA(ai, bj, At, Bt) do { __builtin_amdgcn_s_setprio(1); _Pragma("unroll") for (int m = 0; m < 4; ++m) _Pragma("unroll") for (int n = 0; n < 2; ++n) _Pragma("unroll") for (int k = 0; k < 2; ++k) \
;         acc[ai][bj][m][n] = __builtin_amdgcn_mfma_f32_16x16x32_bf16(Bt[n][k], At[m][k], acc[ai][bj][m][n], 0, 0, 0); __builtin_amdgcn_s_setprio(0); } while (0)
; #define PG8_WAIT_V(n) asm volatile("s_waitcnt vmcnt(" #n ")" ::: "memory")
; #define PG8_WAIT_L(n) asm volatile("s_waitcnt lgkmcnt(" #n ")" ::: "memory")
; #define PG8_BAR __builtin_amdgcn_s_barrier()
; #define PG8_SCHED __builtin_amdgcn_sched_barrier(0)
; template <class Epi, class Sched, bool ALIGN_EPI>
; __device__ __forceinline__ void gemm_phase(LAS unsigned char* lds, const Gemm g, const Sched& S, const Epi& E, int wave_id) {
;     ...
;             PG8_LDA(At, 1, 1); PG8_STAGE(PG8_SB(1, 0), b3, voffB); PG8_STAGE(PG8_SB(1, 1), b3 + hsB, voffB); PG8_STAGE(PG8_SA(1, 0), a3, voffA);
;             PG8_WAIT_V(8); PG8_WAIT_L(0); PG8_BAR; PG8_MMA(1, 0, At, B0); PG8_MMA(1, 1, At, B1); PG8_BAR; PG8_SCHED;
;         }
	s_mov_b32 m0, s63
	v_lshl_add_u64 v[6:7], v[156:157], 0, s[92:93]
	global_load_lds_dwordx4 v[6:7], off
	v_lshl_add_u64 v[6:7], v[208:209], 0, s[92:93]
	s_mov_b32 m0, s64
	s_nop 0
	global_load_lds_dwordx4 v[6:7], off
	v_lshl_add_u64 v[6:7], s[30:31], 0, v[142:143]
	s_mov_b32 m0, s67
	s_nop 0
	global_load_lds_dwordx4 v[6:7], off
	v_lshl_add_u64 v[6:7], s[30:31], 0, v[146:147]
	s_mov_b32 m0, s72
	s_nop 0
	global_load_lds_dwordx4 v[6:7], off
	v_lshl_add_u64 v[6:7], v[210:211], 0, s[92:93]
	s_mov_b32 m0, s65
	s_nop 0
	global_load_lds_dwordx4 v[6:7], off
	v_lshl_add_u64 v[6:7], v[212:213], 0, s[92:93]
	s_mov_b32 m0, s66
	s_nop 0
	global_load_lds_dwordx4 v[6:7], off
	ds_read_b128 v[176:179], v158 offset:50176
	ds_read_b128 v[180:183], v158 offset:51200
	ds_read_b128 v[184:187], v158 offset:52224
	ds_read_b128 v[188:191], v158 offset:53248
	ds_read_b128 v[192:195], v158 offset:54272
	ds_read_b128 v[196:199], v158 offset:55296
	ds_read_b128 v[200:203], v158 offset:56320
	ds_read_b128 v[204:207], v158 offset:57344
	s_waitcnt vmcnt(8)
	s_waitcnt lgkmcnt(0)
	s_barrier
	s_setprio 1
	s_waitcnt lgkmcnt(0)
	v_mfma_f32_16x16x32_bf16 v[96:99], v[100:103], v[176:179], v[96:99]
	v_mfma_f32_16x16x32_bf16 v[92:95], v[148:151], v[176:179], v[92:95]
	v_mfma_f32_16x16x32_bf16 v[88:91], v[100:103], v[184:187], v[88:91]
	v_mfma_f32_16x16x32_bf16 v[84:87], v[148:151], v[184:187], v[84:87]
	v_mfma_f32_16x16x32_bf16 v[80:83], v[100:103], v[192:195], v[80:83]
	v_mfma_f32_16x16x32_bf16 v[76:79], v[148:151], v[192:195], v[76:79]
	v_mfma_f32_16x16x32_bf16 v[72:75], v[100:103], v[200:203], v[72:75]
	v_mfma_f32_16x16x32_bf16 v[68:71], v[148:151], v[200:203], v[68:71]
	v_mfma_f32_16x16x32_bf16 v[96:99], v[108:111], v[180:183], v[96:99]
	v_mfma_f32_16x16x32_bf16 v[92:95], v[152:155], v[180:183], v[92:95]
	v_mfma_f32_16x16x32_bf16 v[88:91], v[108:111], v[188:191], v[88:91]
	v_mfma_f32_16x16x32_bf16 v[84:87], v[152:155], v[188:191], v[84:87]
	v_mfma_f32_16x16x32_bf16 v[80:83], v[108:111], v[196:199], v[80:83]
	v_mfma_f32_16x16x32_bf16 v[76:79], v[152:155], v[196:199], v[76:79]
	v_mfma_f32_16x16x32_bf16 v[72:75], v[108:111], v[204:207], v[72:75]
	v_mfma_f32_16x16x32_bf16 v[68:71], v[152:155], v[204:207], v[68:71]
	s_setprio 0
	s_setprio 1
	v_mfma_f32_16x16x32_bf16 v[32:35], v[160:163], v[176:179], v[32:35]
	v_mfma_f32_16x16x32_bf16 v[28:31], v[168:171], v[176:179], v[28:31]
	v_mfma_f32_16x16x32_bf16 v[24:27], v[160:163], v[184:187], v[24:27]
	v_mfma_f32_16x16x32_bf16 v[20:23], v[168:171], v[184:187], v[20:23]
	v_mfma_f32_16x16x32_bf16 v[16:19], v[160:163], v[192:195], v[16:19]
	v_mfma_f32_16x16x32_bf16 v[12:15], v[168:171], v[192:195], v[12:15]
	v_mfma_f32_16x16x32_bf16 v[6:9], v[160:163], v[200:203], v[8:11]
	v_mfma_f32_16x16x32_bf16 v[2:5], v[168:171], v[200:203], v[2:5]
	v_mfma_f32_16x16x32_bf16 v[32:35], v[164:167], v[180:183], v[32:35]
	v_mfma_f32_16x16x32_bf16 v[28:31], v[172:175], v[180:183], v[28:31]
	v_mfma_f32_16x16x32_bf16 v[24:27], v[164:167], v[188:191], v[24:27]
	v_mfma_f32_16x16x32_bf16 v[20:23], v[172:175], v[188:191], v[20:23]
	v_mfma_f32_16x16x32_bf16 v[16:19], v[164:167], v[196:199], v[16:19]
	v_mfma_f32_16x16x32_bf16 v[12:15], v[172:175], v[196:199], v[12:15]
	v_mfma_f32_16x16x32_bf16 v[8:11], v[164:167], v[204:207], v[6:9]
	v_mfma_f32_16x16x32_bf16 v[4:7], v[172:175], v[204:207], v[2:5]
	s_setprio 0
	s_barrier
	s_andn2_b64 vcc, exec, s[28:29]
	s_mov_b64 s[30:31], -1
	s_mov_b64 s[28:29], 0
	s_mov_b64 s[34:35], 0x100
	s_cbranch_vccz .LBB0_1458
	s_and_b64 vcc, exec, s[16:17]
	s_cbranch_vccz .LBB0_1461
	s_barrier

; #define PG8_STAGE(bufoff, gbase, voff) do { _Pragma("unroll") for (int _i = 0; _i < 2; ++_i) \
;         __builtin_amdgcn_global_load_lds((const GAS unsigned*)((const GAS char*)(gbase) + (voff)[_i]), (LAS unsigned*)(lds + (bufoff) + ldsw + _i * 8192), 16, 0, 0); } while (0)
; #define PG8_LDA(dst, b, h) do { _Pragma("unroll") for (int m = 0; m < 4; ++m) _Pragma("unroll") for (int k = 0; k < 2; ++k) dst[m][k] = *(const LAS bf16x8*)(lds + PG8_SA(b, h) + aoff + m * 2048 + k * 1024); } while (0)
; #define PG8_LDB(dst, b, h) do { _Pragma("unroll") for (int n = 0; n < 2; ++n) _Pragma("unroll") for (int k = 0; k < 2; ++k) dst[n][k] = *(const LAS bf16x8*)(lds + PG8_SB(b, h) + boff + n * 2048 + k * 1024); } while (0)
; #define PG8_MMA(ai, bj, At, Bt) do { __builtin_amdgcn_s_setprio(1); _Pragma("unroll") for (int m = 0; m < 4; ++m) _Pragma("unroll") for (int n = 0; n < 2; ++n) _Pragma("unroll") for (int k = 0; k < 2; ++k) \
;         acc[ai][bj][m][n] = __builtin_amdgcn_mfma_f32_16x16x32_bf16(Bt[n][k], At[m][k], acc[ai][bj][m][n], 0, 0, 0); __builtin_amdgcn_s_setprio(0); } while (0)
; #define PG8_WAIT_V(n) asm volatile("s_waitcnt vmcnt(" #n ")" ::: "memory")
; #define PG8_WAIT_L(n) asm volatile("s_waitcnt lgkmcnt(" #n ")" ::: "memory")
; #define PG8_BAR __builtin_amdgcn_s_barrier()
; #define PG8_SCHED __builtin_amdgcn_sched_barrier(0)
; template <class Epi, class Sched, bool ALIGN_EPI>
; __device__ __forceinline__ void gemm_phase(LAS unsigned char* lds, const Gemm g, const Sched& S, const Epi& E, int wave_id) {
;     ...
;             PG8_LDB(B0, 0, 0); PG8_LDB(B1, 0, 1); PG8_SCHED; PG8_LDA(At, 0, 0); PG8_STAGE(PG8_SA(1, 1), a1 + hsA, voffA);
;             PG8_WAIT_V(8); PG8_WAIT_L(0); PG8_BAR; PG8_MMA(0, 0, At, B0); PG8_MMA(0, 1, At, B1); PG8_BAR; PG8_SCHED;
;             PG8_LDA(At, 0, 1); PG8_STAGE(PG8_SB(0, 0), b2, voffB); PG8_STAGE(PG8_SB(0, 1), b2 + hsB, voffB); PG8_STAGE(PG8_SA(0, 0), a2, voffA);
;             PG8_WAIT_V(8); PG8_WAIT_L(0); PG8_BAR; PG8_MMA(1, 0, At, B0); PG8_MMA(1, 1, At, B1); PG8_BAR; PG8_SCHED;
.LBB0_1645:
	s_add_u32 s20, s18, 0x100
	s_addc_u32 s21, s19, 0
	s_cmp_eq_u32 s55, 2
	s_cselect_b32 s25, s15, s21
	s_cselect_b32 s24, s14, s20
	s_cselect_b32 s23, s17, s54
	s_cselect_b32 s22, s16, s53
	v_lshl_add_u64 v[192:193], s[18:19], 0, v[170:171]
	s_add_i32 m0, s31, 0xc400
	s_nop 0
	global_load_lds_dwordx4 v[192:193], off
	v_lshl_add_u64 v[192:193], s[18:19], 0, v[168:169]
	s_add_i32 m0, s31, 0xe400
	s_nop 0
	global_load_lds_dwordx4 v[192:193], off
	v_add_u32_e32 v134, 0x10400, v195
	v_add_u32_e32 v158, 0x14400, v195
	ds_read_b128 v[114:117], v134
	ds_read_b128 v[118:121], v134 offset:1024
	ds_read_b128 v[130:133], v134 offset:2048
	ds_read_b128 v[134:137], v134 offset:3072
	ds_read_b128 v[146:149], v158
	ds_read_b128 v[150:153], v158 offset:1024
	ds_read_b128 v[154:157], v158 offset:2048
	ds_read_b128 v[158:161], v158 offset:3072
	ds_read_b128 v[172:175], v194 offset:1024
	ds_read_b128 v[176:179], v194 offset:2048
	ds_read_b128 v[180:183], v194 offset:3072
	ds_read_b128 v[184:187], v194 offset:4096
	ds_read_b128 v[188:191], v194 offset:5120
	ds_read_b128 v[196:199], v194 offset:6144
	ds_read_b128 v[200:203], v194 offset:7168
	ds_read_b128 v[204:207], v194 offset:8192
	s_waitcnt vmcnt(8)
	s_waitcnt lgkmcnt(0)
	s_barrier
	s_setprio 1
	s_waitcnt lgkmcnt(0)
	v_mfma_f32_16x16x32_bf16 v[142:145], v[114:117], v[172:175], v[142:145]
	v_mfma_f32_16x16x32_bf16 v[138:141], v[130:133], v[172:175], v[138:141]
	v_mfma_f32_16x16x32_bf16 v[126:129], v[114:117], v[180:183], v[126:129]
	v_mfma_f32_16x16x32_bf16 v[122:125], v[130:133], v[180:183], v[122:125]
	v_mfma_f32_16x16x32_bf16 v[110:113], v[114:117], v[188:191], v[110:113]
	v_mfma_f32_16x16x32_bf16 v[106:109], v[130:133], v[188:191], v[106:109]
	v_mfma_f32_16x16x32_bf16 v[102:105], v[114:117], v[200:203], v[102:105]
	v_mfma_f32_16x16x32_bf16 v[98:101], v[130:133], v[200:203], v[98:101]
	v_mfma_f32_16x16x32_bf16 v[142:145], v[118:121], v[176:179], v[142:145]
	v_mfma_f32_16x16x32_bf16 v[138:141], v[134:137], v[176:179], v[138:141]
	v_mfma_f32_16x16x32_bf16 v[126:129], v[118:121], v[184:187], v[126:129]
	v_mfma_f32_16x16x32_bf16 v[122:125], v[134:137], v[184:187], v[122:125]
	v_mfma_f32_16x16x32_bf16 v[110:113], v[118:121], v[196:199], v[110:113]
	v_mfma_f32_16x16x32_bf16 v[106:109], v[134:137], v[196:199], v[106:109]
	v_mfma_f32_16x16x32_bf16 v[102:105], v[118:121], v[204:207], v[102:105]
	v_mfma_f32_16x16x32_bf16 v[98:101], v[134:137], v[204:207], v[98:101]
	s_setprio 0
	s_setprio 1
	v_mfma_f32_16x16x32_bf16 v[62:65], v[146:149], v[172:175], v[62:65]
	v_mfma_f32_16x16x32_bf16 v[58:61], v[154:157], v[172:175], v[58:61]
	v_mfma_f32_16x16x32_bf16 v[54:57], v[146:149], v[180:183], v[54:57]
	v_mfma_f32_16x16x32_bf16 v[50:53], v[154:157], v[180:183], v[50:53]
	v_mfma_f32_16x16x32_bf16 v[46:49], v[146:149], v[188:191], v[46:49]
	v_mfma_f32_16x16x32_bf16 v[42:45], v[154:157], v[188:191], v[42:45]
	v_mfma_f32_16x16x32_bf16 v[38:41], v[146:149], v[200:203], v[38:41]
	v_mfma_f32_16x16x32_bf16 v[34:37], v[154:157], v[200:203], v[34:37]
	v_mfma_f32_16x16x32_bf16 v[62:65], v[150:153], v[176:179], v[62:65]
	v_mfma_f32_16x16x32_bf16 v[58:61], v[158:161], v[176:179], v[58:61]
	v_mfma_f32_16x16x32_bf16 v[54:57], v[150:153], v[184:187], v[54:57]
	v_mfma_f32_16x16x32_bf16 v[50:53], v[158:161], v[184:187], v[50:53]
	v_mfma_f32_16x16x32_bf16 v[46:49], v[150:153], v[196:199], v[46:49]
	v_mfma_f32_16x16x32_bf16 v[42:45], v[158:161], v[196:199], v[42:45]
	v_mfma_f32_16x16x32_bf16 v[38:41], v[150:153], v[204:207], v[38:41]
	v_mfma_f32_16x16x32_bf16 v[34:37], v[158:161], v[204:207], v[34:37]
	s_setprio 0
	s_barrier
	s_mov_b32 m0, s34
	v_lshl_add_u64 v[192:193], s[22:23], 0, v[0:1]
	s_add_u32 s18, s22, 0x18000
	global_load_lds_dwordx4 v[192:193], off
	v_lshl_add_u64 v[208:209], s[22:23], 0, v[162:163]
	s_mov_b32 m0, s35
	s_addc_u32 s19, s23, 0
	global_load_lds_dwordx4 v[208:209], off
	v_lshl_add_u64 v[210:211], s[18:19], 0, v[0:1]
	s_mov_b32 m0, s36
	v_lshl_add_u64 v[212:213], s[24:25], 0, v[164:165]
	global_load_lds_dwordx4 v[210:211], off
	v_lshl_add_u64 v[210:211], s[18:19], 0, v[162:163]
	s_mov_b32 m0, s37
	s_nop 0
	global_load_lds_dwordx4 v[210:211], off
	v_lshl_add_u64 v[210:211], s[24:25], 0, v[166:167]
	s_mov_b32 m0, s38
	s_nop 0
	global_load_lds_dwordx4 v[210:211], off
	s_mov_b32 m0, s39
	s_nop 0
	global_load_lds_dwordx4 v[212:213], off
	ds_read_b128 v[172:175], v194 offset:17408
	ds_read_b128 v[176:179], v194 offset:18432
	ds_read_b128 v[180:183], v194 offset:19456
	ds_read_b128 v[184:187], v194 offset:20480
	ds_read_b128 v[188:191], v194 offset:21504
	ds_read_b128 v[196:199], v194 offset:22528
	ds_read_b128 v[200:203], v194 offset:23552
	ds_read_b128 v[204:207], v194 offset:24576
	s_waitcnt vmcnt(8)
	s_waitcnt lgkmcnt(0)
	s_barrier
; #define PG8_STAGE(bufoff, gbase, voff) do { _Pragma("unroll") for (int _i = 0; _i < 2; ++_i) \
;         __builtin_amdgcn_global_load_lds((const GAS unsigned*)((const GAS char*)(gbase) + (voff)[_i]), (LAS unsigned*)(lds + (bufoff) + ldsw + _i * 8192), 16, 0, 0); } while (0)
; #define PG8_LDA(dst, b, h) do { _Pragma("unroll") for (int m = 0; m < 4; ++m) _Pragma("unroll") for (int k = 0; k < 2; ++k) dst[m][k] = *(const LAS bf16x8*)(lds + PG8_SA(b, h) + aoff + m * 2048 + k * 1024); } while (0)
; #define PG8_LDB(dst, b, h) do { _Pragma("unroll") for (int n = 0; n < 2; ++n) _Pragma("unroll") for (int k = 0; k < 2; ++k) dst[n][k] = *(const LAS bf16x8*)(lds + PG8_SB(b, h) + boff + n * 2048 + k * 1024); } while (0)
; #define PG8_MMA(ai, bj, At, Bt) do { __builtin_amdgcn_s_setprio(1); _Pragma("unroll") for (int m = 0; m < 4; ++m) _Pragma("unroll") for (int n = 0; n < 2; ++n) _Pragma("unroll") for (int k = 0; k < 2; ++k) \
;         acc[ai][bj][m][n] = __builtin_amdgcn_mfma_f32_16x16x32_bf16(Bt[n][k], At[m][k], acc[ai][bj][m][n], 0, 0, 0); __builtin_amdgcn_s_setprio(0); } while (0)
; #define PG8_WAIT_V(n) asm volatile("s_waitcnt vmcnt(" #n ")" ::: "memory")
; #define PG8_WAIT_L(n) asm volatile("s_waitcnt lgkmcnt(" #n ")" ::: "memory")
; #define PG8_BAR __builtin_amdgcn_s_barrier()
; #define PG8_SCHED __builtin_amdgcn_sched_barrier(0)
; template <class Epi, class Sched, bool ALIGN_EPI>
; __device__ __forceinline__ void gemm_phase(LAS unsigned char* lds, const Gemm g, const Sched& S, const Epi& E, int wave_id) {
;     ...
;             PG8_WAIT_V(8); PG8_WAIT_L(0); PG8_BAR; PG8_MMA(1, 0, At, B0); PG8_MMA(1, 1, At, B1); PG8_BAR; PG8_SCHED;
;             PG8_LDB(B0, 1, 0); PG8_LDB(B1, 1, 1); PG8_SCHED; PG8_LDA(At, 1, 0); PG8_STAGE(PG8_SA(0, 1), a2 + hsA, voffA);
;             PG8_WAIT_V(8); PG8_WAIT_L(0); PG8_BAR; PG8_MMA(0, 0, At, B0); PG8_MMA(0, 1, At, B1); PG8_BAR; PG8_SCHED;
	s_setprio 1
	s_waitcnt lgkmcnt(0)
	v_mfma_f32_16x16x32_bf16 v[94:97], v[114:117], v[172:175], v[94:97]
	v_mfma_f32_16x16x32_bf16 v[90:93], v[130:133], v[172:175], v[90:93]
	v_mfma_f32_16x16x32_bf16 v[86:89], v[114:117], v[180:183], v[86:89]
	v_mfma_f32_16x16x32_bf16 v[82:85], v[130:133], v[180:183], v[82:85]
	v_mfma_f32_16x16x32_bf16 v[78:81], v[114:117], v[188:191], v[78:81]
	v_mfma_f32_16x16x32_bf16 v[74:77], v[130:133], v[188:191], v[74:77]
	v_mfma_f32_16x16x32_bf16 v[70:73], v[114:117], v[200:203], v[70:73]
	v_mfma_f32_16x16x32_bf16 v[66:69], v[130:133], v[200:203], v[66:69]
	v_mfma_f32_16x16x32_bf16 v[94:97], v[118:121], v[176:179], v[94:97]
	v_mfma_f32_16x16x32_bf16 v[90:93], v[134:137], v[176:179], v[90:93]
	v_mfma_f32_16x16x32_bf16 v[86:89], v[118:121], v[184:187], v[86:89]
	v_mfma_f32_16x16x32_bf16 v[82:85], v[134:137], v[184:187], v[82:85]
	v_mfma_f32_16x16x32_bf16 v[78:81], v[118:121], v[196:199], v[78:81]
	v_mfma_f32_16x16x32_bf16 v[74:77], v[134:137], v[196:199], v[74:77]
	v_mfma_f32_16x16x32_bf16 v[70:73], v[118:121], v[204:207], v[70:73]
	v_mfma_f32_16x16x32_bf16 v[66:69], v[134:137], v[204:207], v[66:69]
	s_setprio 0
	s_setprio 1
	v_mfma_f32_16x16x32_bf16 v[30:33], v[146:149], v[172:175], v[30:33]
	v_mfma_f32_16x16x32_bf16 v[26:29], v[154:157], v[172:175], v[26:29]
	v_mfma_f32_16x16x32_bf16 v[22:25], v[146:149], v[180:183], v[22:25]
	v_mfma_f32_16x16x32_bf16 v[18:21], v[154:157], v[180:183], v[18:21]
	v_mfma_f32_16x16x32_bf16 v[14:17], v[146:149], v[188:191], v[14:17]
	v_mfma_f32_16x16x32_bf16 v[10:13], v[154:157], v[188:191], v[10:13]
	v_mfma_f32_16x16x32_bf16 v[6:9], v[146:149], v[200:203], v[6:9]
	v_mfma_f32_16x16x32_bf16 v[2:5], v[154:157], v[200:203], v[2:5]
	v_mfma_f32_16x16x32_bf16 v[30:33], v[150:153], v[176:179], v[30:33]
	v_mfma_f32_16x16x32_bf16 v[26:29], v[158:161], v[176:179], v[26:29]
	v_mfma_f32_16x16x32_bf16 v[22:25], v[150:153], v[184:187], v[22:25]
	v_mfma_f32_16x16x32_bf16 v[18:21], v[158:161], v[184:187], v[18:21]
	v_mfma_f32_16x16x32_bf16 v[14:17], v[150:153], v[196:199], v[14:17]
	v_mfma_f32_16x16x32_bf16 v[10:13], v[158:161], v[196:199], v[10:13]
	v_mfma_f32_16x16x32_bf16 v[6:9], v[150:153], v[204:207], v[6:9]
	v_mfma_f32_16x16x32_bf16 v[2:5], v[158:161], v[204:207], v[2:5]
	s_setprio 0
	s_barrier
	s_add_u32 s18, s24, 0x18000
	s_addc_u32 s19, s25, 0
	s_mov_b32 m0, s40
	v_lshl_add_u64 v[214:215], s[18:19], 0, v[166:167]
	global_load_lds_dwordx4 v[214:215], off
	v_lshl_add_u64 v[214:215], s[18:19], 0, v[164:165]
	s_mov_b32 m0, s41
	s_nop 0
	global_load_lds_dwordx4 v[214:215], off
	v_add_u32_e32 v134, 0x18400, v195
	v_add_u32_e32 v158, 0x1c400, v195
	ds_read_b128 v[114:117], v134
	ds_read_b128 v[118:121], v134 offset:1024
	ds_read_b128 v[130:133], v134 offset:2048
	ds_read_b128 v[134:137], v134 offset:3072
	ds_read_b128 v[146:149], v158
	ds_read_b128 v[150:153], v158 offset:1024
	ds_read_b128 v[154:157], v158 offset:2048
	ds_read_b128 v[158:161], v158 offset:3072
	ds_read_b128 v[172:175], v194 offset:33792
	ds_read_b128 v[176:179], v194 offset:34816
	ds_read_b128 v[180:183], v194 offset:35840
	ds_read_b128 v[184:187], v194 offset:36864
	ds_read_b128 v[188:191], v194 offset:37888
	ds_read_b128 v[196:199], v194 offset:38912
	ds_read_b128 v[200:203], v194 offset:39936
	ds_read_b128 v[204:207], v194 offset:40960
	s_waitcnt vmcnt(8)
	s_waitcnt lgkmcnt(0)
	s_barrier
	s_setprio 1
	s_waitcnt lgkmcnt(0)
	v_mfma_f32_16x16x32_bf16 v[142:145], v[114:117], v[172:175], v[142:145]
	v_mfma_f32_16x16x32_bf16 v[138:141], v[130:133], v[172:175], v[138:141]
	v_mfma_f32_16x16x32_bf16 v[126:129], v[114:117], v[180:183], v[126:129]
	v_mfma_f32_16x16x32_bf16 v[122:125], v[130:133], v[180:183], v[122:125]
	v_mfma_f32_16x16x32_bf16 v[110:113], v[114:117], v[188:191], v[110:113]
	v_mfma_f32_16x16x32_bf16 v[106:109], v[130:133], v[188:191], v[106:109]
	v_mfma_f32_16x16x32_bf16 v[102:105], v[114:117], v[200:203], v[102:105]
	v_mfma_f32_16x16x32_bf16 v[98:101], v[130:133], v[200:203], v[98:101]
	v_mfma_f32_16x16x32_bf16 v[142:145], v[118:121], v[176:179], v[142:145]
	v_mfma_f32_16x16x32_bf16 v[138:141], v[134:137], v[176:179], v[138:141]
	v_mfma_f32_16x16x32_bf16 v[126:129], v[118:121], v[184:187], v[126:129]
	v_mfma_f32_16x16x32_bf16 v[122:125], v[134:137], v[184:187], v[122:125]
	v_mfma_f32_16x16x32_bf16 v[110:113], v[118:121], v[196:199], v[110:113]
	v_mfma_f32_16x16x32_bf16 v[106:109], v[134:137], v[196:199], v[106:109]
	v_mfma_f32_16x16x32_bf16 v[102:105], v[118:121], v[204:207], v[102:105]
	v_mfma_f32_16x16x32_bf16 v[98:101], v[134:137], v[204:207], v[98:101]
	s_setprio 0
	s_setprio 1
	v_mfma_f32_16x16x32_bf16 v[62:65], v[146:149], v[172:175], v[62:65]
	v_mfma_f32_16x16x32_bf16 v[58:61], v[154:157], v[172:175], v[58:61]
	v_mfma_f32_16x16x32_bf16 v[54:57], v[146:149], v[180:183], v[54:57]
	v_mfma_f32_16x16x32_bf16 v[50:53], v[154:157], v[180:183], v[50:53]
	v_mfma_f32_16x16x32_bf16 v[46:49], v[146:149], v[188:191], v[46:49]
	v_mfma_f32_16x16x32_bf16 v[42:45], v[154:157], v[188:191], v[42:45]
	v_mfma_f32_16x16x32_bf16 v[38:41], v[146:149], v[200:203], v[38:41]
	v_mfma_f32_16x16x32_bf16 v[34:37], v[154:157], v[200:203], v[34:37]
	v_mfma_f32_16x16x32_bf16 v[62:65], v[150:153], v[176:179], v[62:65]
	v_mfma_f32_16x16x32_bf16 v[58:61], v[158:161], v[176:179], v[58:61]
	v_mfma_f32_16x16x32_bf16 v[54:57], v[150:153], v[184:187], v[54:57]
	v_mfma_f32_16x16x32_bf16 v[50:53], v[158:161], v[184:187], v[50:53]
	v_mfma_f32_16x16x32_bf16 v[46:49], v[150:153], v[196:199], v[46:49]
	v_mfma_f32_16x16x32_bf16 v[42:45], v[158:161], v[196:199], v[42:45]
	v_mfma_f32_16x16x32_bf16 v[38:41], v[150:153], v[204:207], v[38:41]
	v_mfma_f32_16x16x32_bf16 v[34:37], v[158:161], v[204:207], v[34:37]
	s_setprio 0
	s_barrier
; #define PG8_STAGE(bufoff, gbase, voff) do { _Pragma("unroll") for (int _i = 0; _i < 2; ++_i) \
;         __builtin_amdgcn_global_load_lds((const GAS unsigned*)((const GAS char*)(gbase) + (voff)[_i]), (LAS unsigned*)(lds + (bufoff) + ldsw + _i * 8192), 16, 0, 0); } while (0)
; #define PG8_LDA(dst, b, h) do { _Pragma("unroll") for (int m = 0; m < 4; ++m) _Pragma("unroll") for (int k = 0; k < 2; ++k) dst[m][k] = *(const LAS bf16x8*)(lds + PG8_SA(b, h) + aoff + m * 2048 + k * 1024); } while (0)
; #define PG8_MMA(ai, bj, At, Bt) do { __builtin_amdgcn_s_setprio(1); _Pragma("unroll") for (int m = 0; m < 4; ++m) _Pragma("unroll") for (int n = 0; n < 2; ++n) _Pragma("unroll") for (int k = 0; k < 2; ++k) \
;         acc[ai][bj][m][n] = __builtin_amdgcn_mfma_f32_16x16x32_bf16(Bt[n][k], At[m][k], acc[ai][bj][m][n], 0, 0, 0); __builtin_amdgcn_s_setprio(0); } while (0)
; #define PG8_WAIT_V(n) asm volatile("s_waitcnt vmcnt(" #n ")" ::: "memory")
; #define PG8_WAIT_L(n) asm volatile("s_waitcnt lgkmcnt(" #n ")" ::: "memory")
; #define PG8_BAR __builtin_amdgcn_s_barrier()
; #define PG8_SCHED __builtin_amdgcn_sched_barrier(0)
; template <class Epi, class Sched, bool ALIGN_EPI>
; __device__ __forceinline__ void gemm_phase(LAS unsigned char* lds, const Gemm g, const Sched& S, const Epi& E, int wave_id) {
;     ...
;             PG8_LDA(At, 1, 1); PG8_STAGE(PG8_SB(1, 0), b3, voffB); PG8_STAGE(PG8_SB(1, 1), b3 + hsB, voffB); PG8_STAGE(PG8_SA(1, 0), a3, voffA);
;             PG8_WAIT_V(8); PG8_WAIT_L(0); PG8_BAR; PG8_MMA(1, 0, At, B0); PG8_MMA(1, 1, At, B1); PG8_BAR; PG8_SCHED;
;         }
	s_mov_b32 m0, s44
	v_lshl_add_u64 v[192:193], v[192:193], 0, s[92:93]
	s_add_u32 s18, s22, 0x18080
	global_load_lds_dwordx4 v[192:193], off
	v_lshl_add_u64 v[192:193], v[208:209], 0, s[92:93]
	s_mov_b32 m0, s45
	s_addc_u32 s19, s23, 0
	global_load_lds_dwordx4 v[192:193], off
	v_lshl_add_u64 v[192:193], s[18:19], 0, v[0:1]
	s_mov_b32 m0, s48
	s_nop 0
	global_load_lds_dwordx4 v[192:193], off
	v_lshl_add_u64 v[192:193], s[18:19], 0, v[162:163]
	s_mov_b32 m0, s49
	s_nop 0
	global_load_lds_dwordx4 v[192:193], off
	v_lshl_add_u64 v[192:193], v[210:211], 0, s[92:93]
	s_mov_b32 m0, s46
	s_nop 0
	global_load_lds_dwordx4 v[192:193], off
	v_lshl_add_u64 v[192:193], v[212:213], 0, s[92:93]
	s_mov_b32 m0, s47
	s_nop 0
	global_load_lds_dwordx4 v[192:193], off
	ds_read_b128 v[172:175], v194 offset:50176
	ds_read_b128 v[176:179], v194 offset:51200
	ds_read_b128 v[180:183], v194 offset:52224
	ds_read_b128 v[184:187], v194 offset:53248
	ds_read_b128 v[188:191], v194 offset:54272
	ds_read_b128 v[196:199], v194 offset:55296
	ds_read_b128 v[200:203], v194 offset:56320
	ds_read_b128 v[204:207], v194 offset:57344
	s_waitcnt vmcnt(8)
	s_waitcnt lgkmcnt(0)
	s_barrier
	s_setprio 1
	s_waitcnt lgkmcnt(0)
	v_mfma_f32_16x16x32_bf16 v[94:97], v[114:117], v[172:175], v[94:97]
	v_mfma_f32_16x16x32_bf16 v[90:93], v[130:133], v[172:175], v[90:93]
	v_mfma_f32_16x16x32_bf16 v[86:89], v[114:117], v[180:183], v[86:89]
	v_mfma_f32_16x16x32_bf16 v[82:85], v[130:133], v[180:183], v[82:85]
	v_mfma_f32_16x16x32_bf16 v[78:81], v[114:117], v[188:191], v[78:81]
	v_mfma_f32_16x16x32_bf16 v[74:77], v[130:133], v[188:191], v[74:77]
	v_mfma_f32_16x16x32_bf16 v[70:73], v[114:117], v[200:203], v[70:73]
	v_mfma_f32_16x16x32_bf16 v[66:69], v[130:133], v[200:203], v[66:69]
	v_mfma_f32_16x16x32_bf16 v[94:97], v[118:121], v[176:179], v[94:97]
	v_mfma_f32_16x16x32_bf16 v[90:93], v[134:137], v[176:179], v[90:93]
	v_mfma_f32_16x16x32_bf16 v[86:89], v[118:121], v[184:187], v[86:89]
	v_mfma_f32_16x16x32_bf16 v[82:85], v[134:137], v[184:187], v[82:85]
	v_mfma_f32_16x16x32_bf16 v[78:81], v[118:121], v[196:199], v[78:81]
	v_mfma_f32_16x16x32_bf16 v[74:77], v[134:137], v[196:199], v[74:77]
	v_mfma_f32_16x16x32_bf16 v[70:73], v[118:121], v[204:207], v[70:73]
	v_mfma_f32_16x16x32_bf16 v[66:69], v[134:137], v[204:207], v[66:69]
	s_setprio 0
	s_setprio 1
	v_mfma_f32_16x16x32_bf16 v[30:33], v[146:149], v[172:175], v[30:33]
	v_mfma_f32_16x16x32_bf16 v[26:29], v[154:157], v[172:175], v[26:29]
	v_mfma_f32_16x16x32_bf16 v[22:25], v[146:149], v[180:183], v[22:25]
	v_mfma_f32_16x16x32_bf16 v[18:21], v[154:157], v[180:183], v[18:21]
	v_mfma_f32_16x16x32_bf16 v[14:17], v[146:149], v[188:191], v[14:17]
	v_mfma_f32_16x16x32_bf16 v[10:13], v[154:157], v[188:191], v[10:13]
	v_mfma_f32_16x16x32_bf16 v[6:9], v[146:149], v[200:203], v[6:9]
	v_mfma_f32_16x16x32_bf16 v[2:5], v[154:157], v[200:203], v[2:5]
	v_mfma_f32_16x16x32_bf16 v[30:33], v[150:153], v[176:179], v[30:33]
	v_mfma_f32_16x16x32_bf16 v[26:29], v[158:161], v[176:179], v[26:29]
	v_mfma_f32_16x16x32_bf16 v[22:25], v[150:153], v[184:187], v[22:25]
	v_mfma_f32_16x16x32_bf16 v[18:21], v[158:161], v[184:187], v[18:21]
	v_mfma_f32_16x16x32_bf16 v[14:17], v[150:153], v[196:199], v[14:17]
	v_mfma_f32_16x16x32_bf16 v[10:13], v[158:161], v[196:199], v[10:13]
	v_mfma_f32_16x16x32_bf16 v[6:9], v[150:153], v[204:207], v[6:9]
	v_mfma_f32_16x16x32_bf16 v[2:5], v[158:161], v[204:207], v[2:5]
	s_setprio 0
	s_barrier
	s_add_i32 s55, s55, 2
	s_add_u32 s53, s53, 0x100
	s_addc_u32 s54, s54, 0
	s_cmp_gt_u32 s55, 3
	s_mov_b64 s[18:19], s[20:21]
	s_cbranch_scc0 .LBB0_1645
	s_and_b64 vcc, exec, s[12:13]
	s_cbranch_vccz .LBB0_1648
	s_barrier

; #define PG8_STAGE(bufoff, gbase, voff) do { _Pragma("unroll") for (int _i = 0; _i < 2; ++_i) \
;         __builtin_amdgcn_global_load_lds((const GAS unsigned*)((const GAS char*)(gbase) + (voff)[_i]), (LAS unsigned*)(lds + (bufoff) + ldsw + _i * 8192), 16, 0, 0); } while (0)
; #define PG8_LDA(dst, b, h) do { _Pragma("unroll") for (int m = 0; m < 4; ++m) _Pragma("unroll") for (int k = 0; k < 2; ++k) dst[m][k] = *(const LAS bf16x8*)(lds + PG8_SA(b, h) + aoff + m * 2048 + k * 1024); } while (0)
; #define PG8_LDB(dst, b, h) do { _Pragma("unroll") for (int n = 0; n < 2; ++n) _Pragma("unroll") for (int k = 0; k < 2; ++k) dst[n][k] = *(const LAS bf16x8*)(lds + PG8_SB(b, h) + boff + n * 2048 + k * 1024); } while (0)
; #define PG8_MMA(ai, bj, At, Bt) do { __builtin_amdgcn_s_setprio(1); _Pragma("unroll") for (int m = 0; m < 4; ++m) _Pragma("unroll") for (int n = 0; n < 2; ++n) _Pragma("unroll") for (int k = 0; k < 2; ++k) \
;         acc[ai][bj][m][n] = __builtin_amdgcn_mfma_f32_16x16x32_bf16(Bt[n][k], At[m][k], acc[ai][bj][m][n], 0, 0, 0); __builtin_amdgcn_s_setprio(0); } while (0)
; #define PG8_WAIT_V(n) asm volatile("s_waitcnt vmcnt(" #n ")" ::: "memory")
; #define PG8_WAIT_L(n) asm volatile("s_waitcnt lgkmcnt(" #n ")" ::: "memory")
; #define PG8_BAR __builtin_amdgcn_s_barrier()
; #define PG8_SCHED __builtin_amdgcn_sched_barrier(0)
; template <class Epi, class Sched, bool ALIGN_EPI>
; __device__ __forceinline__ void gemm_phase(LAS unsigned char* lds, const Gemm g, const Sched& S, const Epi& E, int wave_id) {
;     ...
;             PG8_LDB(B0, 0, 0); PG8_LDB(B1, 0, 1); PG8_SCHED; PG8_LDA(At, 0, 0); PG8_STAGE(PG8_SA(1, 1), a1 + hsA, voffA);
;             PG8_WAIT_V(8); PG8_WAIT_L(0); PG8_BAR; PG8_MMA(0, 0, At, B0); PG8_MMA(0, 1, At, B1); PG8_BAR; PG8_SCHED;
;             PG8_LDA(At, 0, 1); PG8_STAGE(PG8_SB(0, 0), b2, voffB); PG8_STAGE(PG8_SB(0, 1), b2 + hsB, voffB); PG8_STAGE(PG8_SA(0, 0), a2, voffA);
;             PG8_WAIT_V(8); PG8_WAIT_L(0); PG8_BAR; PG8_MMA(1, 0, At, B0); PG8_MMA(1, 1, At, B1); PG8_BAR; PG8_SCHED;
.LBB0_1837:
	s_add_u32 s42, s40, 0xfffc0080
	s_addc_u32 s43, s41, -1
	s_cmp_eq_u32 s67, 12
	s_cselect_b32 s45, s5, s43
	s_cselect_b32 s44, s25, s42
	s_cselect_b32 s43, s27, s66
	s_cselect_b32 s42, s37, s39
	v_lshl_add_u64 v[196:197], s[40:41], 0, v[182:183]
	s_add_i32 m0, s1, 0xc400
	s_nop 0
	global_load_lds_dwordx4 v[196:197], off
	v_lshl_add_u64 v[196:197], s[40:41], 0, v[180:181]
	s_add_i32 m0, s1, 0xe400
	s_nop 0
	global_load_lds_dwordx4 v[196:197], off
	v_add_u32_e32 v142, 0x10400, v199
	v_add_u32_e32 v158, 0x14400, v199
	ds_read_b128 v[130:133], v142
	ds_read_b128 v[134:137], v142 offset:1024
	ds_read_b128 v[138:141], v142 offset:2048
	ds_read_b128 v[142:145], v142 offset:3072
	ds_read_b128 v[146:149], v158
	ds_read_b128 v[150:153], v158 offset:1024
	ds_read_b128 v[154:157], v158 offset:2048
	ds_read_b128 v[158:161], v158 offset:3072
	ds_read_b128 v[162:165], v198 offset:1024
	ds_read_b128 v[166:169], v198 offset:2048
	ds_read_b128 v[170:173], v198 offset:3072
	ds_read_b128 v[184:187], v198 offset:4096
	ds_read_b128 v[188:191], v198 offset:5120
	ds_read_b128 v[192:195], v198 offset:6144
	ds_read_b128 v[200:203], v198 offset:7168
	ds_read_b128 v[204:207], v198 offset:8192
	s_waitcnt vmcnt(8)
	s_waitcnt lgkmcnt(0)
	s_barrier
	s_setprio 1
	s_waitcnt lgkmcnt(0)
	v_mfma_f32_16x16x32_bf16 v[126:129], v[130:133], v[162:165], v[126:129]
	v_mfma_f32_16x16x32_bf16 v[122:125], v[138:141], v[162:165], v[122:125]
	v_mfma_f32_16x16x32_bf16 v[114:117], v[130:133], v[170:173], v[114:117]
	v_mfma_f32_16x16x32_bf16 v[106:109], v[138:141], v[170:173], v[106:109]
	v_mfma_f32_16x16x32_bf16 v[98:101], v[130:133], v[188:191], v[98:101]
	v_mfma_f32_16x16x32_bf16 v[90:93], v[138:141], v[188:191], v[90:93]
	v_mfma_f32_16x16x32_bf16 v[82:85], v[130:133], v[200:203], v[82:85]
	v_mfma_f32_16x16x32_bf16 v[74:77], v[138:141], v[200:203], v[74:77]
	v_mfma_f32_16x16x32_bf16 v[126:129], v[134:137], v[166:169], v[126:129]
	v_mfma_f32_16x16x32_bf16 v[122:125], v[142:145], v[166:169], v[122:125]
	v_mfma_f32_16x16x32_bf16 v[114:117], v[134:137], v[184:187], v[114:117]
	v_mfma_f32_16x16x32_bf16 v[106:109], v[142:145], v[184:187], v[106:109]
	v_mfma_f32_16x16x32_bf16 v[98:101], v[134:137], v[192:195], v[98:101]
	v_mfma_f32_16x16x32_bf16 v[90:93], v[142:145], v[192:195], v[90:93]
	v_mfma_f32_16x16x32_bf16 v[82:85], v[134:137], v[204:207], v[82:85]
	v_mfma_f32_16x16x32_bf16 v[74:77], v[142:145], v[204:207], v[74:77]
	s_setprio 0
	s_setprio 1
	v_mfma_f32_16x16x32_bf16 v[118:121], v[146:149], v[162:165], v[118:121]
	v_mfma_f32_16x16x32_bf16 v[110:113], v[154:157], v[162:165], v[110:113]
	v_mfma_f32_16x16x32_bf16 v[102:105], v[146:149], v[170:173], v[102:105]
	v_mfma_f32_16x16x32_bf16 v[94:97], v[154:157], v[170:173], v[94:97]
	v_mfma_f32_16x16x32_bf16 v[86:89], v[146:149], v[188:191], v[86:89]
	v_mfma_f32_16x16x32_bf16 v[78:81], v[154:157], v[188:191], v[78:81]
	v_mfma_f32_16x16x32_bf16 v[70:73], v[146:149], v[200:203], v[70:73]
	v_mfma_f32_16x16x32_bf16 v[66:69], v[154:157], v[200:203], v[66:69]
	v_mfma_f32_16x16x32_bf16 v[118:121], v[150:153], v[166:169], v[118:121]
	v_mfma_f32_16x16x32_bf16 v[110:113], v[158:161], v[166:169], v[110:113]
	v_mfma_f32_16x16x32_bf16 v[102:105], v[150:153], v[184:187], v[102:105]
	v_mfma_f32_16x16x32_bf16 v[94:97], v[158:161], v[184:187], v[94:97]
	v_mfma_f32_16x16x32_bf16 v[86:89], v[150:153], v[192:195], v[86:89]
	v_mfma_f32_16x16x32_bf16 v[78:81], v[158:161], v[192:195], v[78:81]
	v_mfma_f32_16x16x32_bf16 v[70:73], v[150:153], v[204:207], v[70:73]
	v_mfma_f32_16x16x32_bf16 v[66:69], v[158:161], v[204:207], v[66:69]
	s_setprio 0
	s_barrier
	s_mov_b32 m0, s48
	v_lshl_add_u64 v[196:197], s[42:43], 0, v[0:1]
	s_add_u32 s68, s42, 0x40000
	global_load_lds_dwordx4 v[196:197], off
	v_lshl_add_u64 v[208:209], s[42:43], 0, v[178:179]
	s_mov_b32 m0, s49
	s_addc_u32 s69, s43, 0
	global_load_lds_dwordx4 v[208:209], off
	v_lshl_add_u64 v[210:211], s[68:69], 0, v[0:1]
	s_mov_b32 m0, s50
	v_lshl_add_u64 v[212:213], s[44:45], 0, v[176:177]
	global_load_lds_dwordx4 v[210:211], off
	v_lshl_add_u64 v[210:211], s[68:69], 0, v[178:179]
	s_mov_b32 m0, s51
	s_nop 0
	global_load_lds_dwordx4 v[210:211], off
	v_lshl_add_u64 v[210:211], s[44:45], 0, v[174:175]
	s_mov_b32 m0, s52
	s_nop 0
	global_load_lds_dwordx4 v[210:211], off
	s_mov_b32 m0, s53
	s_nop 0
	global_load_lds_dwordx4 v[212:213], off
	ds_read_b128 v[162:165], v198 offset:17408
	ds_read_b128 v[166:169], v198 offset:18432
	ds_read_b128 v[170:173], v198 offset:19456
	ds_read_b128 v[184:187], v198 offset:20480
	ds_read_b128 v[188:191], v198 offset:21504
	ds_read_b128 v[192:195], v198 offset:22528
	ds_read_b128 v[200:203], v198 offset:23552
	ds_read_b128 v[204:207], v198 offset:24576
	s_waitcnt vmcnt(8)
	s_waitcnt lgkmcnt(0)
	s_barrier
; #define PG8_STAGE(bufoff, gbase, voff) do { _Pragma("unroll") for (int _i = 0; _i < 2; ++_i) \
;         __builtin_amdgcn_global_load_lds((const GAS unsigned*)((const GAS char*)(gbase) + (voff)[_i]), (LAS unsigned*)(lds + (bufoff) + ldsw + _i * 8192), 16, 0, 0); } while (0)
; #define PG8_LDA(dst, b, h) do { _Pragma("unroll") for (int m = 0; m < 4; ++m) _Pragma("unroll") for (int k = 0; k < 2; ++k) dst[m][k] = *(const LAS bf16x8*)(lds + PG8_SA(b, h) + aoff + m * 2048 + k * 1024); } while (0)
; #define PG8_LDB(dst, b, h) do { _Pragma("unroll") for (int n = 0; n < 2; ++n) _Pragma("unroll") for (int k = 0; k < 2; ++k) dst[n][k] = *(const LAS bf16x8*)(lds + PG8_SB(b, h) + boff + n * 2048 + k * 1024); } while (0)
; #define PG8_MMA(ai, bj, At, Bt) do { __builtin_amdgcn_s_setprio(1); _Pragma("unroll") for (int m = 0; m < 4; ++m) _Pragma("unroll") for (int n = 0; n < 2; ++n) _Pragma("unroll") for (int k = 0; k < 2; ++k) \
;         acc[ai][bj][m][n] = __builtin_amdgcn_mfma_f32_16x16x32_bf16(Bt[n][k], At[m][k], acc[ai][bj][m][n], 0, 0, 0); __builtin_amdgcn_s_setprio(0); } while (0)
; #define PG8_WAIT_V(n) asm volatile("s_waitcnt vmcnt(" #n ")" ::: "memory")
; #define PG8_WAIT_L(n) asm volatile("s_waitcnt lgkmcnt(" #n ")" ::: "memory")
; #define PG8_BAR __builtin_amdgcn_s_barrier()
; #define PG8_SCHED __builtin_amdgcn_sched_barrier(0)
; template <class Epi, class Sched, bool ALIGN_EPI>
; __device__ __forceinline__ void gemm_phase(LAS unsigned char* lds, const Gemm g, const Sched& S, const Epi& E, int wave_id) {
;     ...
;             PG8_WAIT_V(8); PG8_WAIT_L(0); PG8_BAR; PG8_MMA(1, 0, At, B0); PG8_MMA(1, 1, At, B1); PG8_BAR; PG8_SCHED;
;             PG8_LDB(B0, 1, 0); PG8_LDB(B1, 1, 1); PG8_SCHED; PG8_LDA(At, 1, 0); PG8_STAGE(PG8_SA(0, 1), a2 + hsA, voffA);
;             PG8_WAIT_V(8); PG8_WAIT_L(0); PG8_BAR; PG8_MMA(0, 0, At, B0); PG8_MMA(0, 1, At, B1); PG8_BAR; PG8_SCHED;
	s_setprio 1
	s_waitcnt lgkmcnt(0)
	v_mfma_f32_16x16x32_bf16 v[62:65], v[130:133], v[162:165], v[62:65]
	v_mfma_f32_16x16x32_bf16 v[58:61], v[138:141], v[162:165], v[58:61]
	v_mfma_f32_16x16x32_bf16 v[50:53], v[130:133], v[170:173], v[50:53]
	v_mfma_f32_16x16x32_bf16 v[42:45], v[138:141], v[170:173], v[42:45]
	v_mfma_f32_16x16x32_bf16 v[34:37], v[130:133], v[188:191], v[34:37]
	v_mfma_f32_16x16x32_bf16 v[26:29], v[138:141], v[188:191], v[26:29]
	v_mfma_f32_16x16x32_bf16 v[18:21], v[130:133], v[200:203], v[18:21]
	v_mfma_f32_16x16x32_bf16 v[10:13], v[138:141], v[200:203], v[10:13]
	v_mfma_f32_16x16x32_bf16 v[62:65], v[134:137], v[166:169], v[62:65]
	v_mfma_f32_16x16x32_bf16 v[58:61], v[142:145], v[166:169], v[58:61]
	v_mfma_f32_16x16x32_bf16 v[50:53], v[134:137], v[184:187], v[50:53]
	v_mfma_f32_16x16x32_bf16 v[42:45], v[142:145], v[184:187], v[42:45]
	v_mfma_f32_16x16x32_bf16 v[34:37], v[134:137], v[192:195], v[34:37]
	v_mfma_f32_16x16x32_bf16 v[26:29], v[142:145], v[192:195], v[26:29]
	v_mfma_f32_16x16x32_bf16 v[18:21], v[134:137], v[204:207], v[18:21]
	v_mfma_f32_16x16x32_bf16 v[10:13], v[142:145], v[204:207], v[10:13]
	s_setprio 0
	s_setprio 1
	v_mfma_f32_16x16x32_bf16 v[54:57], v[146:149], v[162:165], v[54:57]
	v_mfma_f32_16x16x32_bf16 v[46:49], v[154:157], v[162:165], v[46:49]
	v_mfma_f32_16x16x32_bf16 v[38:41], v[146:149], v[170:173], v[38:41]
	v_mfma_f32_16x16x32_bf16 v[30:33], v[154:157], v[170:173], v[30:33]
	v_mfma_f32_16x16x32_bf16 v[22:25], v[146:149], v[188:191], v[22:25]
	v_mfma_f32_16x16x32_bf16 v[14:17], v[154:157], v[188:191], v[14:17]
	v_mfma_f32_16x16x32_bf16 v[6:9], v[146:149], v[200:203], v[6:9]
	v_mfma_f32_16x16x32_bf16 v[2:5], v[154:157], v[200:203], v[2:5]
	v_mfma_f32_16x16x32_bf16 v[54:57], v[150:153], v[166:169], v[54:57]
	v_mfma_f32_16x16x32_bf16 v[46:49], v[158:161], v[166:169], v[46:49]
	v_mfma_f32_16x16x32_bf16 v[38:41], v[150:153], v[184:187], v[38:41]
	v_mfma_f32_16x16x32_bf16 v[30:33], v[158:161], v[184:187], v[30:33]
	v_mfma_f32_16x16x32_bf16 v[22:25], v[150:153], v[192:195], v[22:25]
	v_mfma_f32_16x16x32_bf16 v[14:17], v[158:161], v[192:195], v[14:17]
	v_mfma_f32_16x16x32_bf16 v[6:9], v[150:153], v[204:207], v[6:9]
	v_mfma_f32_16x16x32_bf16 v[2:5], v[158:161], v[204:207], v[2:5]
	s_setprio 0
	s_barrier
	s_add_u32 s44, s44, 0x40000
	s_addc_u32 s45, s45, 0
	s_mov_b32 m0, s54
	v_lshl_add_u64 v[214:215], s[44:45], 0, v[174:175]
	global_load_lds_dwordx4 v[214:215], off
	v_lshl_add_u64 v[214:215], s[44:45], 0, v[176:177]
	s_mov_b32 m0, s55
	s_nop 0
	global_load_lds_dwordx4 v[214:215], off
	v_add_u32_e32 v142, 0x18400, v199
	v_add_u32_e32 v158, 0x1c400, v199
	ds_read_b128 v[130:133], v142
	ds_read_b128 v[134:137], v142 offset:1024
	ds_read_b128 v[138:141], v142 offset:2048
	ds_read_b128 v[142:145], v142 offset:3072
	ds_read_b128 v[146:149], v158
	ds_read_b128 v[150:153], v158 offset:1024
	ds_read_b128 v[154:157], v158 offset:2048
	ds_read_b128 v[158:161], v158 offset:3072
	ds_read_b128 v[162:165], v198 offset:33792
	ds_read_b128 v[166:169], v198 offset:34816
	ds_read_b128 v[170:173], v198 offset:35840
	ds_read_b128 v[184:187], v198 offset:36864
	ds_read_b128 v[188:191], v198 offset:37888
	ds_read_b128 v[192:195], v198 offset:38912
	ds_read_b128 v[200:203], v198 offset:39936
	ds_read_b128 v[204:207], v198 offset:40960
	s_waitcnt vmcnt(8)
	s_waitcnt lgkmcnt(0)
	s_barrier
	s_setprio 1
	s_waitcnt lgkmcnt(0)
	v_mfma_f32_16x16x32_bf16 v[126:129], v[130:133], v[162:165], v[126:129]
	v_mfma_f32_16x16x32_bf16 v[122:125], v[138:141], v[162:165], v[122:125]
	v_mfma_f32_16x16x32_bf16 v[114:117], v[130:133], v[170:173], v[114:117]
	v_mfma_f32_16x16x32_bf16 v[106:109], v[138:141], v[170:173], v[106:109]
	v_mfma_f32_16x16x32_bf16 v[98:101], v[130:133], v[188:191], v[98:101]
	v_mfma_f32_16x16x32_bf16 v[90:93], v[138:141], v[188:191], v[90:93]
	v_mfma_f32_16x16x32_bf16 v[82:85], v[130:133], v[200:203], v[82:85]
	v_mfma_f32_16x16x32_bf16 v[74:77], v[138:141], v[200:203], v[74:77]
	v_mfma_f32_16x16x32_bf16 v[126:129], v[134:137], v[166:169], v[126:129]
	v_mfma_f32_16x16x32_bf16 v[122:125], v[142:145], v[166:169], v[122:125]
	v_mfma_f32_16x16x32_bf16 v[114:117], v[134:137], v[184:187], v[114:117]
	v_mfma_f32_16x16x32_bf16 v[106:109], v[142:145], v[184:187], v[106:109]
	v_mfma_f32_16x16x32_bf16 v[98:101], v[134:137], v[192:195], v[98:101]
	v_mfma_f32_16x16x32_bf16 v[90:93], v[142:145], v[192:195], v[90:93]
	v_mfma_f32_16x16x32_bf16 v[82:85], v[134:137], v[204:207], v[82:85]
	v_mfma_f32_16x16x32_bf16 v[74:77], v[142:145], v[204:207], v[74:77]
	s_setprio 0
	s_setprio 1
	v_mfma_f32_16x16x32_bf16 v[118:121], v[146:149], v[162:165], v[118:121]
	v_mfma_f32_16x16x32_bf16 v[110:113], v[154:157], v[162:165], v[110:113]
	v_mfma_f32_16x16x32_bf16 v[102:105], v[146:149], v[170:173], v[102:105]
	v_mfma_f32_16x16x32_bf16 v[94:97], v[154:157], v[170:173], v[94:97]
	v_mfma_f32_16x16x32_bf16 v[86:89], v[146:149], v[188:191], v[86:89]
	v_mfma_f32_16x16x32_bf16 v[78:81], v[154:157], v[188:191], v[78:81]
	v_mfma_f32_16x16x32_bf16 v[70:73], v[146:149], v[200:203], v[70:73]
	v_mfma_f32_16x16x32_bf16 v[66:69], v[154:157], v[200:203], v[66:69]
	v_mfma_f32_16x16x32_bf16 v[118:121], v[150:153], v[166:169], v[118:121]
	v_mfma_f32_16x16x32_bf16 v[110:113], v[158:161], v[166:169], v[110:113]
	v_mfma_f32_16x16x32_bf16 v[102:105], v[150:153], v[184:187], v[102:105]
	v_mfma_f32_16x16x32_bf16 v[94:97], v[158:161], v[184:187], v[94:97]
	v_mfma_f32_16x16x32_bf16 v[86:89], v[150:153], v[192:195], v[86:89]
	v_mfma_f32_16x16x32_bf16 v[78:81], v[158:161], v[192:195], v[78:81]
	v_mfma_f32_16x16x32_bf16 v[70:73], v[150:153], v[204:207], v[70:73]
	v_mfma_f32_16x16x32_bf16 v[66:69], v[158:161], v[204:207], v[66:69]
	s_setprio 0
	s_barrier
; #define PG8_STAGE(bufoff, gbase, voff) do { _Pragma("unroll") for (int _i = 0; _i < 2; ++_i) \
;         __builtin_amdgcn_global_load_lds((const GAS unsigned*)((const GAS char*)(gbase) + (voff)[_i]), (LAS unsigned*)(lds + (bufoff) + ldsw + _i * 8192), 16, 0, 0); } while (0)
; #define PG8_LDA(dst, b, h) do { _Pragma("unroll") for (int m = 0; m < 4; ++m) _Pragma("unroll") for (int k = 0; k < 2; ++k) dst[m][k] = *(const LAS bf16x8*)(lds + PG8_SA(b, h) + aoff + m * 2048 + k * 1024); } while (0)
; #define PG8_MMA(ai, bj, At, Bt) do { __builtin_amdgcn_s_setprio(1); _Pragma("unroll") for (int m = 0; m < 4; ++m) _Pragma("unroll") for (int n = 0; n < 2; ++n) _Pragma("unroll") for (int k = 0; k < 2; ++k) \
;         acc[ai][bj][m][n] = __builtin_amdgcn_mfma_f32_16x16x32_bf16(Bt[n][k], At[m][k], acc[ai][bj][m][n], 0, 0, 0); __builtin_amdgcn_s_setprio(0); } while (0)
; #define PG8_WAIT_V(n) asm volatile("s_waitcnt vmcnt(" #n ")" ::: "memory")
; #define PG8_WAIT_L(n) asm volatile("s_waitcnt lgkmcnt(" #n ")" ::: "memory")
; #define PG8_BAR __builtin_amdgcn_s_barrier()
; #define PG8_SCHED __builtin_amdgcn_sched_barrier(0)
; template <class Epi, class Sched, bool ALIGN_EPI>
; __device__ __forceinline__ void gemm_phase(LAS unsigned char* lds, const Gemm g, const Sched& S, const Epi& E, int wave_id) {
;     ...
;             PG8_LDA(At, 1, 1); PG8_STAGE(PG8_SB(1, 0), b3, voffB); PG8_STAGE(PG8_SB(1, 1), b3 + hsB, voffB); PG8_STAGE(PG8_SA(1, 0), a3, voffA);
;             PG8_WAIT_V(8); PG8_WAIT_L(0); PG8_BAR; PG8_MMA(1, 0, At, B0); PG8_MMA(1, 1, At, B1); PG8_BAR; PG8_SCHED;
;         }
	s_mov_b32 m0, s58
	v_lshl_add_u64 v[196:197], v[196:197], 0, s[92:93]
	s_add_u32 s42, s42, 0x40080
	global_load_lds_dwordx4 v[196:197], off
	v_lshl_add_u64 v[196:197], v[208:209], 0, s[92:93]
	s_mov_b32 m0, s59
	s_addc_u32 s43, s43, 0
	global_load_lds_dwordx4 v[196:197], off
	v_lshl_add_u64 v[196:197], s[42:43], 0, v[0:1]
	s_mov_b32 m0, s62
	s_nop 0
	global_load_lds_dwordx4 v[196:197], off
	v_lshl_add_u64 v[196:197], s[42:43], 0, v[178:179]
	s_mov_b32 m0, s63
	s_nop 0
	global_load_lds_dwordx4 v[196:197], off
	v_lshl_add_u64 v[196:197], v[210:211], 0, s[92:93]
	s_mov_b32 m0, s60
	s_nop 0
	global_load_lds_dwordx4 v[196:197], off
	v_lshl_add_u64 v[196:197], v[212:213], 0, s[92:93]
	s_mov_b32 m0, s61
	s_nop 0
	global_load_lds_dwordx4 v[196:197], off
	ds_read_b128 v[162:165], v198 offset:50176
	ds_read_b128 v[166:169], v198 offset:51200
	ds_read_b128 v[170:173], v198 offset:52224
	ds_read_b128 v[184:187], v198 offset:53248
	ds_read_b128 v[188:191], v198 offset:54272
	ds_read_b128 v[192:195], v198 offset:55296
	ds_read_b128 v[200:203], v198 offset:56320
	ds_read_b128 v[204:207], v198 offset:57344
	s_waitcnt vmcnt(8)
	s_waitcnt lgkmcnt(0)
	s_barrier
	s_setprio 1
	s_waitcnt lgkmcnt(0)
	v_mfma_f32_16x16x32_bf16 v[62:65], v[130:133], v[162:165], v[62:65]
	v_mfma_f32_16x16x32_bf16 v[58:61], v[138:141], v[162:165], v[58:61]
	v_mfma_f32_16x16x32_bf16 v[50:53], v[130:133], v[170:173], v[50:53]
	v_mfma_f32_16x16x32_bf16 v[42:45], v[138:141], v[170:173], v[42:45]
	v_mfma_f32_16x16x32_bf16 v[34:37], v[130:133], v[188:191], v[34:37]
	v_mfma_f32_16x16x32_bf16 v[26:29], v[138:141], v[188:191], v[26:29]
	v_mfma_f32_16x16x32_bf16 v[18:21], v[130:133], v[200:203], v[18:21]
	v_mfma_f32_16x16x32_bf16 v[10:13], v[138:141], v[200:203], v[10:13]
	v_mfma_f32_16x16x32_bf16 v[62:65], v[134:137], v[166:169], v[62:65]
	v_mfma_f32_16x16x32_bf16 v[58:61], v[142:145], v[166:169], v[58:61]
	v_mfma_f32_16x16x32_bf16 v[50:53], v[134:137], v[184:187], v[50:53]
	v_mfma_f32_16x16x32_bf16 v[42:45], v[142:145], v[184:187], v[42:45]
	v_mfma_f32_16x16x32_bf16 v[34:37], v[134:137], v[192:195], v[34:37]
	v_mfma_f32_16x16x32_bf16 v[26:29], v[142:145], v[192:195], v[26:29]
	v_mfma_f32_16x16x32_bf16 v[18:21], v[134:137], v[204:207], v[18:21]
	v_mfma_f32_16x16x32_bf16 v[10:13], v[142:145], v[204:207], v[10:13]
	s_setprio 0
	s_setprio 1
	v_mfma_f32_16x16x32_bf16 v[54:57], v[146:149], v[162:165], v[54:57]
	v_mfma_f32_16x16x32_bf16 v[46:49], v[154:157], v[162:165], v[46:49]
	v_mfma_f32_16x16x32_bf16 v[38:41], v[146:149], v[170:173], v[38:41]
	v_mfma_f32_16x16x32_bf16 v[30:33], v[154:157], v[170:173], v[30:33]
	v_mfma_f32_16x16x32_bf16 v[22:25], v[146:149], v[188:191], v[22:25]
	v_mfma_f32_16x16x32_bf16 v[14:17], v[154:157], v[188:191], v[14:17]
	v_mfma_f32_16x16x32_bf16 v[6:9], v[146:149], v[200:203], v[6:9]
	v_mfma_f32_16x16x32_bf16 v[2:5], v[154:157], v[200:203], v[2:5]
	v_mfma_f32_16x16x32_bf16 v[54:57], v[150:153], v[166:169], v[54:57]
	v_mfma_f32_16x16x32_bf16 v[46:49], v[158:161], v[166:169], v[46:49]
	v_mfma_f32_16x16x32_bf16 v[38:41], v[150:153], v[184:187], v[38:41]
	v_mfma_f32_16x16x32_bf16 v[30:33], v[158:161], v[184:187], v[30:33]
	v_mfma_f32_16x16x32_bf16 v[22:25], v[150:153], v[192:195], v[22:25]
	v_mfma_f32_16x16x32_bf16 v[14:17], v[158:161], v[192:195], v[14:17]
	v_mfma_f32_16x16x32_bf16 v[6:9], v[150:153], v[204:207], v[6:9]
	v_mfma_f32_16x16x32_bf16 v[2:5], v[158:161], v[204:207], v[2:5]
	s_setprio 0
	s_barrier
	s_add_i32 s67, s67, 2
	s_add_u32 s39, s39, 0x100
	s_addc_u32 s66, s66, 0
	s_add_u32 s40, s40, 0x100
	s_addc_u32 s41, s41, 0
	s_cmp_gt_u32 s67, 13
	s_cbranch_scc0 .LBB0_1837
	s_and_b64 vcc, exec, s[22:23]
	s_cbranch_vccz .LBB0_1840
	s_barrier

; #define PG8_STAGE(bufoff, gbase, voff) do { _Pragma("unroll") for (int _i = 0; _i < 2; ++_i) \
;         __builtin_amdgcn_global_load_lds((const GAS unsigned*)((const GAS char*)(gbase) + (voff)[_i]), (LAS unsigned*)(lds + (bufoff) + ldsw + _i * 8192), 16, 0, 0); } while (0)
; #define PG8_LDA(dst, b, h) do { _Pragma("unroll") for (int m = 0; m < 4; ++m) _Pragma("unroll") for (int k = 0; k < 2; ++k) dst[m][k] = *(const LAS bf16x8*)(lds + PG8_SA(b, h) + aoff + m * 2048 + k * 1024); } while (0)
; #define PG8_LDB(dst, b, h) do { _Pragma("unroll") for (int n = 0; n < 2; ++n) _Pragma("unroll") for (int k = 0; k < 2; ++k) dst[n][k] = *(const LAS bf16x8*)(lds + PG8_SB(b, h) + boff + n * 2048 + k * 1024); } while (0)
; #define PG8_MMA(ai, bj, At, Bt) do { __builtin_amdgcn_s_setprio(1); _Pragma("unroll") for (int m = 0; m < 4; ++m) _Pragma("unroll") for (int n = 0; n < 2; ++n) _Pragma("unroll") for (int k = 0; k < 2; ++k) \
;         acc[ai][bj][m][n] = __builtin_amdgcn_mfma_f32_16x16x32_bf16(Bt[n][k], At[m][k], acc[ai][bj][m][n], 0, 0, 0); __builtin_amdgcn_s_setprio(0); } while (0)
; #define PG8_WAIT_V(n) asm volatile("s_waitcnt vmcnt(" #n ")" ::: "memory")
; #define PG8_WAIT_L(n) asm volatile("s_waitcnt lgkmcnt(" #n ")" ::: "memory")
; #define PG8_BAR __builtin_amdgcn_s_barrier()
; #define PG8_SCHED __builtin_amdgcn_sched_barrier(0)
; template <class Epi, class Sched, bool ALIGN_EPI>
; __device__ __forceinline__ void gemm_phase(LAS unsigned char* lds, const Gemm g, const Sched& S, const Epi& E, int wave_id) {
;     ...
;             PG8_LDB(B0, 0, 0); PG8_LDB(B1, 0, 1); PG8_SCHED; PG8_LDA(At, 0, 0); PG8_STAGE(PG8_SA(1, 1), a1 + hsA, voffA);
;             PG8_WAIT_V(8); PG8_WAIT_L(0); PG8_BAR; PG8_MMA(0, 0, At, B0); PG8_MMA(0, 1, At, B1); PG8_BAR; PG8_SCHED;
;             PG8_LDA(At, 0, 1); PG8_STAGE(PG8_SB(0, 0), b2, voffB); PG8_STAGE(PG8_SB(0, 1), b2 + hsB, voffB); PG8_STAGE(PG8_SA(0, 0), a2, voffA);
;             PG8_WAIT_V(8); PG8_WAIT_L(0); PG8_BAR; PG8_MMA(1, 0, At, B0); PG8_MMA(1, 1, At, B1); PG8_BAR; PG8_SCHED;
.LBB0_2565:
	s_add_u32 s28, s26, 0xfffc0080
	s_addc_u32 s29, s27, -1
	s_cmp_eq_u32 s60, 12
	s_cselect_b32 s31, s19, s29
	s_cselect_b32 s30, s33, s28
	s_cselect_b32 s29, s17, s59
	s_cselect_b32 s28, s57, s58
	v_lshl_add_u64 v[206:207], s[26:27], 0, v[138:139]
	s_add_i32 m0, s40, 0xc400
	s_nop 0
	global_load_lds_dwordx4 v[206:207], off
	v_lshl_add_u64 v[206:207], s[26:27], 0, v[136:137]
	s_add_i32 m0, s40, 0xe400
	s_nop 0
	global_load_lds_dwordx4 v[206:207], off
	v_add_u32_e32 v154, 0x10400, v153
	v_add_u32_e32 v170, 0x14400, v153
	ds_read_b128 v[140:143], v154
	ds_read_b128 v[144:147], v154 offset:1024
	ds_read_b128 v[148:151], v154 offset:2048
	ds_read_b128 v[154:157], v154 offset:3072
	ds_read_b128 v[158:161], v170
	ds_read_b128 v[162:165], v170 offset:1024
	ds_read_b128 v[166:169], v170 offset:2048
	ds_read_b128 v[170:173], v170 offset:3072
	ds_read_b128 v[174:177], v152 offset:1024
	ds_read_b128 v[178:181], v152 offset:2048
	ds_read_b128 v[182:185], v152 offset:3072
	ds_read_b128 v[186:189], v152 offset:4096
	ds_read_b128 v[190:193], v152 offset:5120
	ds_read_b128 v[194:197], v152 offset:6144
	ds_read_b128 v[198:201], v152 offset:7168
	ds_read_b128 v[202:205], v152 offset:8192
	s_waitcnt vmcnt(8)
	s_waitcnt lgkmcnt(0)
	s_barrier
	s_setprio 1
	s_waitcnt lgkmcnt(0)
	v_mfma_f32_16x16x32_bf16 v[126:129], v[140:143], v[174:177], v[126:129]
	v_mfma_f32_16x16x32_bf16 v[122:125], v[148:151], v[174:177], v[122:125]
	v_mfma_f32_16x16x32_bf16 v[110:113], v[140:143], v[182:185], v[110:113]
	v_mfma_f32_16x16x32_bf16 v[106:109], v[148:151], v[182:185], v[106:109]
	v_mfma_f32_16x16x32_bf16 v[94:97], v[140:143], v[190:193], v[94:97]
	v_mfma_f32_16x16x32_bf16 v[90:93], v[148:151], v[190:193], v[90:93]
	v_mfma_f32_16x16x32_bf16 v[78:81], v[140:143], v[198:201], v[78:81]
	v_mfma_f32_16x16x32_bf16 v[74:77], v[148:151], v[198:201], v[74:77]
	v_mfma_f32_16x16x32_bf16 v[126:129], v[144:147], v[178:181], v[126:129]
	v_mfma_f32_16x16x32_bf16 v[122:125], v[154:157], v[178:181], v[122:125]
	v_mfma_f32_16x16x32_bf16 v[110:113], v[144:147], v[186:189], v[110:113]
	v_mfma_f32_16x16x32_bf16 v[106:109], v[154:157], v[186:189], v[106:109]
	v_mfma_f32_16x16x32_bf16 v[94:97], v[144:147], v[194:197], v[94:97]
	v_mfma_f32_16x16x32_bf16 v[90:93], v[154:157], v[194:197], v[90:93]
	v_mfma_f32_16x16x32_bf16 v[78:81], v[144:147], v[202:205], v[78:81]
	v_mfma_f32_16x16x32_bf16 v[74:77], v[154:157], v[202:205], v[74:77]
	s_setprio 0
	s_setprio 1
	v_mfma_f32_16x16x32_bf16 v[118:121], v[158:161], v[174:177], v[118:121]
	v_mfma_f32_16x16x32_bf16 v[114:117], v[166:169], v[174:177], v[114:117]
	v_mfma_f32_16x16x32_bf16 v[102:105], v[158:161], v[182:185], v[102:105]
	v_mfma_f32_16x16x32_bf16 v[98:101], v[166:169], v[182:185], v[98:101]
	v_mfma_f32_16x16x32_bf16 v[86:89], v[158:161], v[190:193], v[86:89]
	v_mfma_f32_16x16x32_bf16 v[82:85], v[166:169], v[190:193], v[82:85]
	v_mfma_f32_16x16x32_bf16 v[70:73], v[158:161], v[198:201], v[70:73]
	v_mfma_f32_16x16x32_bf16 v[66:69], v[166:169], v[198:201], v[66:69]
	v_mfma_f32_16x16x32_bf16 v[118:121], v[162:165], v[178:181], v[118:121]
	v_mfma_f32_16x16x32_bf16 v[114:117], v[170:173], v[178:181], v[114:117]
	v_mfma_f32_16x16x32_bf16 v[102:105], v[162:165], v[186:189], v[102:105]
	v_mfma_f32_16x16x32_bf16 v[98:101], v[170:173], v[186:189], v[98:101]
	v_mfma_f32_16x16x32_bf16 v[86:89], v[162:165], v[194:197], v[86:89]
	v_mfma_f32_16x16x32_bf16 v[82:85], v[170:173], v[194:197], v[82:85]
	v_mfma_f32_16x16x32_bf16 v[70:73], v[162:165], v[202:205], v[70:73]
	v_mfma_f32_16x16x32_bf16 v[66:69], v[170:173], v[202:205], v[66:69]
	s_setprio 0
	s_barrier
	s_mov_b32 m0, s25
	v_lshl_add_u64 v[206:207], s[28:29], 0, v[0:1]
	s_add_u32 s62, s28, 0x40000
	global_load_lds_dwordx4 v[206:207], off
	v_lshl_add_u64 v[208:209], s[28:29], 0, v[130:131]
	s_mov_b32 m0, s41
	s_addc_u32 s63, s29, 0
	global_load_lds_dwordx4 v[208:209], off
	v_lshl_add_u64 v[210:211], s[62:63], 0, v[0:1]
	s_mov_b32 m0, s42
	v_lshl_add_u64 v[212:213], s[30:31], 0, v[132:133]
	global_load_lds_dwordx4 v[210:211], off
	v_lshl_add_u64 v[210:211], s[62:63], 0, v[130:131]
	s_mov_b32 m0, s43
	s_nop 0
	global_load_lds_dwordx4 v[210:211], off
	v_lshl_add_u64 v[210:211], s[30:31], 0, v[134:135]
	s_mov_b32 m0, s44
	s_nop 0
	global_load_lds_dwordx4 v[210:211], off
	s_mov_b32 m0, s45
	s_nop 0
	global_load_lds_dwordx4 v[212:213], off
	ds_read_b128 v[174:177], v152 offset:17408
	ds_read_b128 v[178:181], v152 offset:18432
	ds_read_b128 v[182:185], v152 offset:19456
	ds_read_b128 v[186:189], v152 offset:20480
	ds_read_b128 v[190:193], v152 offset:21504
	ds_read_b128 v[194:197], v152 offset:22528
	ds_read_b128 v[198:201], v152 offset:23552
	ds_read_b128 v[202:205], v152 offset:24576
	s_waitcnt vmcnt(8)
	s_waitcnt lgkmcnt(0)
	s_barrier
; #define PG8_STAGE(bufoff, gbase, voff) do { _Pragma("unroll") for (int _i = 0; _i < 2; ++_i) \
;         __builtin_amdgcn_global_load_lds((const GAS unsigned*)((const GAS char*)(gbase) + (voff)[_i]), (LAS unsigned*)(lds + (bufoff) + ldsw + _i * 8192), 16, 0, 0); } while (0)
; #define PG8_LDA(dst, b, h) do { _Pragma("unroll") for (int m = 0; m < 4; ++m) _Pragma("unroll") for (int k = 0; k < 2; ++k) dst[m][k] = *(const LAS bf16x8*)(lds + PG8_SA(b, h) + aoff + m * 2048 + k * 1024); } while (0)
; #define PG8_LDB(dst, b, h) do { _Pragma("unroll") for (int n = 0; n < 2; ++n) _Pragma("unroll") for (int k = 0; k < 2; ++k) dst[n][k] = *(const LAS bf16x8*)(lds + PG8_SB(b, h) + boff + n * 2048 + k * 1024); } while (0)
; #define PG8_MMA(ai, bj, At, Bt) do { __builtin_amdgcn_s_setprio(1); _Pragma("unroll") for (int m = 0; m < 4; ++m) _Pragma("unroll") for (int n = 0; n < 2; ++n) _Pragma("unroll") for (int k = 0; k < 2; ++k) \
;         acc[ai][bj][m][n] = __builtin_amdgcn_mfma_f32_16x16x32_bf16(Bt[n][k], At[m][k], acc[ai][bj][m][n], 0, 0, 0); __builtin_amdgcn_s_setprio(0); } while (0)
; #define PG8_WAIT_V(n) asm volatile("s_waitcnt vmcnt(" #n ")" ::: "memory")
; #define PG8_WAIT_L(n) asm volatile("s_waitcnt lgkmcnt(" #n ")" ::: "memory")
; #define PG8_BAR __builtin_amdgcn_s_barrier()
; #define PG8_SCHED __builtin_amdgcn_sched_barrier(0)
; template <class Epi, class Sched, bool ALIGN_EPI>
; __device__ __forceinline__ void gemm_phase(LAS unsigned char* lds, const Gemm g, const Sched& S, const Epi& E, int wave_id) {
;     ...
;             PG8_WAIT_V(8); PG8_WAIT_L(0); PG8_BAR; PG8_MMA(1, 0, At, B0); PG8_MMA(1, 1, At, B1); PG8_BAR; PG8_SCHED;
;             PG8_LDB(B0, 1, 0); PG8_LDB(B1, 1, 1); PG8_SCHED; PG8_LDA(At, 1, 0); PG8_STAGE(PG8_SA(0, 1), a2 + hsA, voffA);
;             PG8_WAIT_V(8); PG8_WAIT_L(0); PG8_BAR; PG8_MMA(0, 0, At, B0); PG8_MMA(0, 1, At, B1); PG8_BAR; PG8_SCHED;
	s_setprio 1
	s_waitcnt lgkmcnt(0)
	v_mfma_f32_16x16x32_bf16 v[62:65], v[140:143], v[174:177], v[62:65]
	v_mfma_f32_16x16x32_bf16 v[58:61], v[148:151], v[174:177], v[58:61]
	v_mfma_f32_16x16x32_bf16 v[46:49], v[140:143], v[182:185], v[46:49]
	v_mfma_f32_16x16x32_bf16 v[42:45], v[148:151], v[182:185], v[42:45]
	v_mfma_f32_16x16x32_bf16 v[30:33], v[140:143], v[190:193], v[30:33]
	v_mfma_f32_16x16x32_bf16 v[26:29], v[148:151], v[190:193], v[26:29]
	v_mfma_f32_16x16x32_bf16 v[14:17], v[140:143], v[198:201], v[14:17]
	v_mfma_f32_16x16x32_bf16 v[10:13], v[148:151], v[198:201], v[10:13]
	v_mfma_f32_16x16x32_bf16 v[62:65], v[144:147], v[178:181], v[62:65]
	v_mfma_f32_16x16x32_bf16 v[58:61], v[154:157], v[178:181], v[58:61]
	v_mfma_f32_16x16x32_bf16 v[46:49], v[144:147], v[186:189], v[46:49]
	v_mfma_f32_16x16x32_bf16 v[42:45], v[154:157], v[186:189], v[42:45]
	v_mfma_f32_16x16x32_bf16 v[30:33], v[144:147], v[194:197], v[30:33]
	v_mfma_f32_16x16x32_bf16 v[26:29], v[154:157], v[194:197], v[26:29]
	v_mfma_f32_16x16x32_bf16 v[14:17], v[144:147], v[202:205], v[14:17]
	v_mfma_f32_16x16x32_bf16 v[10:13], v[154:157], v[202:205], v[10:13]
	s_setprio 0
	s_setprio 1
	v_mfma_f32_16x16x32_bf16 v[54:57], v[158:161], v[174:177], v[54:57]
	v_mfma_f32_16x16x32_bf16 v[50:53], v[166:169], v[174:177], v[50:53]
	v_mfma_f32_16x16x32_bf16 v[38:41], v[158:161], v[182:185], v[38:41]
	v_mfma_f32_16x16x32_bf16 v[34:37], v[166:169], v[182:185], v[34:37]
	v_mfma_f32_16x16x32_bf16 v[22:25], v[158:161], v[190:193], v[22:25]
	v_mfma_f32_16x16x32_bf16 v[18:21], v[166:169], v[190:193], v[18:21]
	v_mfma_f32_16x16x32_bf16 v[6:9], v[158:161], v[198:201], v[6:9]
	v_mfma_f32_16x16x32_bf16 v[2:5], v[166:169], v[198:201], v[2:5]
	v_mfma_f32_16x16x32_bf16 v[54:57], v[162:165], v[178:181], v[54:57]
	v_mfma_f32_16x16x32_bf16 v[50:53], v[170:173], v[178:181], v[50:53]
	v_mfma_f32_16x16x32_bf16 v[38:41], v[162:165], v[186:189], v[38:41]
	v_mfma_f32_16x16x32_bf16 v[34:37], v[170:173], v[186:189], v[34:37]
	v_mfma_f32_16x16x32_bf16 v[22:25], v[162:165], v[194:197], v[22:25]
	v_mfma_f32_16x16x32_bf16 v[18:21], v[170:173], v[194:197], v[18:21]
	v_mfma_f32_16x16x32_bf16 v[6:9], v[162:165], v[202:205], v[6:9]
	v_mfma_f32_16x16x32_bf16 v[2:5], v[170:173], v[202:205], v[2:5]
	s_setprio 0
	s_barrier
	s_add_u32 s30, s30, 0x40000
	s_addc_u32 s31, s31, 0
	s_mov_b32 m0, s46
	v_lshl_add_u64 v[214:215], s[30:31], 0, v[134:135]
	global_load_lds_dwordx4 v[214:215], off
	v_lshl_add_u64 v[214:215], s[30:31], 0, v[132:133]
	s_mov_b32 m0, s47
	s_nop 0
	global_load_lds_dwordx4 v[214:215], off
	v_add_u32_e32 v154, 0x18400, v153
	v_add_u32_e32 v170, 0x1c400, v153
	ds_read_b128 v[140:143], v154
	ds_read_b128 v[144:147], v154 offset:1024
	ds_read_b128 v[148:151], v154 offset:2048
	ds_read_b128 v[154:157], v154 offset:3072
	ds_read_b128 v[158:161], v170
	ds_read_b128 v[162:165], v170 offset:1024
	ds_read_b128 v[166:169], v170 offset:2048
	ds_read_b128 v[170:173], v170 offset:3072
	ds_read_b128 v[174:177], v152 offset:33792
	ds_read_b128 v[178:181], v152 offset:34816
	ds_read_b128 v[182:185], v152 offset:35840
	ds_read_b128 v[186:189], v152 offset:36864
	ds_read_b128 v[190:193], v152 offset:37888
	ds_read_b128 v[194:197], v152 offset:38912
	ds_read_b128 v[198:201], v152 offset:39936
	ds_read_b128 v[202:205], v152 offset:40960
	s_waitcnt vmcnt(8)
	s_waitcnt lgkmcnt(0)
	s_barrier
	s_setprio 1
	s_waitcnt lgkmcnt(0)
	v_mfma_f32_16x16x32_bf16 v[126:129], v[140:143], v[174:177], v[126:129]
	v_mfma_f32_16x16x32_bf16 v[122:125], v[148:151], v[174:177], v[122:125]
	v_mfma_f32_16x16x32_bf16 v[110:113], v[140:143], v[182:185], v[110:113]
	v_mfma_f32_16x16x32_bf16 v[106:109], v[148:151], v[182:185], v[106:109]
	v_mfma_f32_16x16x32_bf16 v[94:97], v[140:143], v[190:193], v[94:97]
	v_mfma_f32_16x16x32_bf16 v[90:93], v[148:151], v[190:193], v[90:93]
	v_mfma_f32_16x16x32_bf16 v[78:81], v[140:143], v[198:201], v[78:81]
	v_mfma_f32_16x16x32_bf16 v[74:77], v[148:151], v[198:201], v[74:77]
	v_mfma_f32_16x16x32_bf16 v[126:129], v[144:147], v[178:181], v[126:129]
	v_mfma_f32_16x16x32_bf16 v[122:125], v[154:157], v[178:181], v[122:125]
	v_mfma_f32_16x16x32_bf16 v[110:113], v[144:147], v[186:189], v[110:113]
	v_mfma_f32_16x16x32_bf16 v[106:109], v[154:157], v[186:189], v[106:109]
	v_mfma_f32_16x16x32_bf16 v[94:97], v[144:147], v[194:197], v[94:97]
	v_mfma_f32_16x16x32_bf16 v[90:93], v[154:157], v[194:197], v[90:93]
	v_mfma_f32_16x16x32_bf16 v[78:81], v[144:147], v[202:205], v[78:81]
	v_mfma_f32_16x16x32_bf16 v[74:77], v[154:157], v[202:205], v[74:77]
	s_setprio 0
	s_setprio 1
	v_mfma_f32_16x16x32_bf16 v[118:121], v[158:161], v[174:177], v[118:121]
	v_mfma_f32_16x16x32_bf16 v[114:117], v[166:169], v[174:177], v[114:117]
	v_mfma_f32_16x16x32_bf16 v[102:105], v[158:161], v[182:185], v[102:105]
	v_mfma_f32_16x16x32_bf16 v[98:101], v[166:169], v[182:185], v[98:101]
	v_mfma_f32_16x16x32_bf16 v[86:89], v[158:161], v[190:193], v[86:89]
	v_mfma_f32_16x16x32_bf16 v[82:85], v[166:169], v[190:193], v[82:85]
	v_mfma_f32_16x16x32_bf16 v[70:73], v[158:161], v[198:201], v[70:73]
	v_mfma_f32_16x16x32_bf16 v[66:69], v[166:169], v[198:201], v[66:69]
	v_mfma_f32_16x16x32_bf16 v[118:121], v[162:165], v[178:181], v[118:121]
	v_mfma_f32_16x16x32_bf16 v[114:117], v[170:173], v[178:181], v[114:117]
	v_mfma_f32_16x16x32_bf16 v[102:105], v[162:165], v[186:189], v[102:105]
	v_mfma_f32_16x16x32_bf16 v[98:101], v[170:173], v[186:189], v[98:101]
	v_mfma_f32_16x16x32_bf16 v[86:89], v[162:165], v[194:197], v[86:89]
	v_mfma_f32_16x16x32_bf16 v[82:85], v[170:173], v[194:197], v[82:85]
	v_mfma_f32_16x16x32_bf16 v[70:73], v[162:165], v[202:205], v[70:73]
	v_mfma_f32_16x16x32_bf16 v[66:69], v[170:173], v[202:205], v[66:69]
	s_setprio 0
	s_barrier
; #define PG8_STAGE(bufoff, gbase, voff) do { _Pragma("unroll") for (int _i = 0; _i < 2; ++_i) \
;         __builtin_amdgcn_global_load_lds((const GAS unsigned*)((const GAS char*)(gbase) + (voff)[_i]), (LAS unsigned*)(lds + (bufoff) + ldsw + _i * 8192), 16, 0, 0); } while (0)
; #define PG8_LDA(dst, b, h) do { _Pragma("unroll") for (int m = 0; m < 4; ++m) _Pragma("unroll") for (int k = 0; k < 2; ++k) dst[m][k] = *(const LAS bf16x8*)(lds + PG8_SA(b, h) + aoff + m * 2048 + k * 1024); } while (0)
; #define PG8_MMA(ai, bj, At, Bt) do { __builtin_amdgcn_s_setprio(1); _Pragma("unroll") for (int m = 0; m < 4; ++m) _Pragma("unroll") for (int n = 0; n < 2; ++n) _Pragma("unroll") for (int k = 0; k < 2; ++k) \
;         acc[ai][bj][m][n] = __builtin_amdgcn_mfma_f32_16x16x32_bf16(Bt[n][k], At[m][k], acc[ai][bj][m][n], 0, 0, 0); __builtin_amdgcn_s_setprio(0); } while (0)
; #define PG8_WAIT_V(n) asm volatile("s_waitcnt vmcnt(" #n ")" ::: "memory")
; #define PG8_WAIT_L(n) asm volatile("s_waitcnt lgkmcnt(" #n ")" ::: "memory")
; #define PG8_BAR __builtin_amdgcn_s_barrier()
; #define PG8_SCHED __builtin_amdgcn_sched_barrier(0)
; template <class Epi, class Sched, bool ALIGN_EPI>
; __device__ __forceinline__ void gemm_phase(LAS unsigned char* lds, const Gemm g, const Sched& S, const Epi& E, int wave_id) {
;     ...
;             PG8_LDA(At, 1, 1); PG8_STAGE(PG8_SB(1, 0), b3, voffB); PG8_STAGE(PG8_SB(1, 1), b3 + hsB, voffB); PG8_STAGE(PG8_SA(1, 0), a3, voffA);
;             PG8_WAIT_V(8); PG8_WAIT_L(0); PG8_BAR; PG8_MMA(1, 0, At, B0); PG8_MMA(1, 1, At, B1); PG8_BAR; PG8_SCHED;
;         }
	s_mov_b32 m0, s50
	v_lshl_add_u64 v[206:207], v[206:207], 0, s[92:93]
	s_add_u32 s28, s28, 0x40080
	global_load_lds_dwordx4 v[206:207], off
	v_lshl_add_u64 v[206:207], v[208:209], 0, s[92:93]
	s_mov_b32 m0, s51
	s_addc_u32 s29, s29, 0
	global_load_lds_dwordx4 v[206:207], off
	v_lshl_add_u64 v[206:207], s[28:29], 0, v[0:1]
	s_mov_b32 m0, s54
	s_nop 0
	global_load_lds_dwordx4 v[206:207], off
	v_lshl_add_u64 v[206:207], s[28:29], 0, v[130:131]
	s_mov_b32 m0, s55
	s_nop 0
	global_load_lds_dwordx4 v[206:207], off
	v_lshl_add_u64 v[206:207], v[210:211], 0, s[92:93]
	s_mov_b32 m0, s52
	s_nop 0
	global_load_lds_dwordx4 v[206:207], off
	v_lshl_add_u64 v[206:207], v[212:213], 0, s[92:93]
	s_mov_b32 m0, s53
	s_nop 0
	global_load_lds_dwordx4 v[206:207], off
	ds_read_b128 v[174:177], v152 offset:50176
	ds_read_b128 v[178:181], v152 offset:51200
	ds_read_b128 v[182:185], v152 offset:52224
	ds_read_b128 v[186:189], v152 offset:53248
	ds_read_b128 v[190:193], v152 offset:54272
	ds_read_b128 v[194:197], v152 offset:55296
	ds_read_b128 v[198:201], v152 offset:56320
	ds_read_b128 v[202:205], v152 offset:57344
	s_waitcnt vmcnt(8)
	s_waitcnt lgkmcnt(0)
	s_barrier
	s_setprio 1
	s_waitcnt lgkmcnt(0)
	v_mfma_f32_16x16x32_bf16 v[62:65], v[140:143], v[174:177], v[62:65]
	v_mfma_f32_16x16x32_bf16 v[58:61], v[148:151], v[174:177], v[58:61]
	v_mfma_f32_16x16x32_bf16 v[46:49], v[140:143], v[182:185], v[46:49]
	v_mfma_f32_16x16x32_bf16 v[42:45], v[148:151], v[182:185], v[42:45]
	v_mfma_f32_16x16x32_bf16 v[30:33], v[140:143], v[190:193], v[30:33]
	v_mfma_f32_16x16x32_bf16 v[26:29], v[148:151], v[190:193], v[26:29]
	v_mfma_f32_16x16x32_bf16 v[14:17], v[140:143], v[198:201], v[14:17]
	v_mfma_f32_16x16x32_bf16 v[10:13], v[148:151], v[198:201], v[10:13]
	v_mfma_f32_16x16x32_bf16 v[62:65], v[144:147], v[178:181], v[62:65]
	v_mfma_f32_16x16x32_bf16 v[58:61], v[154:157], v[178:181], v[58:61]
	v_mfma_f32_16x16x32_bf16 v[46:49], v[144:147], v[186:189], v[46:49]
	v_mfma_f32_16x16x32_bf16 v[42:45], v[154:157], v[186:189], v[42:45]
	v_mfma_f32_16x16x32_bf16 v[30:33], v[144:147], v[194:197], v[30:33]
	v_mfma_f32_16x16x32_bf16 v[26:29], v[154:157], v[194:197], v[26:29]
	v_mfma_f32_16x16x32_bf16 v[14:17], v[144:147], v[202:205], v[14:17]
	v_mfma_f32_16x16x32_bf16 v[10:13], v[154:157], v[202:205], v[10:13]
	s_setprio 0
	s_setprio 1
	v_mfma_f32_16x16x32_bf16 v[54:57], v[158:161], v[174:177], v[54:57]
	v_mfma_f32_16x16x32_bf16 v[50:53], v[166:169], v[174:177], v[50:53]
	v_mfma_f32_16x16x32_bf16 v[38:41], v[158:161], v[182:185], v[38:41]
	v_mfma_f32_16x16x32_bf16 v[34:37], v[166:169], v[182:185], v[34:37]
	v_mfma_f32_16x16x32_bf16 v[22:25], v[158:161], v[190:193], v[22:25]
	v_mfma_f32_16x16x32_bf16 v[18:21], v[166:169], v[190:193], v[18:21]
	v_mfma_f32_16x16x32_bf16 v[6:9], v[158:161], v[198:201], v[6:9]
	v_mfma_f32_16x16x32_bf16 v[2:5], v[166:169], v[198:201], v[2:5]
	v_mfma_f32_16x16x32_bf16 v[54:57], v[162:165], v[178:181], v[54:57]
	v_mfma_f32_16x16x32_bf16 v[50:53], v[170:173], v[178:181], v[50:53]
	v_mfma_f32_16x16x32_bf16 v[38:41], v[162:165], v[186:189], v[38:41]
	v_mfma_f32_16x16x32_bf16 v[34:37], v[170:173], v[186:189], v[34:37]
	v_mfma_f32_16x16x32_bf16 v[22:25], v[162:165], v[194:197], v[22:25]
	v_mfma_f32_16x16x32_bf16 v[18:21], v[170:173], v[194:197], v[18:21]
	v_mfma_f32_16x16x32_bf16 v[6:9], v[162:165], v[202:205], v[6:9]
	v_mfma_f32_16x16x32_bf16 v[2:5], v[170:173], v[202:205], v[2:5]
	s_setprio 0
	s_barrier
	s_add_i32 s60, s60, 2
	s_add_u32 s58, s58, 0x100
	s_addc_u32 s59, s59, 0
	s_add_u32 s26, s26, 0x100
	s_addc_u32 s27, s27, 0
	s_cmp_gt_u32 s60, 13
	s_cbranch_scc0 .LBB0_2565
	s_and_b64 vcc, exec, s[14:15]
	s_cbranch_vccz .LBB0_2568
	s_barrier

; #define PG8_STAGE(bufoff, gbase, voff) do { _Pragma("unroll") for (int _i = 0; _i < 2; ++_i) \
;         __builtin_amdgcn_global_load_lds((const GAS unsigned*)((const GAS char*)(gbase) + (voff)[_i]), (LAS unsigned*)(lds + (bufoff) + ldsw + _i * 8192), 16, 0, 0); } while (0)
; #define PG8_LDA(dst, b, h) do { _Pragma("unroll") for (int m = 0; m < 4; ++m) _Pragma("unroll") for (int k = 0; k < 2; ++k) dst[m][k] = *(const LAS bf16x8*)(lds + PG8_SA(b, h) + aoff + m * 2048 + k * 1024); } while (0)
; #define PG8_LDB(dst, b, h) do { _Pragma("unroll") for (int n = 0; n < 2; ++n) _Pragma("unroll") for (int k = 0; k < 2; ++k) dst[n][k] = *(const LAS bf16x8*)(lds + PG8_SB(b, h) + boff + n * 2048 + k * 1024); } while (0)
; #define PG8_MMA(ai, bj, At, Bt) do { __builtin_amdgcn_s_setprio(1); _Pragma("unroll") for (int m = 0; m < 4; ++m) _Pragma("unroll") for (int n = 0; n < 2; ++n) _Pragma("unroll") for (int k = 0; k < 2; ++k) \
;         acc[ai][bj][m][n] = __builtin_amdgcn_mfma_f32_16x16x32_bf16(Bt[n][k], At[m][k], acc[ai][bj][m][n], 0, 0, 0); __builtin_amdgcn_s_setprio(0); } while (0)
; #define PG8_WAIT_V(n) asm volatile("s_waitcnt vmcnt(" #n ")" ::: "memory")
; #define PG8_WAIT_L(n) asm volatile("s_waitcnt lgkmcnt(" #n ")" ::: "memory")
; #define PG8_BAR __builtin_amdgcn_s_barrier()
; #define PG8_SCHED __builtin_amdgcn_sched_barrier(0)
; template <class Epi, class Sched, bool ALIGN_EPI>
; __device__ __forceinline__ void gemm_phase(LAS unsigned char* lds, const Gemm g, const Sched& S, const Epi& E, int wave_id) {
;     ...
;             PG8_LDB(B0, 0, 0); PG8_LDB(B1, 0, 1); PG8_SCHED; PG8_LDA(At, 0, 0); PG8_STAGE(PG8_SA(1, 1), a1 + hsA, voffA);
;             PG8_WAIT_V(8); PG8_WAIT_L(0); PG8_BAR; PG8_MMA(0, 0, At, B0); PG8_MMA(0, 1, At, B1); PG8_BAR; PG8_SCHED;
;             PG8_LDA(At, 0, 1); PG8_STAGE(PG8_SB(0, 0), b2, voffB); PG8_STAGE(PG8_SB(0, 1), b2 + hsB, voffB); PG8_STAGE(PG8_SA(0, 0), a2, voffA);
;             PG8_WAIT_V(8); PG8_WAIT_L(0); PG8_BAR; PG8_MMA(1, 0, At, B0); PG8_MMA(1, 1, At, B1); PG8_BAR; PG8_SCHED;
.LBB0_2620:
	s_add_u32 s38, s36, 0xfff80080
	s_addc_u32 s39, s37, -1
	s_cmp_eq_u32 s65, 28
	s_cselect_b32 s41, s1, s39
	s_cselect_b32 s40, s5, s38
	s_cselect_b32 s39, s7, s33
	s_cselect_b32 s38, s27, s29
	v_lshl_add_u64 v[194:195], s[36:37], 0, v[218:219]
	s_add_i32 m0, s43, 0xc400
	s_nop 0
	global_load_lds_dwordx4 v[194:195], off
	v_lshl_add_u64 v[194:195], s[36:37], 0, v[216:217]
	s_add_i32 m0, s43, 0xe400
	s_nop 0
	global_load_lds_dwordx4 v[194:195], off
	v_add_u32_e32 v46, 0x10400, v235
	v_add_u32_e32 v62, 0x14400, v235
	ds_read_b128 v[34:37], v46
	ds_read_b128 v[38:41], v46 offset:1024
	ds_read_b128 v[42:45], v46 offset:2048
	ds_read_b128 v[46:49], v46 offset:3072
	ds_read_b128 v[50:53], v62
	ds_read_b128 v[54:57], v62 offset:1024
	ds_read_b128 v[58:61], v62 offset:2048
	ds_read_b128 v[62:65], v62 offset:3072
	ds_read_b128 v[82:85], v234 offset:1024
	ds_read_b128 v[94:97], v234 offset:2048
	ds_read_b128 v[170:173], v234 offset:3072
	ds_read_b128 v[174:177], v234 offset:4096
	ds_read_b128 v[178:181], v234 offset:5120
	ds_read_b128 v[182:185], v234 offset:6144
	ds_read_b128 v[186:189], v234 offset:7168
	ds_read_b128 v[190:193], v234 offset:8192
	s_waitcnt vmcnt(8)
	s_waitcnt lgkmcnt(0)
	s_barrier
	s_setprio 1
	s_waitcnt lgkmcnt(0)
	v_mfma_f32_16x16x32_bf16 v[166:169], v[34:37], v[82:85], v[166:169]
	v_mfma_f32_16x16x32_bf16 v[162:165], v[42:45], v[82:85], v[162:165]
	v_mfma_f32_16x16x32_bf16 v[150:153], v[34:37], v[170:173], v[150:153]
	v_mfma_f32_16x16x32_bf16 v[146:149], v[42:45], v[170:173], v[146:149]
	v_mfma_f32_16x16x32_bf16 v[134:137], v[34:37], v[178:181], v[134:137]
	v_mfma_f32_16x16x32_bf16 v[130:133], v[42:45], v[178:181], v[130:133]
	v_mfma_f32_16x16x32_bf16 v[118:121], v[34:37], v[186:189], v[118:121]
	v_mfma_f32_16x16x32_bf16 v[114:117], v[42:45], v[186:189], v[114:117]
	v_mfma_f32_16x16x32_bf16 v[166:169], v[38:41], v[94:97], v[166:169]
	v_mfma_f32_16x16x32_bf16 v[162:165], v[46:49], v[94:97], v[162:165]
	v_mfma_f32_16x16x32_bf16 v[150:153], v[38:41], v[174:177], v[150:153]
	v_mfma_f32_16x16x32_bf16 v[146:149], v[46:49], v[174:177], v[146:149]
	v_mfma_f32_16x16x32_bf16 v[134:137], v[38:41], v[182:185], v[134:137]
	v_mfma_f32_16x16x32_bf16 v[130:133], v[46:49], v[182:185], v[130:133]
	v_mfma_f32_16x16x32_bf16 v[118:121], v[38:41], v[190:193], v[118:121]
	v_mfma_f32_16x16x32_bf16 v[114:117], v[46:49], v[190:193], v[114:117]
	s_setprio 0
	s_setprio 1
	v_mfma_f32_16x16x32_bf16 v[158:161], v[50:53], v[82:85], v[158:161]
	v_mfma_f32_16x16x32_bf16 v[82:85], v[58:61], v[82:85], v[154:157]
	v_mfma_f32_16x16x32_bf16 v[138:141], v[58:61], v[170:173], v[138:141]
	v_mfma_f32_16x16x32_bf16 v[126:129], v[50:53], v[178:181], v[126:129]
	v_mfma_f32_16x16x32_bf16 v[122:125], v[58:61], v[178:181], v[122:125]
	v_mfma_f32_16x16x32_bf16 v[110:113], v[50:53], v[186:189], v[110:113]
	v_mfma_f32_16x16x32_bf16 v[106:109], v[58:61], v[186:189], v[106:109]
	v_mfma_f32_16x16x32_bf16 v[158:161], v[54:57], v[94:97], v[158:161]
	v_mfma_f32_16x16x32_bf16 v[82:85], v[62:65], v[94:97], v[82:85]
	v_mfma_f32_16x16x32_bf16 v[94:97], v[50:53], v[170:173], v[142:145]
	v_mfma_f32_16x16x32_bf16 v[138:141], v[62:65], v[174:177], v[138:141]
	v_mfma_f32_16x16x32_bf16 v[126:129], v[54:57], v[182:185], v[126:129]
	v_mfma_f32_16x16x32_bf16 v[122:125], v[62:65], v[182:185], v[122:125]
	v_mfma_f32_16x16x32_bf16 v[110:113], v[54:57], v[190:193], v[110:113]
	v_mfma_f32_16x16x32_bf16 v[106:109], v[62:65], v[190:193], v[106:109]
	v_mfma_f32_16x16x32_bf16 v[94:97], v[54:57], v[174:177], v[94:97]
	s_setprio 0
	s_barrier
	s_mov_b32 m0, s48
	v_lshl_add_u64 v[202:203], s[38:39], 0, v[0:1]
	s_add_u32 s66, s38, 0x80000
	global_load_lds_dwordx4 v[202:203], off
	v_lshl_add_u64 v[204:205], s[38:39], 0, v[210:211]
	s_mov_b32 m0, s49
	s_addc_u32 s67, s39, 0
	global_load_lds_dwordx4 v[204:205], off
	v_lshl_add_u64 v[194:195], s[66:67], 0, v[0:1]
	s_mov_b32 m0, s50
	v_lshl_add_u64 v[220:221], s[40:41], 0, v[206:207]
	global_load_lds_dwordx4 v[194:195], off
	v_lshl_add_u64 v[194:195], s[66:67], 0, v[210:211]
	s_mov_b32 m0, s51
	v_lshl_add_u64 v[224:225], s[40:41], 0, v[208:209]
	global_load_lds_dwordx4 v[194:195], off
	s_mov_b32 m0, s52
	s_nop 0
	global_load_lds_dwordx4 v[220:221], off
	s_mov_b32 m0, s53
	s_nop 0
	global_load_lds_dwordx4 v[224:225], off
	ds_read_b128 v[142:145], v234 offset:17408
	ds_read_b128 v[154:157], v234 offset:18432
	ds_read_b128 v[170:173], v234 offset:19456
	ds_read_b128 v[174:177], v234 offset:20480
	ds_read_b128 v[178:181], v234 offset:21504
	ds_read_b128 v[182:185], v234 offset:22528
	ds_read_b128 v[186:189], v234 offset:23552
	ds_read_b128 v[190:193], v234 offset:24576
	s_waitcnt vmcnt(8)
	s_waitcnt lgkmcnt(0)
	s_barrier
; #define PG8_STAGE(bufoff, gbase, voff) do { _Pragma("unroll") for (int _i = 0; _i < 2; ++_i) \
;         __builtin_amdgcn_global_load_lds((const GAS unsigned*)((const GAS char*)(gbase) + (voff)[_i]), (LAS unsigned*)(lds + (bufoff) + ldsw + _i * 8192), 16, 0, 0); } while (0)
; #define PG8_LDA(dst, b, h) do { _Pragma("unroll") for (int m = 0; m < 4; ++m) _Pragma("unroll") for (int k = 0; k < 2; ++k) dst[m][k] = *(const LAS bf16x8*)(lds + PG8_SA(b, h) + aoff + m * 2048 + k * 1024); } while (0)
; #define PG8_LDB(dst, b, h) do { _Pragma("unroll") for (int n = 0; n < 2; ++n) _Pragma("unroll") for (int k = 0; k < 2; ++k) dst[n][k] = *(const LAS bf16x8*)(lds + PG8_SB(b, h) + boff + n * 2048 + k * 1024); } while (0)
; #define PG8_MMA(ai, bj, At, Bt) do { __builtin_amdgcn_s_setprio(1); _Pragma("unroll") for (int m = 0; m < 4; ++m) _Pragma("unroll") for (int n = 0; n < 2; ++n) _Pragma("unroll") for (int k = 0; k < 2; ++k) \
;         acc[ai][bj][m][n] = __builtin_amdgcn_mfma_f32_16x16x32_bf16(Bt[n][k], At[m][k], acc[ai][bj][m][n], 0, 0, 0); __builtin_amdgcn_s_setprio(0); } while (0)
; #define PG8_WAIT_V(n) asm volatile("s_waitcnt vmcnt(" #n ")" ::: "memory")
; #define PG8_WAIT_L(n) asm volatile("s_waitcnt lgkmcnt(" #n ")" ::: "memory")
; #define PG8_BAR __builtin_amdgcn_s_barrier()
; #define PG8_SCHED __builtin_amdgcn_sched_barrier(0)
; template <class Epi, class Sched, bool ALIGN_EPI>
; __device__ __forceinline__ void gemm_phase(LAS unsigned char* lds, const Gemm g, const Sched& S, const Epi& E, int wave_id) {
;     ...
;             PG8_WAIT_V(8); PG8_WAIT_L(0); PG8_BAR; PG8_MMA(1, 0, At, B0); PG8_MMA(1, 1, At, B1); PG8_BAR; PG8_SCHED;
;             PG8_LDB(B0, 1, 0); PG8_LDB(B1, 1, 1); PG8_SCHED; PG8_LDA(At, 1, 0); PG8_STAGE(PG8_SA(0, 1), a2 + hsA, voffA);
;             PG8_WAIT_V(8); PG8_WAIT_L(0); PG8_BAR; PG8_MMA(0, 0, At, B0); PG8_MMA(0, 1, At, B1); PG8_BAR; PG8_SCHED;
	s_setprio 1
	s_waitcnt lgkmcnt(0)
	v_mfma_f32_16x16x32_bf16 v[102:105], v[34:37], v[142:145], v[102:105]
	v_mfma_f32_16x16x32_bf16 v[98:101], v[42:45], v[142:145], v[98:101]
	v_mfma_f32_16x16x32_bf16 v[78:81], v[34:37], v[170:173], v[78:81]
	v_mfma_f32_16x16x32_bf16 v[74:77], v[42:45], v[170:173], v[74:77]
	v_mfma_f32_16x16x32_bf16 v[30:33], v[34:37], v[178:181], v[30:33]
	v_mfma_f32_16x16x32_bf16 v[26:29], v[42:45], v[178:181], v[26:29]
	v_mfma_f32_16x16x32_bf16 v[14:17], v[34:37], v[186:189], v[14:17]
	v_mfma_f32_16x16x32_bf16 v[10:13], v[42:45], v[186:189], v[10:13]
	v_mfma_f32_16x16x32_bf16 v[102:105], v[38:41], v[154:157], v[102:105]
	v_mfma_f32_16x16x32_bf16 v[98:101], v[46:49], v[154:157], v[98:101]
	v_mfma_f32_16x16x32_bf16 v[78:81], v[38:41], v[174:177], v[78:81]
	v_mfma_f32_16x16x32_bf16 v[74:77], v[46:49], v[174:177], v[74:77]
	v_mfma_f32_16x16x32_bf16 v[30:33], v[38:41], v[182:185], v[30:33]
	v_mfma_f32_16x16x32_bf16 v[26:29], v[46:49], v[182:185], v[26:29]
	v_mfma_f32_16x16x32_bf16 v[14:17], v[38:41], v[190:193], v[14:17]
	v_mfma_f32_16x16x32_bf16 v[10:13], v[46:49], v[190:193], v[10:13]
	s_setprio 0
	s_setprio 1
	v_mfma_f32_16x16x32_bf16 v[22:25], v[50:53], v[178:181], v[22:25]
	v_mfma_f32_16x16x32_bf16 v[18:21], v[58:61], v[178:181], v[18:21]
	v_mfma_f32_16x16x32_bf16 v[6:9], v[50:53], v[186:189], v[6:9]
	v_mfma_f32_16x16x32_bf16 v[2:5], v[58:61], v[186:189], v[2:5]
	v_mfma_f32_16x16x32_bf16 v[34:37], v[50:53], v[142:145], v[90:93]
	v_mfma_f32_16x16x32_bf16 v[38:41], v[58:61], v[142:145], v[86:89]
	v_mfma_f32_16x16x32_bf16 v[42:45], v[50:53], v[170:173], v[70:73]
	v_mfma_f32_16x16x32_bf16 v[46:49], v[58:61], v[170:173], v[66:69]
	v_mfma_f32_16x16x32_bf16 v[22:25], v[54:57], v[182:185], v[22:25]
	v_mfma_f32_16x16x32_bf16 v[18:21], v[62:65], v[182:185], v[18:21]
	v_mfma_f32_16x16x32_bf16 v[6:9], v[54:57], v[190:193], v[6:9]
	v_mfma_f32_16x16x32_bf16 v[2:5], v[62:65], v[190:193], v[2:5]
	v_mfma_f32_16x16x32_bf16 v[34:37], v[54:57], v[154:157], v[34:37]
	v_mfma_f32_16x16x32_bf16 v[38:41], v[62:65], v[154:157], v[38:41]
	v_mfma_f32_16x16x32_bf16 v[42:45], v[54:57], v[174:177], v[42:45]
	v_mfma_f32_16x16x32_bf16 v[46:49], v[62:65], v[174:177], v[46:49]
	s_setprio 0
	s_barrier
	s_add_u32 s40, s40, 0x80000
	s_addc_u32 s41, s41, 0
	s_mov_b32 m0, s54
	v_lshl_add_u64 v[142:143], s[40:41], 0, v[206:207]
	global_load_lds_dwordx4 v[142:143], off
	v_lshl_add_u64 v[142:143], s[40:41], 0, v[208:209]
	s_mov_b32 m0, s55
	s_nop 0
	global_load_lds_dwordx4 v[142:143], off
	v_add_u32_e32 v62, 0x18400, v235
	v_add_u32_e32 v66, 0x1c400, v235
	ds_read_b128 v[50:53], v62
	ds_read_b128 v[54:57], v62 offset:1024
	ds_read_b128 v[58:61], v62 offset:2048
	ds_read_b128 v[62:65], v62 offset:3072
	ds_read_b128 v[170:173], v66
	ds_read_b128 v[174:177], v66 offset:1024
	ds_read_b128 v[178:181], v66 offset:2048
	ds_read_b128 v[182:185], v66 offset:3072
	ds_read_b128 v[66:69], v234 offset:33792
	ds_read_b128 v[70:73], v234 offset:34816
	ds_read_b128 v[86:89], v234 offset:35840
	ds_read_b128 v[90:93], v234 offset:36864
	ds_read_b128 v[186:189], v234 offset:37888
	ds_read_b128 v[190:193], v234 offset:38912
	ds_read_b128 v[194:197], v234 offset:39936
	ds_read_b128 v[198:201], v234 offset:40960
	s_waitcnt vmcnt(8)
	s_waitcnt lgkmcnt(0)
	s_barrier
	s_setprio 1
	s_waitcnt lgkmcnt(0)
	v_mfma_f32_16x16x32_bf16 v[142:145], v[50:53], v[66:69], v[166:169]
	v_mfma_f32_16x16x32_bf16 v[166:169], v[54:57], v[70:73], v[142:145]
	v_mfma_f32_16x16x32_bf16 v[142:145], v[58:61], v[66:69], v[162:165]
	v_mfma_f32_16x16x32_bf16 v[162:165], v[62:65], v[70:73], v[142:145]
	v_mfma_f32_16x16x32_bf16 v[142:145], v[50:53], v[86:89], v[150:153]
	v_mfma_f32_16x16x32_bf16 v[150:153], v[54:57], v[90:93], v[142:145]
	v_mfma_f32_16x16x32_bf16 v[142:145], v[58:61], v[86:89], v[146:149]
	v_mfma_f32_16x16x32_bf16 v[134:137], v[50:53], v[186:189], v[134:137]
	v_mfma_f32_16x16x32_bf16 v[130:133], v[58:61], v[186:189], v[130:133]
	v_mfma_f32_16x16x32_bf16 v[118:121], v[50:53], v[194:197], v[118:121]
	v_mfma_f32_16x16x32_bf16 v[114:117], v[58:61], v[194:197], v[114:117]
	v_mfma_f32_16x16x32_bf16 v[146:149], v[62:65], v[90:93], v[142:145]
	v_mfma_f32_16x16x32_bf16 v[134:137], v[54:57], v[190:193], v[134:137]
	v_mfma_f32_16x16x32_bf16 v[130:133], v[62:65], v[190:193], v[130:133]
	v_mfma_f32_16x16x32_bf16 v[118:121], v[54:57], v[198:201], v[118:121]
	v_mfma_f32_16x16x32_bf16 v[114:117], v[62:65], v[198:201], v[114:117]
	s_setprio 0
	s_setprio 1
	v_mfma_f32_16x16x32_bf16 v[142:145], v[170:173], v[66:69], v[158:161]
	v_mfma_f32_16x16x32_bf16 v[66:69], v[178:181], v[66:69], v[82:85]
	v_mfma_f32_16x16x32_bf16 v[154:157], v[182:185], v[70:73], v[66:69]
	v_mfma_f32_16x16x32_bf16 v[66:69], v[170:173], v[86:89], v[94:97]
	v_mfma_f32_16x16x32_bf16 v[158:161], v[174:177], v[70:73], v[142:145]
	v_mfma_f32_16x16x32_bf16 v[142:145], v[174:177], v[90:93], v[66:69]
	v_mfma_f32_16x16x32_bf16 v[66:69], v[178:181], v[86:89], v[138:141]
	v_mfma_f32_16x16x32_bf16 v[138:141], v[182:185], v[90:93], v[66:69]
	v_mfma_f32_16x16x32_bf16 v[66:69], v[170:173], v[186:189], v[126:129]
	v_mfma_f32_16x16x32_bf16 v[126:129], v[174:177], v[190:193], v[66:69]
	v_mfma_f32_16x16x32_bf16 v[66:69], v[178:181], v[186:189], v[122:125]
	v_mfma_f32_16x16x32_bf16 v[122:125], v[182:185], v[190:193], v[66:69]
	v_mfma_f32_16x16x32_bf16 v[66:69], v[170:173], v[194:197], v[110:113]
	v_mfma_f32_16x16x32_bf16 v[110:113], v[174:177], v[198:201], v[66:69]
	v_mfma_f32_16x16x32_bf16 v[66:69], v[178:181], v[194:197], v[106:109]
	v_mfma_f32_16x16x32_bf16 v[106:109], v[182:185], v[198:201], v[66:69]
	s_setprio 0
	s_barrier
; #define PG8_STAGE(bufoff, gbase, voff) do { _Pragma("unroll") for (int _i = 0; _i < 2; ++_i) \
;         __builtin_amdgcn_global_load_lds((const GAS unsigned*)((const GAS char*)(gbase) + (voff)[_i]), (LAS unsigned*)(lds + (bufoff) + ldsw + _i * 8192), 16, 0, 0); } while (0)
; #define PG8_LDA(dst, b, h) do { _Pragma("unroll") for (int m = 0; m < 4; ++m) _Pragma("unroll") for (int k = 0; k < 2; ++k) dst[m][k] = *(const LAS bf16x8*)(lds + PG8_SA(b, h) + aoff + m * 2048 + k * 1024); } while (0)
; #define PG8_MMA(ai, bj, At, Bt) do { __builtin_amdgcn_s_setprio(1); _Pragma("unroll") for (int m = 0; m < 4; ++m) _Pragma("unroll") for (int n = 0; n < 2; ++n) _Pragma("unroll") for (int k = 0; k < 2; ++k) \
;         acc[ai][bj][m][n] = __builtin_amdgcn_mfma_f32_16x16x32_bf16(Bt[n][k], At[m][k], acc[ai][bj][m][n], 0, 0, 0); __builtin_amdgcn_s_setprio(0); } while (0)
; #define PG8_WAIT_V(n) asm volatile("s_waitcnt vmcnt(" #n ")" ::: "memory")
; #define PG8_WAIT_L(n) asm volatile("s_waitcnt lgkmcnt(" #n ")" ::: "memory")
; #define PG8_BAR __builtin_amdgcn_s_barrier()
; #define PG8_SCHED __builtin_amdgcn_sched_barrier(0)
; template <class Epi, class Sched, bool ALIGN_EPI>
; __device__ __forceinline__ void gemm_phase(LAS unsigned char* lds, const Gemm g, const Sched& S, const Epi& E, int wave_id) {
;     ...
;             PG8_LDA(At, 1, 1); PG8_STAGE(PG8_SB(1, 0), b3, voffB); PG8_STAGE(PG8_SB(1, 1), b3 + hsB, voffB); PG8_STAGE(PG8_SA(1, 0), a3, voffA);
;             PG8_WAIT_V(8); PG8_WAIT_L(0); PG8_BAR; PG8_MMA(1, 0, At, B0); PG8_MMA(1, 1, At, B1); PG8_BAR; PG8_SCHED;
;         }
	s_mov_b32 m0, s58
	v_lshl_add_u64 v[86:87], v[202:203], 0, s[92:93]
	s_add_u32 s38, s38, 0x80080
	s_nop 1
	global_load_lds_dwordx4 v[86:87], off
	v_lshl_add_u64 v[86:87], v[204:205], 0, s[92:93]
	s_mov_b32 m0, s59
	s_addc_u32 s39, s39, 0
	global_load_lds_dwordx4 v[86:87], off
	v_lshl_add_u64 v[86:87], s[38:39], 0, v[0:1]
	s_mov_b32 m0, s62
	s_nop 0
	global_load_lds_dwordx4 v[86:87], off
	v_lshl_add_u64 v[86:87], s[38:39], 0, v[210:211]
	s_mov_b32 m0, s63
	s_nop 0
	global_load_lds_dwordx4 v[86:87], off
	v_lshl_add_u64 v[86:87], v[220:221], 0, s[92:93]
	s_mov_b32 m0, s60
	s_nop 0
	global_load_lds_dwordx4 v[86:87], off
	v_lshl_add_u64 v[86:87], v[224:225], 0, s[92:93]
	s_mov_b32 m0, s61
	s_nop 0
	global_load_lds_dwordx4 v[86:87], off
	ds_read_b128 v[66:69], v234 offset:50176
	ds_read_b128 v[70:73], v234 offset:51200
	ds_read_b128 v[82:85], v234 offset:52224
	ds_read_b128 v[94:97], v234 offset:53248
	ds_read_b128 v[186:189], v234 offset:54272
	ds_read_b128 v[190:193], v234 offset:55296
	ds_read_b128 v[194:197], v234 offset:56320
	ds_read_b128 v[198:201], v234 offset:57344
	s_waitcnt vmcnt(8)
	s_waitcnt lgkmcnt(0)
	s_barrier
	s_setprio 1
	s_waitcnt lgkmcnt(0)
	v_mfma_f32_16x16x32_bf16 v[86:89], v[50:53], v[66:69], v[102:105]
	v_mfma_f32_16x16x32_bf16 v[102:105], v[54:57], v[70:73], v[86:89]
	v_mfma_f32_16x16x32_bf16 v[86:89], v[58:61], v[66:69], v[98:101]
	v_mfma_f32_16x16x32_bf16 v[78:81], v[50:53], v[82:85], v[78:81]
	v_mfma_f32_16x16x32_bf16 v[74:77], v[58:61], v[82:85], v[74:77]
	v_mfma_f32_16x16x32_bf16 v[30:33], v[50:53], v[186:189], v[30:33]
	v_mfma_f32_16x16x32_bf16 v[26:29], v[58:61], v[186:189], v[26:29]
	v_mfma_f32_16x16x32_bf16 v[14:17], v[50:53], v[194:197], v[14:17]
	v_mfma_f32_16x16x32_bf16 v[10:13], v[58:61], v[194:197], v[10:13]
	v_mfma_f32_16x16x32_bf16 v[98:101], v[62:65], v[70:73], v[86:89]
	v_mfma_f32_16x16x32_bf16 v[78:81], v[54:57], v[94:97], v[78:81]
	v_mfma_f32_16x16x32_bf16 v[74:77], v[62:65], v[94:97], v[74:77]
	v_mfma_f32_16x16x32_bf16 v[30:33], v[54:57], v[190:193], v[30:33]
	v_mfma_f32_16x16x32_bf16 v[26:29], v[62:65], v[190:193], v[26:29]
	v_mfma_f32_16x16x32_bf16 v[14:17], v[54:57], v[198:201], v[14:17]
	v_mfma_f32_16x16x32_bf16 v[10:13], v[62:65], v[198:201], v[10:13]
	s_setprio 0
	s_setprio 1
	v_mfma_f32_16x16x32_bf16 v[34:37], v[170:173], v[66:69], v[34:37]
	v_mfma_f32_16x16x32_bf16 v[90:93], v[174:177], v[70:73], v[34:37]
	v_mfma_f32_16x16x32_bf16 v[34:37], v[178:181], v[66:69], v[38:41]
	v_mfma_f32_16x16x32_bf16 v[86:89], v[182:185], v[70:73], v[34:37]
	v_mfma_f32_16x16x32_bf16 v[34:37], v[170:173], v[82:85], v[42:45]
	v_mfma_f32_16x16x32_bf16 v[70:73], v[174:177], v[94:97], v[34:37]
	v_mfma_f32_16x16x32_bf16 v[34:37], v[178:181], v[82:85], v[46:49]
	v_mfma_f32_16x16x32_bf16 v[22:25], v[170:173], v[186:189], v[22:25]
	v_mfma_f32_16x16x32_bf16 v[18:21], v[178:181], v[186:189], v[18:21]
	v_mfma_f32_16x16x32_bf16 v[6:9], v[170:173], v[194:197], v[6:9]
	v_mfma_f32_16x16x32_bf16 v[2:5], v[178:181], v[194:197], v[2:5]
	v_mfma_f32_16x16x32_bf16 v[66:69], v[182:185], v[94:97], v[34:37]
	v_mfma_f32_16x16x32_bf16 v[22:25], v[174:177], v[190:193], v[22:25]
	v_mfma_f32_16x16x32_bf16 v[18:21], v[182:185], v[190:193], v[18:21]
	v_mfma_f32_16x16x32_bf16 v[6:9], v[174:177], v[198:201], v[6:9]
	v_mfma_f32_16x16x32_bf16 v[2:5], v[182:185], v[198:201], v[2:5]
	s_setprio 0
	s_barrier
	s_add_i32 s65, s65, 2
	s_add_u32 s29, s29, 0x100
	s_addc_u32 s33, s33, 0
	s_add_u32 s36, s36, 0x100
	s_addc_u32 s37, s37, 0
	s_cmp_gt_u32 s65, 29
	s_cbranch_scc0 .LBB0_2620
	s_and_b64 vcc, exec, s[22:23]
	s_cbranch_vccz .LBB0_2623
	s_barrier

; #define PG8_STAGE(bufoff, gbase, voff) do { _Pragma("unroll") for (int _i = 0; _i < 2; ++_i) \
;         __builtin_amdgcn_global_load_lds((const GAS unsigned*)((const GAS char*)(gbase) + (voff)[_i]), (LAS unsigned*)(lds + (bufoff) + ldsw + _i * 8192), 16, 0, 0); } while (0)
; #define PG8_LDA(dst, b, h) do { _Pragma("unroll") for (int m = 0; m < 4; ++m) _Pragma("unroll") for (int k = 0; k < 2; ++k) dst[m][k] = *(const LAS bf16x8*)(lds + PG8_SA(b, h) + aoff + m * 2048 + k * 1024); } while (0)
; #define PG8_LDB(dst, b, h) do { _Pragma("unroll") for (int n = 0; n < 2; ++n) _Pragma("unroll") for (int k = 0; k < 2; ++k) dst[n][k] = *(const LAS bf16x8*)(lds + PG8_SB(b, h) + boff + n * 2048 + k * 1024); } while (0)
; #define PG8_MMA(ai, bj, At, Bt) do { __builtin_amdgcn_s_setprio(1); _Pragma("unroll") for (int m = 0; m < 4; ++m) _Pragma("unroll") for (int n = 0; n < 2; ++n) _Pragma("unroll") for (int k = 0; k < 2; ++k) \
;         acc[ai][bj][m][n] = __builtin_amdgcn_mfma_f32_16x16x32_bf16(Bt[n][k], At[m][k], acc[ai][bj][m][n], 0, 0, 0); __builtin_amdgcn_s_setprio(0); } while (0)
; #define PG8_WAIT_V(n) asm volatile("s_waitcnt vmcnt(" #n ")" ::: "memory")
; #define PG8_WAIT_L(n) asm volatile("s_waitcnt lgkmcnt(" #n ")" ::: "memory")
; #define PG8_BAR __builtin_amdgcn_s_barrier()
; #define PG8_SCHED __builtin_amdgcn_sched_barrier(0)
; template <class Epi, class Sched, bool ALIGN_EPI>
; __device__ __forceinline__ void gemm_phase(LAS unsigned char* lds, const Gemm g, const Sched& S, const Epi& E, int wave_id) {
;     ...
;             PG8_LDB(B0, 0, 0); PG8_LDB(B1, 0, 1); PG8_SCHED; PG8_LDA(At, 0, 0); PG8_STAGE(PG8_SA(1, 1), a1 + hsA, voffA);
;             PG8_WAIT_V(8); PG8_WAIT_L(0); PG8_BAR; PG8_MMA(0, 0, At, B0); PG8_MMA(0, 1, At, B1); PG8_BAR; PG8_SCHED;
;             PG8_LDA(At, 0, 1); PG8_STAGE(PG8_SB(0, 0), b2, voffB); PG8_STAGE(PG8_SB(0, 1), b2 + hsB, voffB); PG8_STAGE(PG8_SA(0, 0), a2, voffA);
;             PG8_WAIT_V(8); PG8_WAIT_L(0); PG8_BAR; PG8_MMA(1, 0, At, B0); PG8_MMA(1, 1, At, B1); PG8_BAR; PG8_SCHED;
.LBB0_2874:
	s_add_u32 s28, s2, 0xfff80080
	s_addc_u32 s29, s3, -1
	s_cmp_eq_u32 s67, 28
	s_cselect_b32 s31, s23, s29
	s_cselect_b32 s30, s22, s28
	s_cselect_b32 s29, s21, s66
	s_cselect_b32 s28, s27, s33
	v_lshl_add_u64 v[208:209], s[2:3], 0, v[232:233]
	s_add_i32 m0, s40, 0xc400
	s_nop 0
	global_load_lds_dwordx4 v[208:209], off
	v_lshl_add_u64 v[208:209], s[2:3], 0, v[230:231]
	s_add_i32 m0, s40, 0xe400
	s_nop 0
	global_load_lds_dwordx4 v[208:209], off
	v_add_u32_e32 v82, 0x10400, v240
	ds_read_b128 v[18:21], v82
	ds_read_b128 v[88:91], v82 offset:1024
	ds_read_b128 v[108:111], v82 offset:2048
	ds_read_b128 v[112:115], v82 offset:3072
	v_add_u32_e32 v82, 0x14400, v240
	ds_read_b128 v[116:119], v82
	ds_read_b128 v[120:123], v82 offset:1024
	ds_read_b128 v[128:131], v82 offset:2048
	ds_read_b128 v[132:135], v82 offset:3072
	ds_read_b128 v[136:139], v239 offset:1024
	ds_read_b128 v[140:143], v239 offset:2048
	ds_read_b128 v[144:147], v239 offset:3072
	ds_read_b128 v[164:167], v239 offset:4096
	ds_read_b128 v[180:183], v239 offset:5120
	ds_read_b128 v[184:187], v239 offset:6144
	ds_read_b128 v[188:191], v239 offset:7168
	ds_read_b128 v[192:195], v239 offset:8192
	s_waitcnt vmcnt(8)
	s_waitcnt lgkmcnt(0)
	s_barrier
	s_setprio 1
	s_waitcnt lgkmcnt(0)
	v_mfma_f32_16x16x32_bf16 v[176:179], v[18:21], v[136:139], v[176:179]
	v_mfma_f32_16x16x32_bf16 v[30:33], v[108:111], v[136:139], v[30:33]
	v_mfma_f32_16x16x32_bf16 v[172:175], v[18:21], v[144:147], v[172:175]
	v_mfma_f32_16x16x32_bf16 v[50:53], v[108:111], v[144:147], v[50:53]
	v_mfma_f32_16x16x32_bf16 v[156:159], v[18:21], v[180:183], v[156:159]
	v_mfma_f32_16x16x32_bf16 v[78:81], v[108:111], v[180:183], v[78:81]
	v_mfma_f32_16x16x32_bf16 v[124:127], v[18:21], v[188:191], v[124:127]
	v_mfma_f32_16x16x32_bf16 v[104:107], v[108:111], v[188:191], v[104:107]
	v_mfma_f32_16x16x32_bf16 v[176:179], v[88:91], v[140:143], v[176:179]
	v_mfma_f32_16x16x32_bf16 v[30:33], v[112:115], v[140:143], v[30:33]
	v_mfma_f32_16x16x32_bf16 v[172:175], v[88:91], v[164:167], v[172:175]
	v_mfma_f32_16x16x32_bf16 v[50:53], v[112:115], v[164:167], v[50:53]
	v_mfma_f32_16x16x32_bf16 v[156:159], v[88:91], v[184:187], v[156:159]
	v_mfma_f32_16x16x32_bf16 v[78:81], v[112:115], v[184:187], v[78:81]
	v_mfma_f32_16x16x32_bf16 v[124:127], v[88:91], v[192:195], v[124:127]
	v_mfma_f32_16x16x32_bf16 v[104:107], v[112:115], v[192:195], v[104:107]
	s_setprio 0
	s_setprio 1
	v_mfma_f32_16x16x32_bf16 v[160:163], v[116:119], v[136:139], v[160:163]
	v_mfma_f32_16x16x32_bf16 v[62:65], v[128:131], v[136:139], v[62:65]
	v_mfma_f32_16x16x32_bf16 v[92:95], v[128:131], v[144:147], v[92:95]
	v_mfma_f32_16x16x32_bf16 v[100:103], v[116:119], v[188:191], v[100:103]
	v_mfma_f32_16x16x32_bf16 v[96:99], v[128:131], v[188:191], v[96:99]
	v_mfma_f32_16x16x32_bf16 v[160:163], v[120:123], v[140:143], v[160:163]
	v_mfma_f32_16x16x32_bf16 v[62:65], v[132:135], v[140:143], v[62:65]
	v_mfma_f32_16x16x32_bf16 v[136:139], v[116:119], v[144:147], v[168:171]
	v_mfma_f32_16x16x32_bf16 v[92:95], v[132:135], v[164:167], v[92:95]
	v_mfma_f32_16x16x32_bf16 v[140:143], v[116:119], v[180:183], v[152:155]
	v_mfma_f32_16x16x32_bf16 v[144:147], v[128:131], v[180:183], v[148:151]
	v_mfma_f32_16x16x32_bf16 v[100:103], v[120:123], v[192:195], v[100:103]
	v_mfma_f32_16x16x32_bf16 v[96:99], v[132:135], v[192:195], v[96:99]
	v_mfma_f32_16x16x32_bf16 v[136:139], v[120:123], v[164:167], v[136:139]
	v_mfma_f32_16x16x32_bf16 v[140:143], v[120:123], v[184:187], v[140:143]
	v_mfma_f32_16x16x32_bf16 v[144:147], v[132:135], v[184:187], v[144:147]
	s_setprio 0
	s_barrier
	s_mov_b32 m0, s41
	v_lshl_add_u64 v[200:201], s[28:29], 0, v[0:1]
	s_add_u32 s68, s28, 0x80000
	global_load_lds_dwordx4 v[200:201], off
	v_lshl_add_u64 v[202:203], s[28:29], 0, v[228:229]
	s_mov_b32 m0, s42
	s_addc_u32 s69, s29, 0
	global_load_lds_dwordx4 v[202:203], off
	v_lshl_add_u64 v[82:83], s[68:69], 0, v[0:1]
	s_mov_b32 m0, s43
	v_lshl_add_u64 v[204:205], s[30:31], 0, v[224:225]
	global_load_lds_dwordx4 v[82:83], off
	v_lshl_add_u64 v[82:83], s[68:69], 0, v[228:229]
	s_mov_b32 m0, s44
	v_lshl_add_u64 v[206:207], s[30:31], 0, v[226:227]
	global_load_lds_dwordx4 v[82:83], off
	s_mov_b32 m0, s45
	s_nop 0
	global_load_lds_dwordx4 v[204:205], off
	s_mov_b32 m0, s46
	s_nop 0
	global_load_lds_dwordx4 v[206:207], off
	ds_read_b128 v[148:151], v239 offset:17408
	ds_read_b128 v[152:155], v239 offset:18432
	ds_read_b128 v[164:167], v239 offset:19456
	ds_read_b128 v[168:171], v239 offset:20480
	ds_read_b128 v[180:183], v239 offset:21504
	ds_read_b128 v[184:187], v239 offset:22528
	ds_read_b128 v[188:191], v239 offset:23552
	ds_read_b128 v[192:195], v239 offset:24576
	s_waitcnt vmcnt(8)
	s_waitcnt lgkmcnt(0)
	s_barrier
; #define PG8_STAGE(bufoff, gbase, voff) do { _Pragma("unroll") for (int _i = 0; _i < 2; ++_i) \
;         __builtin_amdgcn_global_load_lds((const GAS unsigned*)((const GAS char*)(gbase) + (voff)[_i]), (LAS unsigned*)(lds + (bufoff) + ldsw + _i * 8192), 16, 0, 0); } while (0)
; #define PG8_LDA(dst, b, h) do { _Pragma("unroll") for (int m = 0; m < 4; ++m) _Pragma("unroll") for (int k = 0; k < 2; ++k) dst[m][k] = *(const LAS bf16x8*)(lds + PG8_SA(b, h) + aoff + m * 2048 + k * 1024); } while (0)
; #define PG8_LDB(dst, b, h) do { _Pragma("unroll") for (int n = 0; n < 2; ++n) _Pragma("unroll") for (int k = 0; k < 2; ++k) dst[n][k] = *(const LAS bf16x8*)(lds + PG8_SB(b, h) + boff + n * 2048 + k * 1024); } while (0)
; #define PG8_MMA(ai, bj, At, Bt) do { __builtin_amdgcn_s_setprio(1); _Pragma("unroll") for (int m = 0; m < 4; ++m) _Pragma("unroll") for (int n = 0; n < 2; ++n) _Pragma("unroll") for (int k = 0; k < 2; ++k) \
;         acc[ai][bj][m][n] = __builtin_amdgcn_mfma_f32_16x16x32_bf16(Bt[n][k], At[m][k], acc[ai][bj][m][n], 0, 0, 0); __builtin_amdgcn_s_setprio(0); } while (0)
; #define PG8_WAIT_V(n) asm volatile("s_waitcnt vmcnt(" #n ")" ::: "memory")
; #define PG8_WAIT_L(n) asm volatile("s_waitcnt lgkmcnt(" #n ")" ::: "memory")
; #define PG8_BAR __builtin_amdgcn_s_barrier()
; #define PG8_SCHED __builtin_amdgcn_sched_barrier(0)
; template <class Epi, class Sched, bool ALIGN_EPI>
; __device__ __forceinline__ void gemm_phase(LAS unsigned char* lds, const Gemm g, const Sched& S, const Epi& E, int wave_id) {
;     ...
;             PG8_WAIT_V(8); PG8_WAIT_L(0); PG8_BAR; PG8_MMA(1, 0, At, B0); PG8_MMA(1, 1, At, B1); PG8_BAR; PG8_SCHED;
;             PG8_LDB(B0, 1, 0); PG8_LDB(B1, 1, 1); PG8_SCHED; PG8_LDA(At, 1, 0); PG8_STAGE(PG8_SA(0, 1), a2 + hsA, voffA);
;             PG8_WAIT_V(8); PG8_WAIT_L(0); PG8_BAR; PG8_MMA(0, 0, At, B0); PG8_MMA(0, 1, At, B1); PG8_BAR; PG8_SCHED;
	s_setprio 1
	s_waitcnt lgkmcnt(0)
	v_mfma_f32_16x16x32_bf16 v[82:85], v[18:21], v[148:151], v[84:87]
	v_mfma_f32_16x16x32_bf16 v[70:73], v[108:111], v[148:151], v[70:73]
	v_mfma_f32_16x16x32_bf16 v[58:61], v[18:21], v[164:167], v[58:61]
	v_mfma_f32_16x16x32_bf16 v[54:57], v[108:111], v[164:167], v[54:57]
	v_mfma_f32_16x16x32_bf16 v[38:41], v[18:21], v[180:183], v[38:41]
	v_mfma_f32_16x16x32_bf16 v[34:37], v[108:111], v[180:183], v[34:37]
	v_mfma_f32_16x16x32_bf16 v[14:17], v[18:21], v[188:191], v[14:17]
	v_mfma_f32_16x16x32_bf16 v[10:13], v[108:111], v[188:191], v[10:13]
	v_mfma_f32_16x16x32_bf16 v[82:85], v[88:91], v[152:155], v[82:85]
	v_mfma_f32_16x16x32_bf16 v[70:73], v[112:115], v[152:155], v[70:73]
	v_mfma_f32_16x16x32_bf16 v[58:61], v[88:91], v[168:171], v[58:61]
	v_mfma_f32_16x16x32_bf16 v[54:57], v[112:115], v[168:171], v[54:57]
	v_mfma_f32_16x16x32_bf16 v[38:41], v[88:91], v[184:187], v[38:41]
	v_mfma_f32_16x16x32_bf16 v[34:37], v[112:115], v[184:187], v[34:37]
	v_mfma_f32_16x16x32_bf16 v[14:17], v[88:91], v[192:195], v[14:17]
	v_mfma_f32_16x16x32_bf16 v[10:13], v[112:115], v[192:195], v[10:13]
	s_setprio 0
	s_setprio 1
	v_mfma_f32_16x16x32_bf16 v[66:69], v[128:131], v[148:151], v[66:69]
	v_mfma_f32_16x16x32_bf16 v[46:49], v[116:119], v[164:167], v[46:49]
	v_mfma_f32_16x16x32_bf16 v[42:45], v[128:131], v[164:167], v[42:45]
	v_mfma_f32_16x16x32_bf16 v[26:29], v[116:119], v[180:183], v[26:29]
	v_mfma_f32_16x16x32_bf16 v[22:25], v[128:131], v[180:183], v[22:25]
	v_mfma_f32_16x16x32_bf16 v[6:9], v[116:119], v[188:191], v[6:9]
	v_mfma_f32_16x16x32_bf16 v[2:5], v[128:131], v[188:191], v[2:5]
	v_mfma_f32_16x16x32_bf16 v[18:21], v[116:119], v[148:151], v[74:77]
	v_mfma_f32_16x16x32_bf16 v[66:69], v[132:135], v[152:155], v[66:69]
	v_mfma_f32_16x16x32_bf16 v[46:49], v[120:123], v[168:171], v[46:49]
	v_mfma_f32_16x16x32_bf16 v[42:45], v[132:135], v[168:171], v[42:45]
	v_mfma_f32_16x16x32_bf16 v[26:29], v[120:123], v[184:187], v[26:29]
	v_mfma_f32_16x16x32_bf16 v[22:25], v[132:135], v[184:187], v[22:25]
	v_mfma_f32_16x16x32_bf16 v[6:9], v[120:123], v[192:195], v[6:9]
	v_mfma_f32_16x16x32_bf16 v[2:5], v[132:135], v[192:195], v[2:5]
	v_mfma_f32_16x16x32_bf16 v[18:21], v[120:123], v[152:155], v[18:21]
	s_setprio 0
	s_barrier
	s_add_u32 s30, s30, 0x80000
	s_addc_u32 s31, s31, 0
	s_mov_b32 m0, s47
	v_lshl_add_u64 v[210:211], s[30:31], 0, v[224:225]
	global_load_lds_dwordx4 v[210:211], off
	v_lshl_add_u64 v[210:211], s[30:31], 0, v[226:227]
	s_mov_b32 m0, s48
	s_nop 0
	global_load_lds_dwordx4 v[210:211], off
	v_add_u32_e32 v86, 0x18400, v240
	ds_read_b128 v[74:77], v86
	ds_read_b128 v[88:91], v86 offset:1024
	ds_read_b128 v[108:111], v86 offset:2048
	ds_read_b128 v[112:115], v86 offset:3072
	v_add_u32_e32 v86, 0x1c400, v240
	ds_read_b128 v[116:119], v86
	ds_read_b128 v[120:123], v86 offset:1024
	ds_read_b128 v[128:131], v86 offset:2048
	ds_read_b128 v[132:135], v86 offset:3072
	ds_read_b128 v[148:151], v239 offset:33792
	ds_read_b128 v[152:155], v239 offset:34816
	ds_read_b128 v[164:167], v239 offset:35840
	ds_read_b128 v[180:183], v239 offset:36864
	ds_read_b128 v[184:187], v239 offset:37888
	ds_read_b128 v[188:191], v239 offset:38912
	ds_read_b128 v[192:195], v239 offset:39936
	ds_read_b128 v[196:199], v239 offset:40960
	s_waitcnt vmcnt(8)
	s_waitcnt lgkmcnt(0)
	s_barrier
	s_setprio 1
	s_waitcnt lgkmcnt(0)
	v_mfma_f32_16x16x32_bf16 v[168:171], v[74:77], v[148:151], v[176:179]
	v_mfma_f32_16x16x32_bf16 v[176:179], v[88:91], v[152:155], v[168:171]
	v_mfma_f32_16x16x32_bf16 v[30:33], v[108:111], v[148:151], v[30:33]
	v_mfma_f32_16x16x32_bf16 v[168:171], v[74:77], v[164:167], v[172:175]
	v_mfma_f32_16x16x32_bf16 v[50:53], v[108:111], v[164:167], v[50:53]
	v_mfma_f32_16x16x32_bf16 v[156:159], v[74:77], v[184:187], v[156:159]
	v_mfma_f32_16x16x32_bf16 v[78:81], v[108:111], v[184:187], v[78:81]
	v_mfma_f32_16x16x32_bf16 v[124:127], v[74:77], v[192:195], v[124:127]
	v_mfma_f32_16x16x32_bf16 v[104:107], v[108:111], v[192:195], v[104:107]
	v_mfma_f32_16x16x32_bf16 v[30:33], v[112:115], v[152:155], v[30:33]
	v_mfma_f32_16x16x32_bf16 v[172:175], v[88:91], v[180:183], v[168:171]
	v_mfma_f32_16x16x32_bf16 v[50:53], v[112:115], v[180:183], v[50:53]
	v_mfma_f32_16x16x32_bf16 v[156:159], v[88:91], v[188:191], v[156:159]
	v_mfma_f32_16x16x32_bf16 v[78:81], v[112:115], v[188:191], v[78:81]
	v_mfma_f32_16x16x32_bf16 v[124:127], v[88:91], v[196:199], v[124:127]
	v_mfma_f32_16x16x32_bf16 v[104:107], v[112:115], v[196:199], v[104:107]
	s_setprio 0
	s_setprio 1
	v_mfma_f32_16x16x32_bf16 v[136:139], v[116:119], v[164:167], v[136:139]
	v_mfma_f32_16x16x32_bf16 v[160:163], v[116:119], v[148:151], v[160:163]
	v_mfma_f32_16x16x32_bf16 v[62:65], v[128:131], v[148:151], v[62:65]
	v_mfma_f32_16x16x32_bf16 v[168:171], v[120:123], v[180:183], v[136:139]
	v_mfma_f32_16x16x32_bf16 v[136:139], v[116:119], v[184:187], v[140:143]
	v_mfma_f32_16x16x32_bf16 v[160:163], v[120:123], v[152:155], v[160:163]
	v_mfma_f32_16x16x32_bf16 v[62:65], v[132:135], v[152:155], v[62:65]
	v_mfma_f32_16x16x32_bf16 v[92:95], v[128:131], v[164:167], v[92:95]
	v_mfma_f32_16x16x32_bf16 v[152:155], v[120:123], v[188:191], v[136:139]
	v_mfma_f32_16x16x32_bf16 v[136:139], v[128:131], v[184:187], v[144:147]
	v_mfma_f32_16x16x32_bf16 v[100:103], v[116:119], v[192:195], v[100:103]
	v_mfma_f32_16x16x32_bf16 v[96:99], v[128:131], v[192:195], v[96:99]
	v_mfma_f32_16x16x32_bf16 v[92:95], v[132:135], v[180:183], v[92:95]
	v_mfma_f32_16x16x32_bf16 v[148:151], v[132:135], v[188:191], v[136:139]
	v_mfma_f32_16x16x32_bf16 v[100:103], v[120:123], v[196:199], v[100:103]
	v_mfma_f32_16x16x32_bf16 v[96:99], v[132:135], v[196:199], v[96:99]
	s_setprio 0
	s_barrier
; #define PG8_STAGE(bufoff, gbase, voff) do { _Pragma("unroll") for (int _i = 0; _i < 2; ++_i) \
;         __builtin_amdgcn_global_load_lds((const GAS unsigned*)((const GAS char*)(gbase) + (voff)[_i]), (LAS unsigned*)(lds + (bufoff) + ldsw + _i * 8192), 16, 0, 0); } while (0)
; #define PG8_LDA(dst, b, h) do { _Pragma("unroll") for (int m = 0; m < 4; ++m) _Pragma("unroll") for (int k = 0; k < 2; ++k) dst[m][k] = *(const LAS bf16x8*)(lds + PG8_SA(b, h) + aoff + m * 2048 + k * 1024); } while (0)
; #define PG8_MMA(ai, bj, At, Bt) do { __builtin_amdgcn_s_setprio(1); _Pragma("unroll") for (int m = 0; m < 4; ++m) _Pragma("unroll") for (int n = 0; n < 2; ++n) _Pragma("unroll") for (int k = 0; k < 2; ++k) \
;         acc[ai][bj][m][n] = __builtin_amdgcn_mfma_f32_16x16x32_bf16(Bt[n][k], At[m][k], acc[ai][bj][m][n], 0, 0, 0); __builtin_amdgcn_s_setprio(0); } while (0)
; #define PG8_WAIT_V(n) asm volatile("s_waitcnt vmcnt(" #n ")" ::: "memory")
; #define PG8_WAIT_L(n) asm volatile("s_waitcnt lgkmcnt(" #n ")" ::: "memory")
; #define PG8_BAR __builtin_amdgcn_s_barrier()
; #define PG8_SCHED __builtin_amdgcn_sched_barrier(0)
; template <class Epi, class Sched, bool ALIGN_EPI>
; __device__ __forceinline__ void gemm_phase(LAS unsigned char* lds, const Gemm g, const Sched& S, const Epi& E, int wave_id) {
;     ...
;             PG8_LDA(At, 1, 1); PG8_STAGE(PG8_SB(1, 0), b3, voffB); PG8_STAGE(PG8_SB(1, 1), b3 + hsB, voffB); PG8_STAGE(PG8_SA(1, 0), a3, voffA);
;             PG8_WAIT_V(8); PG8_WAIT_L(0); PG8_BAR; PG8_MMA(1, 0, At, B0); PG8_MMA(1, 1, At, B1); PG8_BAR; PG8_SCHED;
;         }
	s_mov_b32 m0, s52
	v_lshl_add_u64 v[86:87], v[200:201], 0, s[92:93]
	s_add_u32 s28, s28, 0x80080
	global_load_lds_dwordx4 v[86:87], off
	v_lshl_add_u64 v[86:87], v[202:203], 0, s[92:93]
	s_mov_b32 m0, s53
	s_addc_u32 s29, s29, 0
	global_load_lds_dwordx4 v[86:87], off
	v_lshl_add_u64 v[86:87], s[28:29], 0, v[0:1]
	s_mov_b32 m0, s56
	s_nop 0
	global_load_lds_dwordx4 v[86:87], off
	v_lshl_add_u64 v[86:87], s[28:29], 0, v[228:229]
	s_mov_b32 m0, s57
	s_nop 0
	global_load_lds_dwordx4 v[86:87], off
	v_lshl_add_u64 v[86:87], v[204:205], 0, s[92:93]
	s_mov_b32 m0, s54
	s_nop 0
	global_load_lds_dwordx4 v[86:87], off
	v_lshl_add_u64 v[86:87], v[206:207], 0, s[92:93]
	s_mov_b32 m0, s55
	s_nop 0
	global_load_lds_dwordx4 v[86:87], off
	ds_read_b128 v[136:139], v239 offset:50176
	ds_read_b128 v[140:143], v239 offset:51200
	ds_read_b128 v[144:147], v239 offset:52224
	ds_read_b128 v[164:167], v239 offset:53248
	ds_read_b128 v[180:183], v239 offset:54272
	ds_read_b128 v[184:187], v239 offset:55296
	ds_read_b128 v[188:191], v239 offset:56320
	ds_read_b128 v[192:195], v239 offset:57344
	s_waitcnt vmcnt(8)
	s_waitcnt lgkmcnt(0)
	s_barrier
	s_setprio 1
	s_waitcnt lgkmcnt(0)
	v_mfma_f32_16x16x32_bf16 v[82:85], v[74:77], v[136:139], v[82:85]
	v_mfma_f32_16x16x32_bf16 v[70:73], v[108:111], v[136:139], v[70:73]
	v_mfma_f32_16x16x32_bf16 v[58:61], v[74:77], v[144:147], v[58:61]
	v_mfma_f32_16x16x32_bf16 v[54:57], v[108:111], v[144:147], v[54:57]
	v_mfma_f32_16x16x32_bf16 v[38:41], v[74:77], v[180:183], v[38:41]
	v_mfma_f32_16x16x32_bf16 v[34:37], v[108:111], v[180:183], v[34:37]
	v_mfma_f32_16x16x32_bf16 v[14:17], v[74:77], v[188:191], v[14:17]
	v_mfma_f32_16x16x32_bf16 v[10:13], v[108:111], v[188:191], v[10:13]
	v_mfma_f32_16x16x32_bf16 v[84:87], v[88:91], v[140:143], v[82:85]
	v_mfma_f32_16x16x32_bf16 v[70:73], v[112:115], v[140:143], v[70:73]
	v_mfma_f32_16x16x32_bf16 v[58:61], v[88:91], v[164:167], v[58:61]
	v_mfma_f32_16x16x32_bf16 v[54:57], v[112:115], v[164:167], v[54:57]
	v_mfma_f32_16x16x32_bf16 v[38:41], v[88:91], v[184:187], v[38:41]
	v_mfma_f32_16x16x32_bf16 v[34:37], v[112:115], v[184:187], v[34:37]
	v_mfma_f32_16x16x32_bf16 v[14:17], v[88:91], v[192:195], v[14:17]
	v_mfma_f32_16x16x32_bf16 v[10:13], v[112:115], v[192:195], v[10:13]
	s_setprio 0
	s_setprio 1
	v_mfma_f32_16x16x32_bf16 v[18:21], v[116:119], v[136:139], v[18:21]
	v_mfma_f32_16x16x32_bf16 v[74:77], v[120:123], v[140:143], v[18:21]
	v_mfma_f32_16x16x32_bf16 v[18:21], v[128:131], v[136:139], v[66:69]
	v_mfma_f32_16x16x32_bf16 v[66:69], v[132:135], v[140:143], v[18:21]
	v_mfma_f32_16x16x32_bf16 v[18:21], v[116:119], v[144:147], v[46:49]
	v_mfma_f32_16x16x32_bf16 v[46:49], v[120:123], v[164:167], v[18:21]
	v_mfma_f32_16x16x32_bf16 v[18:21], v[128:131], v[144:147], v[42:45]
	v_mfma_f32_16x16x32_bf16 v[42:45], v[132:135], v[164:167], v[18:21]
	v_mfma_f32_16x16x32_bf16 v[18:21], v[116:119], v[180:183], v[26:29]
	v_mfma_f32_16x16x32_bf16 v[26:29], v[120:123], v[184:187], v[18:21]
	v_mfma_f32_16x16x32_bf16 v[18:21], v[128:131], v[180:183], v[22:25]
	v_mfma_f32_16x16x32_bf16 v[6:9], v[116:119], v[188:191], v[6:9]
	v_mfma_f32_16x16x32_bf16 v[2:5], v[128:131], v[188:191], v[2:5]
	v_mfma_f32_16x16x32_bf16 v[22:25], v[132:135], v[184:187], v[18:21]
	v_mfma_f32_16x16x32_bf16 v[6:9], v[120:123], v[192:195], v[6:9]
	v_mfma_f32_16x16x32_bf16 v[2:5], v[132:135], v[192:195], v[2:5]
	s_setprio 0
	s_barrier
	s_add_i32 s67, s67, 2
	s_add_u32 s33, s33, 0x100
	s_addc_u32 s66, s66, 0
	s_add_u32 s2, s2, 0x100
	s_addc_u32 s3, s3, 0
	s_cmp_gt_u32 s67, 29
	s_cbranch_scc0 .LBB0_2874
	s_and_b64 vcc, exec, s[16:17]
	s_cbranch_vccz .LBB0_2877
	s_barrier

; #define PG8_STAGE(bufoff, gbase, voff) do { _Pragma("unroll") for (int _i = 0; _i < 2; ++_i) \
;         __builtin_amdgcn_global_load_lds((const GAS unsigned*)((const GAS char*)(gbase) + (voff)[_i]), (LAS unsigned*)(lds + (bufoff) + ldsw + _i * 8192), 16, 0, 0); } while (0)
; #define PG8_LDA(dst, b, h) do { _Pragma("unroll") for (int m = 0; m < 4; ++m) _Pragma("unroll") for (int k = 0; k < 2; ++k) dst[m][k] = *(const LAS bf16x8*)(lds + PG8_SA(b, h) + aoff + m * 2048 + k * 1024); } while (0)
; #define PG8_LDB(dst, b, h) do { _Pragma("unroll") for (int n = 0; n < 2; ++n) _Pragma("unroll") for (int k = 0; k < 2; ++k) dst[n][k] = *(const LAS bf16x8*)(lds + PG8_SB(b, h) + boff + n * 2048 + k * 1024); } while (0)
; #define PG8_MMA(ai, bj, At, Bt) do { __builtin_amdgcn_s_setprio(1); _Pragma("unroll") for (int m = 0; m < 4; ++m) _Pragma("unroll") for (int n = 0; n < 2; ++n) _Pragma("unroll") for (int k = 0; k < 2; ++k) \
;         acc[ai][bj][m][n] = __builtin_amdgcn_mfma_f32_16x16x32_bf16(Bt[n][k], At[m][k], acc[ai][bj][m][n], 0, 0, 0); __builtin_amdgcn_s_setprio(0); } while (0)
; #define PG8_WAIT_V(n) asm volatile("s_waitcnt vmcnt(" #n ")" ::: "memory")
; #define PG8_WAIT_L(n) asm volatile("s_waitcnt lgkmcnt(" #n ")" ::: "memory")
; #define PG8_BAR __builtin_amdgcn_s_barrier()
; #define PG8_SCHED __builtin_amdgcn_sched_barrier(0)
; template <class Epi, class Sched, bool ALIGN_EPI>
; __device__ __forceinline__ void gemm_phase(LAS unsigned char* lds, const Gemm g, const Sched& S, const Epi& E, int wave_id) {
;     ...
;             PG8_LDB(B0, 0, 0); PG8_LDB(B1, 0, 1); PG8_SCHED; PG8_LDA(At, 0, 0); PG8_STAGE(PG8_SA(1, 1), a1 + hsA, voffA);
;             PG8_WAIT_V(8); PG8_WAIT_L(0); PG8_BAR; PG8_MMA(0, 0, At, B0); PG8_MMA(0, 1, At, B1); PG8_BAR; PG8_SCHED;
;             PG8_LDA(At, 0, 1); PG8_STAGE(PG8_SB(0, 0), b2, voffB); PG8_STAGE(PG8_SB(0, 1), b2 + hsB, voffB); PG8_STAGE(PG8_SA(0, 0), a2, voffA);
;             PG8_WAIT_V(8); PG8_WAIT_L(0); PG8_BAR; PG8_MMA(1, 0, At, B0); PG8_MMA(1, 1, At, B1); PG8_BAR; PG8_SCHED;
.LBB0_3681:
	s_add_u32 s0, s28, 0x100
	s_addc_u32 s1, s29, 0
	s_cmpk_eq_i32 s63, 0x54
	s_cselect_b32 s35, s25, s1
	s_cselect_b32 s34, s24, s0
	s_cselect_b32 s31, s27, s62
	s_cselect_b32 s30, s26, s61
	v_lshl_add_u64 v[204:205], s[28:29], 0, v[190:191]
	s_add_i32 m0, s41, 0xc400
	s_nop 0
	global_load_lds_dwordx4 v[204:205], off
	v_lshl_add_u64 v[204:205], s[28:29], 0, v[188:189]
	s_add_i32 m0, s41, 0xe400
	s_nop 0
	global_load_lds_dwordx4 v[204:205], off
	v_add_u32_e32 v46, 0x10400, v208
	v_add_u32_e32 v62, 0x14400, v208
	ds_read_b128 v[34:37], v46
	ds_read_b128 v[38:41], v46 offset:1024
	ds_read_b128 v[42:45], v46 offset:2048
	ds_read_b128 v[46:49], v46 offset:3072
	ds_read_b128 v[50:53], v62
	ds_read_b128 v[54:57], v62 offset:1024
	ds_read_b128 v[58:61], v62 offset:2048
	ds_read_b128 v[62:65], v62 offset:3072
	ds_read_b128 v[162:165], v207 offset:1024
	ds_read_b128 v[166:169], v207 offset:2048
	ds_read_b128 v[170:173], v207 offset:3072
	ds_read_b128 v[174:177], v207 offset:4096
	ds_read_b128 v[178:181], v207 offset:5120
	ds_read_b128 v[192:195], v207 offset:6144
	ds_read_b128 v[196:199], v207 offset:7168
	ds_read_b128 v[200:203], v207 offset:8192
	s_waitcnt vmcnt(8)
	s_waitcnt lgkmcnt(0)
	s_barrier
	s_setprio 1
	s_waitcnt lgkmcnt(0)
	v_mfma_f32_16x16x32_bf16 v[158:161], v[34:37], v[162:165], v[158:161]
	v_mfma_f32_16x16x32_bf16 v[154:157], v[42:45], v[162:165], v[154:157]
	v_mfma_f32_16x16x32_bf16 v[142:145], v[34:37], v[170:173], v[142:145]
	v_mfma_f32_16x16x32_bf16 v[138:141], v[42:45], v[170:173], v[138:141]
	v_mfma_f32_16x16x32_bf16 v[126:129], v[34:37], v[178:181], v[126:129]
	v_mfma_f32_16x16x32_bf16 v[122:125], v[42:45], v[178:181], v[122:125]
	v_mfma_f32_16x16x32_bf16 v[110:113], v[34:37], v[196:199], v[110:113]
	v_mfma_f32_16x16x32_bf16 v[106:109], v[42:45], v[196:199], v[106:109]
	v_mfma_f32_16x16x32_bf16 v[158:161], v[38:41], v[166:169], v[158:161]
	v_mfma_f32_16x16x32_bf16 v[154:157], v[46:49], v[166:169], v[154:157]
	v_mfma_f32_16x16x32_bf16 v[142:145], v[38:41], v[174:177], v[142:145]
	v_mfma_f32_16x16x32_bf16 v[138:141], v[46:49], v[174:177], v[138:141]
	v_mfma_f32_16x16x32_bf16 v[126:129], v[38:41], v[192:195], v[126:129]
	v_mfma_f32_16x16x32_bf16 v[122:125], v[46:49], v[192:195], v[122:125]
	v_mfma_f32_16x16x32_bf16 v[110:113], v[38:41], v[200:203], v[110:113]
	v_mfma_f32_16x16x32_bf16 v[106:109], v[46:49], v[200:203], v[106:109]
	s_setprio 0
	s_setprio 1
	v_mfma_f32_16x16x32_bf16 v[150:153], v[50:53], v[162:165], v[150:153]
	v_mfma_f32_16x16x32_bf16 v[146:149], v[58:61], v[162:165], v[146:149]
	v_mfma_f32_16x16x32_bf16 v[134:137], v[50:53], v[170:173], v[134:137]
	v_mfma_f32_16x16x32_bf16 v[130:133], v[58:61], v[170:173], v[130:133]
	v_mfma_f32_16x16x32_bf16 v[118:121], v[50:53], v[178:181], v[118:121]
	v_mfma_f32_16x16x32_bf16 v[114:117], v[58:61], v[178:181], v[114:117]
	v_mfma_f32_16x16x32_bf16 v[102:105], v[50:53], v[196:199], v[102:105]
	v_mfma_f32_16x16x32_bf16 v[98:101], v[58:61], v[196:199], v[98:101]
	v_mfma_f32_16x16x32_bf16 v[150:153], v[54:57], v[166:169], v[150:153]
	v_mfma_f32_16x16x32_bf16 v[146:149], v[62:65], v[166:169], v[146:149]
	v_mfma_f32_16x16x32_bf16 v[134:137], v[54:57], v[174:177], v[134:137]
	v_mfma_f32_16x16x32_bf16 v[130:133], v[62:65], v[174:177], v[130:133]
	v_mfma_f32_16x16x32_bf16 v[118:121], v[54:57], v[192:195], v[118:121]
	v_mfma_f32_16x16x32_bf16 v[114:117], v[62:65], v[192:195], v[114:117]
	v_mfma_f32_16x16x32_bf16 v[102:105], v[54:57], v[200:203], v[102:105]
	v_mfma_f32_16x16x32_bf16 v[98:101], v[62:65], v[200:203], v[98:101]
	s_setprio 0
	s_barrier
	s_mov_b32 m0, s42
	v_lshl_add_u64 v[204:205], s[30:31], 0, v[0:1]
	s_add_u32 s28, s30, 0x160000
	global_load_lds_dwordx4 v[204:205], off
	v_lshl_add_u64 v[218:219], s[30:31], 0, v[186:187]
	s_mov_b32 m0, s43
	s_addc_u32 s29, s31, 0
	global_load_lds_dwordx4 v[218:219], off
	v_lshl_add_u64 v[210:211], s[28:29], 0, v[0:1]
	s_mov_b32 m0, s44
	v_lshl_add_u64 v[220:221], s[34:35], 0, v[182:183]
	global_load_lds_dwordx4 v[210:211], off
	v_lshl_add_u64 v[210:211], s[28:29], 0, v[186:187]
	s_mov_b32 m0, s45
	v_lshl_add_u64 v[224:225], s[34:35], 0, v[184:185]
	global_load_lds_dwordx4 v[210:211], off
	s_mov_b32 m0, s46
	s_nop 0
	global_load_lds_dwordx4 v[220:221], off
	s_mov_b32 m0, s47
	s_nop 0
	global_load_lds_dwordx4 v[224:225], off
	ds_read_b128 v[162:165], v207 offset:17408
	ds_read_b128 v[166:169], v207 offset:18432
	ds_read_b128 v[170:173], v207 offset:19456
	ds_read_b128 v[174:177], v207 offset:20480
	ds_read_b128 v[178:181], v207 offset:21504
	ds_read_b128 v[192:195], v207 offset:22528
	ds_read_b128 v[196:199], v207 offset:23552
	ds_read_b128 v[200:203], v207 offset:24576
	s_waitcnt vmcnt(8)
	s_waitcnt lgkmcnt(0)
	s_barrier
; #define PG8_STAGE(bufoff, gbase, voff) do { _Pragma("unroll") for (int _i = 0; _i < 2; ++_i) \
;         __builtin_amdgcn_global_load_lds((const GAS unsigned*)((const GAS char*)(gbase) + (voff)[_i]), (LAS unsigned*)(lds + (bufoff) + ldsw + _i * 8192), 16, 0, 0); } while (0)
; #define PG8_LDA(dst, b, h) do { _Pragma("unroll") for (int m = 0; m < 4; ++m) _Pragma("unroll") for (int k = 0; k < 2; ++k) dst[m][k] = *(const LAS bf16x8*)(lds + PG8_SA(b, h) + aoff + m * 2048 + k * 1024); } while (0)
; #define PG8_LDB(dst, b, h) do { _Pragma("unroll") for (int n = 0; n < 2; ++n) _Pragma("unroll") for (int k = 0; k < 2; ++k) dst[n][k] = *(const LAS bf16x8*)(lds + PG8_SB(b, h) + boff + n * 2048 + k * 1024); } while (0)
; #define PG8_MMA(ai, bj, At, Bt) do { __builtin_amdgcn_s_setprio(1); _Pragma("unroll") for (int m = 0; m < 4; ++m) _Pragma("unroll") for (int n = 0; n < 2; ++n) _Pragma("unroll") for (int k = 0; k < 2; ++k) \
;         acc[ai][bj][m][n] = __builtin_amdgcn_mfma_f32_16x16x32_bf16(Bt[n][k], At[m][k], acc[ai][bj][m][n], 0, 0, 0); __builtin_amdgcn_s_setprio(0); } while (0)
; #define PG8_WAIT_V(n) asm volatile("s_waitcnt vmcnt(" #n ")" ::: "memory")
; #define PG8_WAIT_L(n) asm volatile("s_waitcnt lgkmcnt(" #n ")" ::: "memory")
; #define PG8_BAR __builtin_amdgcn_s_barrier()
; #define PG8_SCHED __builtin_amdgcn_sched_barrier(0)
; template <class Epi, class Sched, bool ALIGN_EPI>
; __device__ __forceinline__ void gemm_phase(LAS unsigned char* lds, const Gemm g, const Sched& S, const Epi& E, int wave_id) {
;     ...
;             PG8_WAIT_V(8); PG8_WAIT_L(0); PG8_BAR; PG8_MMA(1, 0, At, B0); PG8_MMA(1, 1, At, B1); PG8_BAR; PG8_SCHED;
;             PG8_LDB(B0, 1, 0); PG8_LDB(B1, 1, 1); PG8_SCHED; PG8_LDA(At, 1, 0); PG8_STAGE(PG8_SA(0, 1), a2 + hsA, voffA);
;             PG8_WAIT_V(8); PG8_WAIT_L(0); PG8_BAR; PG8_MMA(0, 0, At, B0); PG8_MMA(0, 1, At, B1); PG8_BAR; PG8_SCHED;
	s_setprio 1
	s_waitcnt lgkmcnt(0)
	v_mfma_f32_16x16x32_bf16 v[94:97], v[34:37], v[162:165], v[94:97]
	v_mfma_f32_16x16x32_bf16 v[90:93], v[42:45], v[162:165], v[90:93]
	v_mfma_f32_16x16x32_bf16 v[78:81], v[34:37], v[170:173], v[78:81]
	v_mfma_f32_16x16x32_bf16 v[74:77], v[42:45], v[170:173], v[74:77]
	v_mfma_f32_16x16x32_bf16 v[30:33], v[34:37], v[178:181], v[30:33]
	v_mfma_f32_16x16x32_bf16 v[26:29], v[42:45], v[178:181], v[26:29]
	v_mfma_f32_16x16x32_bf16 v[14:17], v[34:37], v[196:199], v[14:17]
	v_mfma_f32_16x16x32_bf16 v[10:13], v[42:45], v[196:199], v[10:13]
	v_mfma_f32_16x16x32_bf16 v[94:97], v[38:41], v[166:169], v[94:97]
	v_mfma_f32_16x16x32_bf16 v[90:93], v[46:49], v[166:169], v[90:93]
	v_mfma_f32_16x16x32_bf16 v[78:81], v[38:41], v[174:177], v[78:81]
	v_mfma_f32_16x16x32_bf16 v[74:77], v[46:49], v[174:177], v[74:77]
	v_mfma_f32_16x16x32_bf16 v[30:33], v[38:41], v[192:195], v[30:33]
	v_mfma_f32_16x16x32_bf16 v[26:29], v[46:49], v[192:195], v[26:29]
	v_mfma_f32_16x16x32_bf16 v[14:17], v[38:41], v[200:203], v[14:17]
	v_mfma_f32_16x16x32_bf16 v[10:13], v[46:49], v[200:203], v[10:13]
	s_setprio 0
	s_setprio 1
	v_mfma_f32_16x16x32_bf16 v[22:25], v[50:53], v[178:181], v[22:25]
	v_mfma_f32_16x16x32_bf16 v[18:21], v[58:61], v[178:181], v[18:21]
	v_mfma_f32_16x16x32_bf16 v[6:9], v[50:53], v[196:199], v[6:9]
	v_mfma_f32_16x16x32_bf16 v[2:5], v[58:61], v[196:199], v[2:5]
	v_mfma_f32_16x16x32_bf16 v[34:37], v[50:53], v[162:165], v[86:89]
	v_mfma_f32_16x16x32_bf16 v[38:41], v[58:61], v[162:165], v[82:85]
	v_mfma_f32_16x16x32_bf16 v[42:45], v[50:53], v[170:173], v[70:73]
	v_mfma_f32_16x16x32_bf16 v[46:49], v[58:61], v[170:173], v[66:69]
	v_mfma_f32_16x16x32_bf16 v[22:25], v[54:57], v[192:195], v[22:25]
	v_mfma_f32_16x16x32_bf16 v[18:21], v[62:65], v[192:195], v[18:21]
	v_mfma_f32_16x16x32_bf16 v[6:9], v[54:57], v[200:203], v[6:9]
	v_mfma_f32_16x16x32_bf16 v[2:5], v[62:65], v[200:203], v[2:5]
	v_mfma_f32_16x16x32_bf16 v[34:37], v[54:57], v[166:169], v[34:37]
	v_mfma_f32_16x16x32_bf16 v[38:41], v[62:65], v[166:169], v[38:41]
	v_mfma_f32_16x16x32_bf16 v[42:45], v[54:57], v[174:177], v[42:45]
	v_mfma_f32_16x16x32_bf16 v[46:49], v[62:65], v[174:177], v[46:49]
	s_setprio 0
	s_barrier
	s_add_u32 s28, s34, 0x160000
	s_addc_u32 s29, s35, 0
	s_mov_b32 m0, s48
	v_lshl_add_u64 v[210:211], s[28:29], 0, v[182:183]
	global_load_lds_dwordx4 v[210:211], off
	v_lshl_add_u64 v[210:211], s[28:29], 0, v[184:185]
	s_mov_b32 m0, s49
	s_nop 0
	global_load_lds_dwordx4 v[210:211], off
	v_add_u32_e32 v62, 0x18400, v208
	v_add_u32_e32 v66, 0x1c400, v208
	ds_read_b128 v[50:53], v62
	ds_read_b128 v[54:57], v62 offset:1024
	ds_read_b128 v[58:61], v62 offset:2048
	ds_read_b128 v[62:65], v62 offset:3072
	ds_read_b128 v[162:165], v66
	ds_read_b128 v[166:169], v66 offset:1024
	ds_read_b128 v[170:173], v66 offset:2048
	ds_read_b128 v[174:177], v66 offset:3072
	ds_read_b128 v[66:69], v207 offset:33792
	ds_read_b128 v[70:73], v207 offset:34816
	ds_read_b128 v[82:85], v207 offset:35840
	ds_read_b128 v[86:89], v207 offset:36864
	ds_read_b128 v[178:181], v207 offset:37888
	ds_read_b128 v[192:195], v207 offset:38912
	ds_read_b128 v[196:199], v207 offset:39936
	ds_read_b128 v[200:203], v207 offset:40960
	s_waitcnt vmcnt(8)
	s_waitcnt lgkmcnt(0)
	s_barrier
	s_setprio 1
	s_waitcnt lgkmcnt(0)
	v_mfma_f32_16x16x32_bf16 v[158:161], v[50:53], v[66:69], v[158:161]
	v_mfma_f32_16x16x32_bf16 v[154:157], v[58:61], v[66:69], v[154:157]
	v_mfma_f32_16x16x32_bf16 v[142:145], v[50:53], v[82:85], v[142:145]
	v_mfma_f32_16x16x32_bf16 v[138:141], v[58:61], v[82:85], v[138:141]
	v_mfma_f32_16x16x32_bf16 v[126:129], v[50:53], v[178:181], v[126:129]
	v_mfma_f32_16x16x32_bf16 v[122:125], v[58:61], v[178:181], v[122:125]
	v_mfma_f32_16x16x32_bf16 v[110:113], v[50:53], v[196:199], v[110:113]
	v_mfma_f32_16x16x32_bf16 v[106:109], v[58:61], v[196:199], v[106:109]
	v_mfma_f32_16x16x32_bf16 v[158:161], v[54:57], v[70:73], v[158:161]
	v_mfma_f32_16x16x32_bf16 v[154:157], v[62:65], v[70:73], v[154:157]
	v_mfma_f32_16x16x32_bf16 v[142:145], v[54:57], v[86:89], v[142:145]
	v_mfma_f32_16x16x32_bf16 v[138:141], v[62:65], v[86:89], v[138:141]
	v_mfma_f32_16x16x32_bf16 v[126:129], v[54:57], v[192:195], v[126:129]
	v_mfma_f32_16x16x32_bf16 v[122:125], v[62:65], v[192:195], v[122:125]
	v_mfma_f32_16x16x32_bf16 v[110:113], v[54:57], v[200:203], v[110:113]
	v_mfma_f32_16x16x32_bf16 v[106:109], v[62:65], v[200:203], v[106:109]
	s_setprio 0
	s_setprio 1
	v_mfma_f32_16x16x32_bf16 v[150:153], v[162:165], v[66:69], v[150:153]
	v_mfma_f32_16x16x32_bf16 v[66:69], v[170:173], v[66:69], v[146:149]
	v_mfma_f32_16x16x32_bf16 v[146:149], v[174:177], v[70:73], v[66:69]
	v_mfma_f32_16x16x32_bf16 v[66:69], v[162:165], v[82:85], v[134:137]
	v_mfma_f32_16x16x32_bf16 v[134:137], v[166:169], v[86:89], v[66:69]
	v_mfma_f32_16x16x32_bf16 v[66:69], v[170:173], v[82:85], v[130:133]
	v_mfma_f32_16x16x32_bf16 v[130:133], v[174:177], v[86:89], v[66:69]
	v_mfma_f32_16x16x32_bf16 v[66:69], v[162:165], v[178:181], v[118:121]
	v_mfma_f32_16x16x32_bf16 v[118:121], v[166:169], v[192:195], v[66:69]
	v_mfma_f32_16x16x32_bf16 v[66:69], v[170:173], v[178:181], v[114:117]
	v_mfma_f32_16x16x32_bf16 v[114:117], v[174:177], v[192:195], v[66:69]
	v_mfma_f32_16x16x32_bf16 v[66:69], v[162:165], v[196:199], v[102:105]
	v_mfma_f32_16x16x32_bf16 v[102:105], v[166:169], v[200:203], v[66:69]
	v_mfma_f32_16x16x32_bf16 v[66:69], v[170:173], v[196:199], v[98:101]
	v_mfma_f32_16x16x32_bf16 v[150:153], v[166:169], v[70:73], v[150:153]
	v_mfma_f32_16x16x32_bf16 v[98:101], v[174:177], v[200:203], v[66:69]
	s_setprio 0
	s_barrier
; #define PG8_STAGE(bufoff, gbase, voff) do { _Pragma("unroll") for (int _i = 0; _i < 2; ++_i) \
;         __builtin_amdgcn_global_load_lds((const GAS unsigned*)((const GAS char*)(gbase) + (voff)[_i]), (LAS unsigned*)(lds + (bufoff) + ldsw + _i * 8192), 16, 0, 0); } while (0)
; #define PG8_LDA(dst, b, h) do { _Pragma("unroll") for (int m = 0; m < 4; ++m) _Pragma("unroll") for (int k = 0; k < 2; ++k) dst[m][k] = *(const LAS bf16x8*)(lds + PG8_SA(b, h) + aoff + m * 2048 + k * 1024); } while (0)
; #define PG8_MMA(ai, bj, At, Bt) do { __builtin_amdgcn_s_setprio(1); _Pragma("unroll") for (int m = 0; m < 4; ++m) _Pragma("unroll") for (int n = 0; n < 2; ++n) _Pragma("unroll") for (int k = 0; k < 2; ++k) \
;         acc[ai][bj][m][n] = __builtin_amdgcn_mfma_f32_16x16x32_bf16(Bt[n][k], At[m][k], acc[ai][bj][m][n], 0, 0, 0); __builtin_amdgcn_s_setprio(0); } while (0)
; #define PG8_WAIT_V(n) asm volatile("s_waitcnt vmcnt(" #n ")" ::: "memory")
; #define PG8_WAIT_L(n) asm volatile("s_waitcnt lgkmcnt(" #n ")" ::: "memory")
; #define PG8_BAR __builtin_amdgcn_s_barrier()
; #define PG8_SCHED __builtin_amdgcn_sched_barrier(0)
; template <class Epi, class Sched, bool ALIGN_EPI>
; __device__ __forceinline__ void gemm_phase(LAS unsigned char* lds, const Gemm g, const Sched& S, const Epi& E, int wave_id) {
;     ...
;             PG8_LDA(At, 1, 1); PG8_STAGE(PG8_SB(1, 0), b3, voffB); PG8_STAGE(PG8_SB(1, 1), b3 + hsB, voffB); PG8_STAGE(PG8_SA(1, 0), a3, voffA);
;             PG8_WAIT_V(8); PG8_WAIT_L(0); PG8_BAR; PG8_MMA(1, 0, At, B0); PG8_MMA(1, 1, At, B1); PG8_BAR; PG8_SCHED;
;         }
	s_mov_b32 m0, s52
	v_lshl_add_u64 v[82:83], v[204:205], 0, s[92:93]
	s_add_u32 s28, s30, 0x160080
	s_nop 0
	global_load_lds_dwordx4 v[82:83], off
	v_lshl_add_u64 v[82:83], v[218:219], 0, s[92:93]
	s_mov_b32 m0, s53
	s_addc_u32 s29, s31, 0
	global_load_lds_dwordx4 v[82:83], off
	v_lshl_add_u64 v[82:83], s[28:29], 0, v[0:1]
	s_mov_b32 m0, s56
	s_nop 0
	global_load_lds_dwordx4 v[82:83], off
	v_lshl_add_u64 v[82:83], s[28:29], 0, v[186:187]
	s_mov_b32 m0, s57
	s_nop 0
	global_load_lds_dwordx4 v[82:83], off
	v_lshl_add_u64 v[82:83], v[220:221], 0, s[92:93]
	s_mov_b32 m0, s54
	s_nop 0
	global_load_lds_dwordx4 v[82:83], off
	v_lshl_add_u64 v[82:83], v[224:225], 0, s[92:93]
	s_mov_b32 m0, s55
	s_nop 0
	global_load_lds_dwordx4 v[82:83], off
	ds_read_b128 v[66:69], v207 offset:50176
	ds_read_b128 v[70:73], v207 offset:51200
	ds_read_b128 v[178:181], v207 offset:52224
	ds_read_b128 v[192:195], v207 offset:53248
	ds_read_b128 v[196:199], v207 offset:54272
	ds_read_b128 v[200:203], v207 offset:55296
	ds_read_b128 v[210:213], v207 offset:56320
	ds_read_b128 v[214:217], v207 offset:57344
	s_waitcnt vmcnt(8)
	s_waitcnt lgkmcnt(0)
	s_barrier
	s_setprio 1
	s_waitcnt lgkmcnt(0)
	v_mfma_f32_16x16x32_bf16 v[82:85], v[50:53], v[66:69], v[94:97]
	v_mfma_f32_16x16x32_bf16 v[94:97], v[54:57], v[70:73], v[82:85]
	v_mfma_f32_16x16x32_bf16 v[82:85], v[58:61], v[66:69], v[90:93]
	v_mfma_f32_16x16x32_bf16 v[78:81], v[50:53], v[178:181], v[78:81]
	v_mfma_f32_16x16x32_bf16 v[74:77], v[58:61], v[178:181], v[74:77]
	v_mfma_f32_16x16x32_bf16 v[30:33], v[50:53], v[196:199], v[30:33]
	v_mfma_f32_16x16x32_bf16 v[26:29], v[58:61], v[196:199], v[26:29]
	v_mfma_f32_16x16x32_bf16 v[14:17], v[50:53], v[210:213], v[14:17]
	v_mfma_f32_16x16x32_bf16 v[10:13], v[58:61], v[210:213], v[10:13]
	v_mfma_f32_16x16x32_bf16 v[90:93], v[62:65], v[70:73], v[82:85]
	v_mfma_f32_16x16x32_bf16 v[78:81], v[54:57], v[192:195], v[78:81]
	v_mfma_f32_16x16x32_bf16 v[74:77], v[62:65], v[192:195], v[74:77]
	v_mfma_f32_16x16x32_bf16 v[30:33], v[54:57], v[200:203], v[30:33]
	v_mfma_f32_16x16x32_bf16 v[26:29], v[62:65], v[200:203], v[26:29]
	v_mfma_f32_16x16x32_bf16 v[14:17], v[54:57], v[214:217], v[14:17]
	v_mfma_f32_16x16x32_bf16 v[10:13], v[62:65], v[214:217], v[10:13]
	s_setprio 0
	s_setprio 1
	v_mfma_f32_16x16x32_bf16 v[34:37], v[162:165], v[66:69], v[34:37]
	v_mfma_f32_16x16x32_bf16 v[86:89], v[166:169], v[70:73], v[34:37]
	v_mfma_f32_16x16x32_bf16 v[34:37], v[170:173], v[66:69], v[38:41]
	v_mfma_f32_16x16x32_bf16 v[82:85], v[174:177], v[70:73], v[34:37]
	v_mfma_f32_16x16x32_bf16 v[34:37], v[162:165], v[178:181], v[42:45]
	v_mfma_f32_16x16x32_bf16 v[70:73], v[166:169], v[192:195], v[34:37]
	v_mfma_f32_16x16x32_bf16 v[34:37], v[170:173], v[178:181], v[46:49]
	v_mfma_f32_16x16x32_bf16 v[22:25], v[162:165], v[196:199], v[22:25]
	v_mfma_f32_16x16x32_bf16 v[18:21], v[170:173], v[196:199], v[18:21]
	v_mfma_f32_16x16x32_bf16 v[6:9], v[162:165], v[210:213], v[6:9]
	v_mfma_f32_16x16x32_bf16 v[2:5], v[170:173], v[210:213], v[2:5]
	v_mfma_f32_16x16x32_bf16 v[66:69], v[174:177], v[192:195], v[34:37]
	v_mfma_f32_16x16x32_bf16 v[22:25], v[166:169], v[200:203], v[22:25]
	v_mfma_f32_16x16x32_bf16 v[18:21], v[174:177], v[200:203], v[18:21]
	v_mfma_f32_16x16x32_bf16 v[6:9], v[166:169], v[214:217], v[6:9]
	v_mfma_f32_16x16x32_bf16 v[2:5], v[174:177], v[214:217], v[2:5]
	s_setprio 0
	s_barrier
	s_add_i32 s63, s63, 2
	s_add_u32 s61, s61, 0x100
	s_addc_u32 s62, s62, 0
	s_cmpk_gt_u32 s63, 0x55
	s_mov_b64 s[28:29], s[0:1]
	s_cbranch_scc0 .LBB0_3681
	s_and_b64 vcc, exec, s[22:23]
	s_cbranch_vccz .LBB0_3684
	s_barrier
